# P0 adaLN silu staging loop unrolled: 36 loads issued up front with counted waits (was 36 exposed round trips per unit)
# speedup vs baseline: 1.0136x; 1.0051x over previous
.LBB0_34:
	s_or_saveexec_b64 s[0:1], s[52:53]
	s_mov_b64 s[52:53], 0
	s_xor_b64 exec, exec, s[0:1]
	s_cbranch_execz .LBB0_42
	v_mov_b32_e32 v2, v80
	v_mov_b32_e32 v3, v7
	v_mov_b32_e32 v4, s65
	v_mov_b32_e32 v5, s66
	ds_read_b64 v[210:211], v4
	ds_read_b64 v[212:213], v5
	v_lshlrev_b32_e32 v8, 2, v3
	s_waitcnt lgkmcnt(0)
	v_add_co_u32_e32 v210, vcc, v210, v8
	v_addc_co_u32_e32 v211, vcc, 0, v211, vcc
	v_add_co_u32_e32 v212, vcc, v212, v8
	v_addc_co_u32_e32 v213, vcc, 0, v213, vcc
	global_load_dword v150, v[210:211], off
	global_load_dword v151, v[210:211], off offset:1024
	global_load_dword v152, v[210:211], off offset:2048
	global_load_dword v153, v[210:211], off offset:3072
	v_add_co_u32_e32 v210, vcc, 0x1000, v210
	v_addc_co_u32_e32 v211, vcc, 0, v211, vcc
	global_load_dword v154, v[210:211], off
	global_load_dword v155, v[210:211], off offset:1024
	global_load_dword v156, v[210:211], off offset:2048
	global_load_dword v157, v[210:211], off offset:3072
	v_add_co_u32_e32 v210, vcc, 0x1000, v210
	v_addc_co_u32_e32 v211, vcc, 0, v211, vcc
	global_load_dword v158, v[210:211], off
	global_load_dword v159, v[210:211], off offset:1024
	global_load_dword v160, v[210:211], off offset:2048
	global_load_dword v161, v[210:211], off offset:3072
	v_add_co_u32_e32 v210, vcc, 0x1000, v210
	v_addc_co_u32_e32 v211, vcc, 0, v211, vcc
	global_load_dword v162, v[210:211], off
	global_load_dword v163, v[210:211], off offset:1024
	global_load_dword v164, v[210:211], off offset:2048
	global_load_dword v165, v[210:211], off offset:3072
	v_add_co_u32_e32 v210, vcc, 0x1000, v210
	v_addc_co_u32_e32 v211, vcc, 0, v211, vcc
	global_load_dword v166, v[210:211], off
	global_load_dword v167, v[210:211], off offset:1024
	global_load_dword v168, v[210:211], off offset:2048
	global_load_dword v169, v[210:211], off offset:3072
	v_add_co_u32_e32 v210, vcc, 0x1000, v210
	v_addc_co_u32_e32 v211, vcc, 0, v211, vcc
	global_load_dword v170, v[210:211], off
	global_load_dword v171, v[210:211], off offset:1024
	global_load_dword v172, v[210:211], off offset:2048
	global_load_dword v173, v[210:211], off offset:3072
	v_add_co_u32_e32 v210, vcc, 0x1000, v210
	v_addc_co_u32_e32 v211, vcc, 0, v211, vcc
	global_load_dword v174, v[210:211], off
	global_load_dword v175, v[210:211], off offset:1024
	global_load_dword v176, v[210:211], off offset:2048
	global_load_dword v177, v[210:211], off offset:3072
	v_add_co_u32_e32 v210, vcc, 0x1000, v210
	v_addc_co_u32_e32 v211, vcc, 0, v211, vcc
	global_load_dword v178, v[210:211], off
	global_load_dword v179, v[210:211], off offset:1024
	global_load_dword v180, v[210:211], off offset:2048
	global_load_dword v181, v[210:211], off offset:3072
	global_load_dword v182, v[212:213], off
	global_load_dword v183, v[212:213], off offset:1024
	global_load_dword v184, v[212:213], off offset:2048
	global_load_dword v185, v[212:213], off offset:3072
	s_waitcnt vmcnt(35)
	v_mov_b32_e32 v4, v150
	v_mul_f32_e32 v5, 0xbfb8aa3b, v4
	v_fma_f32 v8, v4, s67, -v5
	v_rndne_f32_e32 v23, v5
	v_fmac_f32_e32 v8, 0xb2a5705f, v4
	v_sub_f32_e32 v5, v5, v23
	v_add_f32_e32 v5, v5, v8
	v_cvt_i32_f32_e32 v23, v23
	v_exp_f32_e32 v5, v5
	v_cmp_nlt_f32_e32 vcc, s68, v4
	v_ldexp_f32 v5, v5, v23
	s_nop 0
	v_cndmask_b32_e32 v5, 0, v5, vcc
	v_cmp_ngt_f32_e32 vcc, s69, v4
	s_nop 1
	v_cndmask_b32_e32 v5, v95, v5, vcc
	v_add_f32_e32 v5, 1.0, v5
	v_div_scale_f32 v8, s[54:55], v5, v5, v4
	v_rcp_f32_e32 v23, v8
	v_div_scale_f32 v61, vcc, v4, v5, v4
	v_fma_f32 v65, -v8, v23, 1.0
	v_fmac_f32_e32 v23, v65, v23
	v_mul_f32_e32 v65, v61, v23
	v_fma_f32 v66, -v8, v65, v61
	v_fmac_f32_e32 v65, v66, v23
	v_fma_f32 v8, -v8, v65, v61
	v_div_fmas_f32 v8, v8, v23, v65
	v_div_fixup_f32 v4, v8, v5, v4
	ds_write_b32 v2, v4
	s_waitcnt vmcnt(34)
	v_mov_b32_e32 v4, v151
	v_mul_f32_e32 v5, 0xbfb8aa3b, v4
	v_fma_f32 v8, v4, s67, -v5
	v_rndne_f32_e32 v23, v5
	v_fmac_f32_e32 v8, 0xb2a5705f, v4
	v_sub_f32_e32 v5, v5, v23
	v_add_f32_e32 v5, v5, v8
	v_cvt_i32_f32_e32 v23, v23
	v_exp_f32_e32 v5, v5
	v_cmp_nlt_f32_e32 vcc, s68, v4
	v_ldexp_f32 v5, v5, v23
	s_nop 0
	v_cndmask_b32_e32 v5, 0, v5, vcc
	v_cmp_ngt_f32_e32 vcc, s69, v4
	s_nop 1
	v_cndmask_b32_e32 v5, v95, v5, vcc
	v_add_f32_e32 v5, 1.0, v5
	v_div_scale_f32 v8, s[54:55], v5, v5, v4
	v_rcp_f32_e32 v23, v8
	v_div_scale_f32 v61, vcc, v4, v5, v4
	v_fma_f32 v65, -v8, v23, 1.0
	v_fmac_f32_e32 v23, v65, v23
	v_mul_f32_e32 v65, v61, v23
	v_fma_f32 v66, -v8, v65, v61
	v_fmac_f32_e32 v65, v66, v23
	v_fma_f32 v8, -v8, v65, v61
	v_div_fmas_f32 v8, v8, v23, v65
	v_div_fixup_f32 v4, v8, v5, v4
	ds_write_b32 v2, v4 offset:1024
	s_waitcnt vmcnt(33)
	v_mov_b32_e32 v4, v152
	v_mul_f32_e32 v5, 0xbfb8aa3b, v4
	v_fma_f32 v8, v4, s67, -v5
	v_rndne_f32_e32 v23, v5
	v_fmac_f32_e32 v8, 0xb2a5705f, v4
	v_sub_f32_e32 v5, v5, v23
	v_add_f32_e32 v5, v5, v8
	v_cvt_i32_f32_e32 v23, v23
	v_exp_f32_e32 v5, v5
	v_cmp_nlt_f32_e32 vcc, s68, v4
	v_ldexp_f32 v5, v5, v23
	s_nop 0
	v_cndmask_b32_e32 v5, 0, v5, vcc
	v_cmp_ngt_f32_e32 vcc, s69, v4
	s_nop 1
	v_cndmask_b32_e32 v5, v95, v5, vcc
	v_add_f32_e32 v5, 1.0, v5
	v_div_scale_f32 v8, s[54:55], v5, v5, v4
	v_rcp_f32_e32 v23, v8
	v_div_scale_f32 v61, vcc, v4, v5, v4
	v_fma_f32 v65, -v8, v23, 1.0
	v_fmac_f32_e32 v23, v65, v23
	v_mul_f32_e32 v65, v61, v23
	v_fma_f32 v66, -v8, v65, v61
	v_fmac_f32_e32 v65, v66, v23
	v_fma_f32 v8, -v8, v65, v61
	v_div_fmas_f32 v8, v8, v23, v65
	v_div_fixup_f32 v4, v8, v5, v4
	ds_write_b32 v2, v4 offset:2048
	s_waitcnt vmcnt(32)
	v_mov_b32_e32 v4, v153
	v_mul_f32_e32 v5, 0xbfb8aa3b, v4
	v_fma_f32 v8, v4, s67, -v5
	v_rndne_f32_e32 v23, v5
	v_fmac_f32_e32 v8, 0xb2a5705f, v4
	v_sub_f32_e32 v5, v5, v23
	v_add_f32_e32 v5, v5, v8
	v_cvt_i32_f32_e32 v23, v23
	v_exp_f32_e32 v5, v5
	v_cmp_nlt_f32_e32 vcc, s68, v4
	v_ldexp_f32 v5, v5, v23
	s_nop 0
	v_cndmask_b32_e32 v5, 0, v5, vcc
	v_cmp_ngt_f32_e32 vcc, s69, v4
	s_nop 1
	v_cndmask_b32_e32 v5, v95, v5, vcc
	v_add_f32_e32 v5, 1.0, v5
	v_div_scale_f32 v8, s[54:55], v5, v5, v4
	v_rcp_f32_e32 v23, v8
	v_div_scale_f32 v61, vcc, v4, v5, v4
	v_fma_f32 v65, -v8, v23, 1.0
	v_fmac_f32_e32 v23, v65, v23
	v_mul_f32_e32 v65, v61, v23
	v_fma_f32 v66, -v8, v65, v61
	v_fmac_f32_e32 v65, v66, v23
	v_fma_f32 v8, -v8, v65, v61
	v_div_fmas_f32 v8, v8, v23, v65
	v_div_fixup_f32 v4, v8, v5, v4
	ds_write_b32 v2, v4 offset:3072
	s_waitcnt vmcnt(31)
	v_mov_b32_e32 v4, v154
	v_mul_f32_e32 v5, 0xbfb8aa3b, v4
	v_fma_f32 v8, v4, s67, -v5
	v_rndne_f32_e32 v23, v5
	v_fmac_f32_e32 v8, 0xb2a5705f, v4
	v_sub_f32_e32 v5, v5, v23
	v_add_f32_e32 v5, v5, v8
	v_cvt_i32_f32_e32 v23, v23
	v_exp_f32_e32 v5, v5
	v_cmp_nlt_f32_e32 vcc, s68, v4
	v_ldexp_f32 v5, v5, v23
	s_nop 0
	v_cndmask_b32_e32 v5, 0, v5, vcc
	v_cmp_ngt_f32_e32 vcc, s69, v4
	s_nop 1
	v_cndmask_b32_e32 v5, v95, v5, vcc
	v_add_f32_e32 v5, 1.0, v5
	v_div_scale_f32 v8, s[54:55], v5, v5, v4
	v_rcp_f32_e32 v23, v8
	v_div_scale_f32 v61, vcc, v4, v5, v4
	v_fma_f32 v65, -v8, v23, 1.0
	v_fmac_f32_e32 v23, v65, v23
	v_mul_f32_e32 v65, v61, v23
	v_fma_f32 v66, -v8, v65, v61
	v_fmac_f32_e32 v65, v66, v23
	v_fma_f32 v8, -v8, v65, v61
	v_div_fmas_f32 v8, v8, v23, v65
	v_div_fixup_f32 v4, v8, v5, v4
	ds_write_b32 v2, v4 offset:4096
	s_waitcnt vmcnt(30)
	v_mov_b32_e32 v4, v155
	v_mul_f32_e32 v5, 0xbfb8aa3b, v4
	v_fma_f32 v8, v4, s67, -v5
	v_rndne_f32_e32 v23, v5
	v_fmac_f32_e32 v8, 0xb2a5705f, v4
	v_sub_f32_e32 v5, v5, v23
	v_add_f32_e32 v5, v5, v8
	v_cvt_i32_f32_e32 v23, v23
	v_exp_f32_e32 v5, v5
	v_cmp_nlt_f32_e32 vcc, s68, v4
	v_ldexp_f32 v5, v5, v23
	s_nop 0
	v_cndmask_b32_e32 v5, 0, v5, vcc
	v_cmp_ngt_f32_e32 vcc, s69, v4
	s_nop 1
	v_cndmask_b32_e32 v5, v95, v5, vcc
	v_add_f32_e32 v5, 1.0, v5
	v_div_scale_f32 v8, s[54:55], v5, v5, v4
	v_rcp_f32_e32 v23, v8
	v_div_scale_f32 v61, vcc, v4, v5, v4
	v_fma_f32 v65, -v8, v23, 1.0
	v_fmac_f32_e32 v23, v65, v23
	v_mul_f32_e32 v65, v61, v23
	v_fma_f32 v66, -v8, v65, v61
	v_fmac_f32_e32 v65, v66, v23
	v_fma_f32 v8, -v8, v65, v61
	v_div_fmas_f32 v8, v8, v23, v65
	v_div_fixup_f32 v4, v8, v5, v4
	ds_write_b32 v2, v4 offset:5120
	s_waitcnt vmcnt(29)
	v_mov_b32_e32 v4, v156
	v_mul_f32_e32 v5, 0xbfb8aa3b, v4
	v_fma_f32 v8, v4, s67, -v5
	v_rndne_f32_e32 v23, v5
	v_fmac_f32_e32 v8, 0xb2a5705f, v4
	v_sub_f32_e32 v5, v5, v23
	v_add_f32_e32 v5, v5, v8
	v_cvt_i32_f32_e32 v23, v23
	v_exp_f32_e32 v5, v5
	v_cmp_nlt_f32_e32 vcc, s68, v4
	v_ldexp_f32 v5, v5, v23
	s_nop 0
	v_cndmask_b32_e32 v5, 0, v5, vcc
	v_cmp_ngt_f32_e32 vcc, s69, v4
	s_nop 1
	v_cndmask_b32_e32 v5, v95, v5, vcc
	v_add_f32_e32 v5, 1.0, v5
	v_div_scale_f32 v8, s[54:55], v5, v5, v4
	v_rcp_f32_e32 v23, v8
	v_div_scale_f32 v61, vcc, v4, v5, v4
	v_fma_f32 v65, -v8, v23, 1.0
	v_fmac_f32_e32 v23, v65, v23
	v_mul_f32_e32 v65, v61, v23
	v_fma_f32 v66, -v8, v65, v61
	v_fmac_f32_e32 v65, v66, v23
	v_fma_f32 v8, -v8, v65, v61
	v_div_fmas_f32 v8, v8, v23, v65
	v_div_fixup_f32 v4, v8, v5, v4
	ds_write_b32 v2, v4 offset:6144
	s_waitcnt vmcnt(28)
	v_mov_b32_e32 v4, v157
	v_mul_f32_e32 v5, 0xbfb8aa3b, v4
	v_fma_f32 v8, v4, s67, -v5
	v_rndne_f32_e32 v23, v5
	v_fmac_f32_e32 v8, 0xb2a5705f, v4
	v_sub_f32_e32 v5, v5, v23
	v_add_f32_e32 v5, v5, v8
	v_cvt_i32_f32_e32 v23, v23
	v_exp_f32_e32 v5, v5
	v_cmp_nlt_f32_e32 vcc, s68, v4
	v_ldexp_f32 v5, v5, v23
	s_nop 0
	v_cndmask_b32_e32 v5, 0, v5, vcc
	v_cmp_ngt_f32_e32 vcc, s69, v4
	s_nop 1
	v_cndmask_b32_e32 v5, v95, v5, vcc
	v_add_f32_e32 v5, 1.0, v5
	v_div_scale_f32 v8, s[54:55], v5, v5, v4
	v_rcp_f32_e32 v23, v8
	v_div_scale_f32 v61, vcc, v4, v5, v4
	v_fma_f32 v65, -v8, v23, 1.0
	v_fmac_f32_e32 v23, v65, v23
	v_mul_f32_e32 v65, v61, v23
	v_fma_f32 v66, -v8, v65, v61
	v_fmac_f32_e32 v65, v66, v23
	v_fma_f32 v8, -v8, v65, v61
	v_div_fmas_f32 v8, v8, v23, v65
	v_div_fixup_f32 v4, v8, v5, v4
	ds_write_b32 v2, v4 offset:7168
	s_waitcnt vmcnt(27)
	v_mov_b32_e32 v4, v158
	v_mul_f32_e32 v5, 0xbfb8aa3b, v4
	v_fma_f32 v8, v4, s67, -v5
	v_rndne_f32_e32 v23, v5
	v_fmac_f32_e32 v8, 0xb2a5705f, v4
	v_sub_f32_e32 v5, v5, v23
	v_add_f32_e32 v5, v5, v8
	v_cvt_i32_f32_e32 v23, v23
	v_exp_f32_e32 v5, v5
	v_cmp_nlt_f32_e32 vcc, s68, v4
	v_ldexp_f32 v5, v5, v23
	s_nop 0
	v_cndmask_b32_e32 v5, 0, v5, vcc
	v_cmp_ngt_f32_e32 vcc, s69, v4
	s_nop 1
	v_cndmask_b32_e32 v5, v95, v5, vcc
	v_add_f32_e32 v5, 1.0, v5
	v_div_scale_f32 v8, s[54:55], v5, v5, v4
	v_rcp_f32_e32 v23, v8
	v_div_scale_f32 v61, vcc, v4, v5, v4
	v_fma_f32 v65, -v8, v23, 1.0
	v_fmac_f32_e32 v23, v65, v23
	v_mul_f32_e32 v65, v61, v23
	v_fma_f32 v66, -v8, v65, v61
	v_fmac_f32_e32 v65, v66, v23
	v_fma_f32 v8, -v8, v65, v61
	v_div_fmas_f32 v8, v8, v23, v65
	v_div_fixup_f32 v4, v8, v5, v4
	ds_write_b32 v2, v4 offset:8192
	s_waitcnt vmcnt(26)
	v_mov_b32_e32 v4, v159
	v_mul_f32_e32 v5, 0xbfb8aa3b, v4
	v_fma_f32 v8, v4, s67, -v5
	v_rndne_f32_e32 v23, v5
	v_fmac_f32_e32 v8, 0xb2a5705f, v4
	v_sub_f32_e32 v5, v5, v23
	v_add_f32_e32 v5, v5, v8
	v_cvt_i32_f32_e32 v23, v23
	v_exp_f32_e32 v5, v5
	v_cmp_nlt_f32_e32 vcc, s68, v4
	v_ldexp_f32 v5, v5, v23
	s_nop 0
	v_cndmask_b32_e32 v5, 0, v5, vcc
	v_cmp_ngt_f32_e32 vcc, s69, v4
	s_nop 1
	v_cndmask_b32_e32 v5, v95, v5, vcc
	v_add_f32_e32 v5, 1.0, v5
	v_div_scale_f32 v8, s[54:55], v5, v5, v4
	v_rcp_f32_e32 v23, v8
	v_div_scale_f32 v61, vcc, v4, v5, v4
	v_fma_f32 v65, -v8, v23, 1.0
	v_fmac_f32_e32 v23, v65, v23
	v_mul_f32_e32 v65, v61, v23
	v_fma_f32 v66, -v8, v65, v61
	v_fmac_f32_e32 v65, v66, v23
	v_fma_f32 v8, -v8, v65, v61
	v_div_fmas_f32 v8, v8, v23, v65
	v_div_fixup_f32 v4, v8, v5, v4
	ds_write_b32 v2, v4 offset:9216
	s_waitcnt vmcnt(25)
	v_mov_b32_e32 v4, v160
	v_mul_f32_e32 v5, 0xbfb8aa3b, v4
	v_fma_f32 v8, v4, s67, -v5
	v_rndne_f32_e32 v23, v5
	v_fmac_f32_e32 v8, 0xb2a5705f, v4
	v_sub_f32_e32 v5, v5, v23
	v_add_f32_e32 v5, v5, v8
	v_cvt_i32_f32_e32 v23, v23
	v_exp_f32_e32 v5, v5
	v_cmp_nlt_f32_e32 vcc, s68, v4
	v_ldexp_f32 v5, v5, v23
	s_nop 0
	v_cndmask_b32_e32 v5, 0, v5, vcc
	v_cmp_ngt_f32_e32 vcc, s69, v4
	s_nop 1
	v_cndmask_b32_e32 v5, v95, v5, vcc
	v_add_f32_e32 v5, 1.0, v5
	v_div_scale_f32 v8, s[54:55], v5, v5, v4
	v_rcp_f32_e32 v23, v8
	v_div_scale_f32 v61, vcc, v4, v5, v4
	v_fma_f32 v65, -v8, v23, 1.0
	v_fmac_f32_e32 v23, v65, v23
	v_mul_f32_e32 v65, v61, v23
	v_fma_f32 v66, -v8, v65, v61
	v_fmac_f32_e32 v65, v66, v23
	v_fma_f32 v8, -v8, v65, v61
	v_div_fmas_f32 v8, v8, v23, v65
	v_div_fixup_f32 v4, v8, v5, v4
	ds_write_b32 v2, v4 offset:10240
	s_waitcnt vmcnt(24)
	v_mov_b32_e32 v4, v161
	v_mul_f32_e32 v5, 0xbfb8aa3b, v4
	v_fma_f32 v8, v4, s67, -v5
	v_rndne_f32_e32 v23, v5
	v_fmac_f32_e32 v8, 0xb2a5705f, v4
	v_sub_f32_e32 v5, v5, v23
	v_add_f32_e32 v5, v5, v8
	v_cvt_i32_f32_e32 v23, v23
	v_exp_f32_e32 v5, v5
	v_cmp_nlt_f32_e32 vcc, s68, v4
	v_ldexp_f32 v5, v5, v23
	s_nop 0
	v_cndmask_b32_e32 v5, 0, v5, vcc
	v_cmp_ngt_f32_e32 vcc, s69, v4
	s_nop 1
	v_cndmask_b32_e32 v5, v95, v5, vcc
	v_add_f32_e32 v5, 1.0, v5
	v_div_scale_f32 v8, s[54:55], v5, v5, v4
	v_rcp_f32_e32 v23, v8
	v_div_scale_f32 v61, vcc, v4, v5, v4
	v_fma_f32 v65, -v8, v23, 1.0
	v_fmac_f32_e32 v23, v65, v23
	v_mul_f32_e32 v65, v61, v23
	v_fma_f32 v66, -v8, v65, v61
	v_fmac_f32_e32 v65, v66, v23
	v_fma_f32 v8, -v8, v65, v61
	v_div_fmas_f32 v8, v8, v23, v65
	v_div_fixup_f32 v4, v8, v5, v4
	ds_write_b32 v2, v4 offset:11264
	s_waitcnt vmcnt(23)
	v_mov_b32_e32 v4, v162
	v_mul_f32_e32 v5, 0xbfb8aa3b, v4
	v_fma_f32 v8, v4, s67, -v5
	v_rndne_f32_e32 v23, v5
	v_fmac_f32_e32 v8, 0xb2a5705f, v4
	v_sub_f32_e32 v5, v5, v23
	v_add_f32_e32 v5, v5, v8
	v_cvt_i32_f32_e32 v23, v23
	v_exp_f32_e32 v5, v5
	v_cmp_nlt_f32_e32 vcc, s68, v4
	v_ldexp_f32 v5, v5, v23
	s_nop 0
	v_cndmask_b32_e32 v5, 0, v5, vcc
	v_cmp_ngt_f32_e32 vcc, s69, v4
	s_nop 1
	v_cndmask_b32_e32 v5, v95, v5, vcc
	v_add_f32_e32 v5, 1.0, v5
	v_div_scale_f32 v8, s[54:55], v5, v5, v4
	v_rcp_f32_e32 v23, v8
	v_div_scale_f32 v61, vcc, v4, v5, v4
	v_fma_f32 v65, -v8, v23, 1.0
	v_fmac_f32_e32 v23, v65, v23
	v_mul_f32_e32 v65, v61, v23
	v_fma_f32 v66, -v8, v65, v61
	v_fmac_f32_e32 v65, v66, v23
	v_fma_f32 v8, -v8, v65, v61
	v_div_fmas_f32 v8, v8, v23, v65
	v_div_fixup_f32 v4, v8, v5, v4
	ds_write_b32 v2, v4 offset:12288
	s_waitcnt vmcnt(22)
	v_mov_b32_e32 v4, v163
	v_mul_f32_e32 v5, 0xbfb8aa3b, v4
	v_fma_f32 v8, v4, s67, -v5
	v_rndne_f32_e32 v23, v5
	v_fmac_f32_e32 v8, 0xb2a5705f, v4
	v_sub_f32_e32 v5, v5, v23
	v_add_f32_e32 v5, v5, v8
	v_cvt_i32_f32_e32 v23, v23
	v_exp_f32_e32 v5, v5
	v_cmp_nlt_f32_e32 vcc, s68, v4
	v_ldexp_f32 v5, v5, v23
	s_nop 0
	v_cndmask_b32_e32 v5, 0, v5, vcc
	v_cmp_ngt_f32_e32 vcc, s69, v4
	s_nop 1
	v_cndmask_b32_e32 v5, v95, v5, vcc
	v_add_f32_e32 v5, 1.0, v5
	v_div_scale_f32 v8, s[54:55], v5, v5, v4
	v_rcp_f32_e32 v23, v8
	v_div_scale_f32 v61, vcc, v4, v5, v4
	v_fma_f32 v65, -v8, v23, 1.0
	v_fmac_f32_e32 v23, v65, v23
	v_mul_f32_e32 v65, v61, v23
	v_fma_f32 v66, -v8, v65, v61
	v_fmac_f32_e32 v65, v66, v23
	v_fma_f32 v8, -v8, v65, v61
	v_div_fmas_f32 v8, v8, v23, v65
	v_div_fixup_f32 v4, v8, v5, v4
	ds_write_b32 v2, v4 offset:13312
	s_waitcnt vmcnt(21)
	v_mov_b32_e32 v4, v164
	v_mul_f32_e32 v5, 0xbfb8aa3b, v4
	v_fma_f32 v8, v4, s67, -v5
	v_rndne_f32_e32 v23, v5
	v_fmac_f32_e32 v8, 0xb2a5705f, v4
	v_sub_f32_e32 v5, v5, v23
	v_add_f32_e32 v5, v5, v8
	v_cvt_i32_f32_e32 v23, v23
	v_exp_f32_e32 v5, v5
	v_cmp_nlt_f32_e32 vcc, s68, v4
	v_ldexp_f32 v5, v5, v23
	s_nop 0
	v_cndmask_b32_e32 v5, 0, v5, vcc
	v_cmp_ngt_f32_e32 vcc, s69, v4
	s_nop 1
	v_cndmask_b32_e32 v5, v95, v5, vcc
	v_add_f32_e32 v5, 1.0, v5
	v_div_scale_f32 v8, s[54:55], v5, v5, v4
	v_rcp_f32_e32 v23, v8
	v_div_scale_f32 v61, vcc, v4, v5, v4
	v_fma_f32 v65, -v8, v23, 1.0
	v_fmac_f32_e32 v23, v65, v23
	v_mul_f32_e32 v65, v61, v23
	v_fma_f32 v66, -v8, v65, v61
	v_fmac_f32_e32 v65, v66, v23
	v_fma_f32 v8, -v8, v65, v61
	v_div_fmas_f32 v8, v8, v23, v65
	v_div_fixup_f32 v4, v8, v5, v4
	ds_write_b32 v2, v4 offset:14336
	s_waitcnt vmcnt(20)
	v_mov_b32_e32 v4, v165
	v_mul_f32_e32 v5, 0xbfb8aa3b, v4
	v_fma_f32 v8, v4, s67, -v5
	v_rndne_f32_e32 v23, v5
	v_fmac_f32_e32 v8, 0xb2a5705f, v4
	v_sub_f32_e32 v5, v5, v23
	v_add_f32_e32 v5, v5, v8
	v_cvt_i32_f32_e32 v23, v23
	v_exp_f32_e32 v5, v5
	v_cmp_nlt_f32_e32 vcc, s68, v4
	v_ldexp_f32 v5, v5, v23
	s_nop 0
	v_cndmask_b32_e32 v5, 0, v5, vcc
	v_cmp_ngt_f32_e32 vcc, s69, v4
	s_nop 1
	v_cndmask_b32_e32 v5, v95, v5, vcc
	v_add_f32_e32 v5, 1.0, v5
	v_div_scale_f32 v8, s[54:55], v5, v5, v4
	v_rcp_f32_e32 v23, v8
	v_div_scale_f32 v61, vcc, v4, v5, v4
	v_fma_f32 v65, -v8, v23, 1.0
	v_fmac_f32_e32 v23, v65, v23
	v_mul_f32_e32 v65, v61, v23
	v_fma_f32 v66, -v8, v65, v61
	v_fmac_f32_e32 v65, v66, v23
	v_fma_f32 v8, -v8, v65, v61
	v_div_fmas_f32 v8, v8, v23, v65
	v_div_fixup_f32 v4, v8, v5, v4
	ds_write_b32 v2, v4 offset:15360
	s_waitcnt vmcnt(19)
	v_mov_b32_e32 v4, v166
	v_mul_f32_e32 v5, 0xbfb8aa3b, v4
	v_fma_f32 v8, v4, s67, -v5
	v_rndne_f32_e32 v23, v5
	v_fmac_f32_e32 v8, 0xb2a5705f, v4
	v_sub_f32_e32 v5, v5, v23
	v_add_f32_e32 v5, v5, v8
	v_cvt_i32_f32_e32 v23, v23
	v_exp_f32_e32 v5, v5
	v_cmp_nlt_f32_e32 vcc, s68, v4
	v_ldexp_f32 v5, v5, v23
	s_nop 0
	v_cndmask_b32_e32 v5, 0, v5, vcc
	v_cmp_ngt_f32_e32 vcc, s69, v4
	s_nop 1
	v_cndmask_b32_e32 v5, v95, v5, vcc
	v_add_f32_e32 v5, 1.0, v5
	v_div_scale_f32 v8, s[54:55], v5, v5, v4
	v_rcp_f32_e32 v23, v8
	v_div_scale_f32 v61, vcc, v4, v5, v4
	v_fma_f32 v65, -v8, v23, 1.0
	v_fmac_f32_e32 v23, v65, v23
	v_mul_f32_e32 v65, v61, v23
	v_fma_f32 v66, -v8, v65, v61
	v_fmac_f32_e32 v65, v66, v23
	v_fma_f32 v8, -v8, v65, v61
	v_div_fmas_f32 v8, v8, v23, v65
	v_div_fixup_f32 v4, v8, v5, v4
	ds_write_b32 v2, v4 offset:16384
	s_waitcnt vmcnt(18)
	v_mov_b32_e32 v4, v167
	v_mul_f32_e32 v5, 0xbfb8aa3b, v4
	v_fma_f32 v8, v4, s67, -v5
	v_rndne_f32_e32 v23, v5
	v_fmac_f32_e32 v8, 0xb2a5705f, v4
	v_sub_f32_e32 v5, v5, v23
	v_add_f32_e32 v5, v5, v8
	v_cvt_i32_f32_e32 v23, v23
	v_exp_f32_e32 v5, v5
	v_cmp_nlt_f32_e32 vcc, s68, v4
	v_ldexp_f32 v5, v5, v23
	s_nop 0
	v_cndmask_b32_e32 v5, 0, v5, vcc
	v_cmp_ngt_f32_e32 vcc, s69, v4
	s_nop 1
	v_cndmask_b32_e32 v5, v95, v5, vcc
	v_add_f32_e32 v5, 1.0, v5
	v_div_scale_f32 v8, s[54:55], v5, v5, v4
	v_rcp_f32_e32 v23, v8
	v_div_scale_f32 v61, vcc, v4, v5, v4
	v_fma_f32 v65, -v8, v23, 1.0
	v_fmac_f32_e32 v23, v65, v23
	v_mul_f32_e32 v65, v61, v23
	v_fma_f32 v66, -v8, v65, v61
	v_fmac_f32_e32 v65, v66, v23
	v_fma_f32 v8, -v8, v65, v61
	v_div_fmas_f32 v8, v8, v23, v65
	v_div_fixup_f32 v4, v8, v5, v4
	ds_write_b32 v2, v4 offset:17408
	s_waitcnt vmcnt(17)
	v_mov_b32_e32 v4, v168
	v_mul_f32_e32 v5, 0xbfb8aa3b, v4
	v_fma_f32 v8, v4, s67, -v5
	v_rndne_f32_e32 v23, v5
	v_fmac_f32_e32 v8, 0xb2a5705f, v4
	v_sub_f32_e32 v5, v5, v23
	v_add_f32_e32 v5, v5, v8
	v_cvt_i32_f32_e32 v23, v23
	v_exp_f32_e32 v5, v5
	v_cmp_nlt_f32_e32 vcc, s68, v4
	v_ldexp_f32 v5, v5, v23
	s_nop 0
	v_cndmask_b32_e32 v5, 0, v5, vcc
	v_cmp_ngt_f32_e32 vcc, s69, v4
	s_nop 1
	v_cndmask_b32_e32 v5, v95, v5, vcc
	v_add_f32_e32 v5, 1.0, v5
	v_div_scale_f32 v8, s[54:55], v5, v5, v4
	v_rcp_f32_e32 v23, v8
	v_div_scale_f32 v61, vcc, v4, v5, v4
	v_fma_f32 v65, -v8, v23, 1.0
	v_fmac_f32_e32 v23, v65, v23
	v_mul_f32_e32 v65, v61, v23
	v_fma_f32 v66, -v8, v65, v61
	v_fmac_f32_e32 v65, v66, v23
	v_fma_f32 v8, -v8, v65, v61
	v_div_fmas_f32 v8, v8, v23, v65
	v_div_fixup_f32 v4, v8, v5, v4
	ds_write_b32 v2, v4 offset:18432
	s_waitcnt vmcnt(16)
	v_mov_b32_e32 v4, v169
	v_mul_f32_e32 v5, 0xbfb8aa3b, v4
	v_fma_f32 v8, v4, s67, -v5
	v_rndne_f32_e32 v23, v5
	v_fmac_f32_e32 v8, 0xb2a5705f, v4
	v_sub_f32_e32 v5, v5, v23
	v_add_f32_e32 v5, v5, v8
	v_cvt_i32_f32_e32 v23, v23
	v_exp_f32_e32 v5, v5
	v_cmp_nlt_f32_e32 vcc, s68, v4
	v_ldexp_f32 v5, v5, v23
	s_nop 0
	v_cndmask_b32_e32 v5, 0, v5, vcc
	v_cmp_ngt_f32_e32 vcc, s69, v4
	s_nop 1
	v_cndmask_b32_e32 v5, v95, v5, vcc
	v_add_f32_e32 v5, 1.0, v5
	v_div_scale_f32 v8, s[54:55], v5, v5, v4
	v_rcp_f32_e32 v23, v8
	v_div_scale_f32 v61, vcc, v4, v5, v4
	v_fma_f32 v65, -v8, v23, 1.0
	v_fmac_f32_e32 v23, v65, v23
	v_mul_f32_e32 v65, v61, v23
	v_fma_f32 v66, -v8, v65, v61
	v_fmac_f32_e32 v65, v66, v23
	v_fma_f32 v8, -v8, v65, v61
	v_div_fmas_f32 v8, v8, v23, v65
	v_div_fixup_f32 v4, v8, v5, v4
	ds_write_b32 v2, v4 offset:19456
	s_waitcnt vmcnt(15)
	v_mov_b32_e32 v4, v170
	v_mul_f32_e32 v5, 0xbfb8aa3b, v4
	v_fma_f32 v8, v4, s67, -v5
	v_rndne_f32_e32 v23, v5
	v_fmac_f32_e32 v8, 0xb2a5705f, v4
	v_sub_f32_e32 v5, v5, v23
	v_add_f32_e32 v5, v5, v8
	v_cvt_i32_f32_e32 v23, v23
	v_exp_f32_e32 v5, v5
	v_cmp_nlt_f32_e32 vcc, s68, v4
	v_ldexp_f32 v5, v5, v23
	s_nop 0
	v_cndmask_b32_e32 v5, 0, v5, vcc
	v_cmp_ngt_f32_e32 vcc, s69, v4
	s_nop 1
	v_cndmask_b32_e32 v5, v95, v5, vcc
	v_add_f32_e32 v5, 1.0, v5
	v_div_scale_f32 v8, s[54:55], v5, v5, v4
	v_rcp_f32_e32 v23, v8
	v_div_scale_f32 v61, vcc, v4, v5, v4
	v_fma_f32 v65, -v8, v23, 1.0
	v_fmac_f32_e32 v23, v65, v23
	v_mul_f32_e32 v65, v61, v23
	v_fma_f32 v66, -v8, v65, v61
	v_fmac_f32_e32 v65, v66, v23
	v_fma_f32 v8, -v8, v65, v61
	v_div_fmas_f32 v8, v8, v23, v65
	v_div_fixup_f32 v4, v8, v5, v4
	ds_write_b32 v2, v4 offset:20480
	s_waitcnt vmcnt(14)
	v_mov_b32_e32 v4, v171
	v_mul_f32_e32 v5, 0xbfb8aa3b, v4
	v_fma_f32 v8, v4, s67, -v5
	v_rndne_f32_e32 v23, v5
	v_fmac_f32_e32 v8, 0xb2a5705f, v4
	v_sub_f32_e32 v5, v5, v23
	v_add_f32_e32 v5, v5, v8
	v_cvt_i32_f32_e32 v23, v23
	v_exp_f32_e32 v5, v5
	v_cmp_nlt_f32_e32 vcc, s68, v4
	v_ldexp_f32 v5, v5, v23
	s_nop 0
	v_cndmask_b32_e32 v5, 0, v5, vcc
	v_cmp_ngt_f32_e32 vcc, s69, v4
	s_nop 1
	v_cndmask_b32_e32 v5, v95, v5, vcc
	v_add_f32_e32 v5, 1.0, v5
	v_div_scale_f32 v8, s[54:55], v5, v5, v4
	v_rcp_f32_e32 v23, v8
	v_div_scale_f32 v61, vcc, v4, v5, v4
	v_fma_f32 v65, -v8, v23, 1.0
	v_fmac_f32_e32 v23, v65, v23
	v_mul_f32_e32 v65, v61, v23
	v_fma_f32 v66, -v8, v65, v61
	v_fmac_f32_e32 v65, v66, v23
	v_fma_f32 v8, -v8, v65, v61
	v_div_fmas_f32 v8, v8, v23, v65
	v_div_fixup_f32 v4, v8, v5, v4
	ds_write_b32 v2, v4 offset:21504
	s_waitcnt vmcnt(13)
	v_mov_b32_e32 v4, v172
	v_mul_f32_e32 v5, 0xbfb8aa3b, v4
	v_fma_f32 v8, v4, s67, -v5
	v_rndne_f32_e32 v23, v5
	v_fmac_f32_e32 v8, 0xb2a5705f, v4
	v_sub_f32_e32 v5, v5, v23
	v_add_f32_e32 v5, v5, v8
	v_cvt_i32_f32_e32 v23, v23
	v_exp_f32_e32 v5, v5
	v_cmp_nlt_f32_e32 vcc, s68, v4
	v_ldexp_f32 v5, v5, v23
	s_nop 0
	v_cndmask_b32_e32 v5, 0, v5, vcc
	v_cmp_ngt_f32_e32 vcc, s69, v4
	s_nop 1
	v_cndmask_b32_e32 v5, v95, v5, vcc
	v_add_f32_e32 v5, 1.0, v5
	v_div_scale_f32 v8, s[54:55], v5, v5, v4
	v_rcp_f32_e32 v23, v8
	v_div_scale_f32 v61, vcc, v4, v5, v4
	v_fma_f32 v65, -v8, v23, 1.0
	v_fmac_f32_e32 v23, v65, v23
	v_mul_f32_e32 v65, v61, v23
	v_fma_f32 v66, -v8, v65, v61
	v_fmac_f32_e32 v65, v66, v23
	v_fma_f32 v8, -v8, v65, v61
	v_div_fmas_f32 v8, v8, v23, v65
	v_div_fixup_f32 v4, v8, v5, v4
	ds_write_b32 v2, v4 offset:22528
	s_waitcnt vmcnt(12)
	v_mov_b32_e32 v4, v173
	v_mul_f32_e32 v5, 0xbfb8aa3b, v4
	v_fma_f32 v8, v4, s67, -v5
	v_rndne_f32_e32 v23, v5
	v_fmac_f32_e32 v8, 0xb2a5705f, v4
	v_sub_f32_e32 v5, v5, v23
	v_add_f32_e32 v5, v5, v8
	v_cvt_i32_f32_e32 v23, v23
	v_exp_f32_e32 v5, v5
	v_cmp_nlt_f32_e32 vcc, s68, v4
	v_ldexp_f32 v5, v5, v23
	s_nop 0
	v_cndmask_b32_e32 v5, 0, v5, vcc
	v_cmp_ngt_f32_e32 vcc, s69, v4
	s_nop 1
	v_cndmask_b32_e32 v5, v95, v5, vcc
	v_add_f32_e32 v5, 1.0, v5
	v_div_scale_f32 v8, s[54:55], v5, v5, v4
	v_rcp_f32_e32 v23, v8
	v_div_scale_f32 v61, vcc, v4, v5, v4
	v_fma_f32 v65, -v8, v23, 1.0
	v_fmac_f32_e32 v23, v65, v23
	v_mul_f32_e32 v65, v61, v23
	v_fma_f32 v66, -v8, v65, v61
	v_fmac_f32_e32 v65, v66, v23
	v_fma_f32 v8, -v8, v65, v61
	v_div_fmas_f32 v8, v8, v23, v65
	v_div_fixup_f32 v4, v8, v5, v4
	ds_write_b32 v2, v4 offset:23552
	s_waitcnt vmcnt(11)
	v_mov_b32_e32 v4, v174
	v_mul_f32_e32 v5, 0xbfb8aa3b, v4
	v_fma_f32 v8, v4, s67, -v5
	v_rndne_f32_e32 v23, v5
	v_fmac_f32_e32 v8, 0xb2a5705f, v4
	v_sub_f32_e32 v5, v5, v23
	v_add_f32_e32 v5, v5, v8
	v_cvt_i32_f32_e32 v23, v23
	v_exp_f32_e32 v5, v5
	v_cmp_nlt_f32_e32 vcc, s68, v4
	v_ldexp_f32 v5, v5, v23
	s_nop 0
	v_cndmask_b32_e32 v5, 0, v5, vcc
	v_cmp_ngt_f32_e32 vcc, s69, v4
	s_nop 1
	v_cndmask_b32_e32 v5, v95, v5, vcc
	v_add_f32_e32 v5, 1.0, v5
	v_div_scale_f32 v8, s[54:55], v5, v5, v4
	v_rcp_f32_e32 v23, v8
	v_div_scale_f32 v61, vcc, v4, v5, v4
	v_fma_f32 v65, -v8, v23, 1.0
	v_fmac_f32_e32 v23, v65, v23
	v_mul_f32_e32 v65, v61, v23
	v_fma_f32 v66, -v8, v65, v61
	v_fmac_f32_e32 v65, v66, v23
	v_fma_f32 v8, -v8, v65, v61
	v_div_fmas_f32 v8, v8, v23, v65
	v_div_fixup_f32 v4, v8, v5, v4
	ds_write_b32 v2, v4 offset:24576
	s_waitcnt vmcnt(10)
	v_mov_b32_e32 v4, v175
	v_mul_f32_e32 v5, 0xbfb8aa3b, v4
	v_fma_f32 v8, v4, s67, -v5
	v_rndne_f32_e32 v23, v5
	v_fmac_f32_e32 v8, 0xb2a5705f, v4
	v_sub_f32_e32 v5, v5, v23
	v_add_f32_e32 v5, v5, v8
	v_cvt_i32_f32_e32 v23, v23
	v_exp_f32_e32 v5, v5
	v_cmp_nlt_f32_e32 vcc, s68, v4
	v_ldexp_f32 v5, v5, v23
	s_nop 0
	v_cndmask_b32_e32 v5, 0, v5, vcc
	v_cmp_ngt_f32_e32 vcc, s69, v4
	s_nop 1
	v_cndmask_b32_e32 v5, v95, v5, vcc
	v_add_f32_e32 v5, 1.0, v5
	v_div_scale_f32 v8, s[54:55], v5, v5, v4
	v_rcp_f32_e32 v23, v8
	v_div_scale_f32 v61, vcc, v4, v5, v4
	v_fma_f32 v65, -v8, v23, 1.0
	v_fmac_f32_e32 v23, v65, v23
	v_mul_f32_e32 v65, v61, v23
	v_fma_f32 v66, -v8, v65, v61
	v_fmac_f32_e32 v65, v66, v23
	v_fma_f32 v8, -v8, v65, v61
	v_div_fmas_f32 v8, v8, v23, v65
	v_div_fixup_f32 v4, v8, v5, v4
	ds_write_b32 v2, v4 offset:25600
	s_waitcnt vmcnt(9)
	v_mov_b32_e32 v4, v176
	v_mul_f32_e32 v5, 0xbfb8aa3b, v4
	v_fma_f32 v8, v4, s67, -v5
	v_rndne_f32_e32 v23, v5
	v_fmac_f32_e32 v8, 0xb2a5705f, v4
	v_sub_f32_e32 v5, v5, v23
	v_add_f32_e32 v5, v5, v8
	v_cvt_i32_f32_e32 v23, v23
	v_exp_f32_e32 v5, v5
	v_cmp_nlt_f32_e32 vcc, s68, v4
	v_ldexp_f32 v5, v5, v23
	s_nop 0
	v_cndmask_b32_e32 v5, 0, v5, vcc
	v_cmp_ngt_f32_e32 vcc, s69, v4
	s_nop 1
	v_cndmask_b32_e32 v5, v95, v5, vcc
	v_add_f32_e32 v5, 1.0, v5
	v_div_scale_f32 v8, s[54:55], v5, v5, v4
	v_rcp_f32_e32 v23, v8
	v_div_scale_f32 v61, vcc, v4, v5, v4
	v_fma_f32 v65, -v8, v23, 1.0
	v_fmac_f32_e32 v23, v65, v23
	v_mul_f32_e32 v65, v61, v23
	v_fma_f32 v66, -v8, v65, v61
	v_fmac_f32_e32 v65, v66, v23
	v_fma_f32 v8, -v8, v65, v61
	v_div_fmas_f32 v8, v8, v23, v65
	v_div_fixup_f32 v4, v8, v5, v4
	ds_write_b32 v2, v4 offset:26624
	s_waitcnt vmcnt(8)
	v_mov_b32_e32 v4, v177
	v_mul_f32_e32 v5, 0xbfb8aa3b, v4
	v_fma_f32 v8, v4, s67, -v5
	v_rndne_f32_e32 v23, v5
	v_fmac_f32_e32 v8, 0xb2a5705f, v4
	v_sub_f32_e32 v5, v5, v23
	v_add_f32_e32 v5, v5, v8
	v_cvt_i32_f32_e32 v23, v23
	v_exp_f32_e32 v5, v5
	v_cmp_nlt_f32_e32 vcc, s68, v4
	v_ldexp_f32 v5, v5, v23
	s_nop 0
	v_cndmask_b32_e32 v5, 0, v5, vcc
	v_cmp_ngt_f32_e32 vcc, s69, v4
	s_nop 1
	v_cndmask_b32_e32 v5, v95, v5, vcc
	v_add_f32_e32 v5, 1.0, v5
	v_div_scale_f32 v8, s[54:55], v5, v5, v4
	v_rcp_f32_e32 v23, v8
	v_div_scale_f32 v61, vcc, v4, v5, v4
	v_fma_f32 v65, -v8, v23, 1.0
	v_fmac_f32_e32 v23, v65, v23
	v_mul_f32_e32 v65, v61, v23
	v_fma_f32 v66, -v8, v65, v61
	v_fmac_f32_e32 v65, v66, v23
	v_fma_f32 v8, -v8, v65, v61
	v_div_fmas_f32 v8, v8, v23, v65
	v_div_fixup_f32 v4, v8, v5, v4
	ds_write_b32 v2, v4 offset:27648
	s_waitcnt vmcnt(7)
	v_mov_b32_e32 v4, v178
	v_mul_f32_e32 v5, 0xbfb8aa3b, v4
	v_fma_f32 v8, v4, s67, -v5
	v_rndne_f32_e32 v23, v5
	v_fmac_f32_e32 v8, 0xb2a5705f, v4
	v_sub_f32_e32 v5, v5, v23
	v_add_f32_e32 v5, v5, v8
	v_cvt_i32_f32_e32 v23, v23
	v_exp_f32_e32 v5, v5
	v_cmp_nlt_f32_e32 vcc, s68, v4
	v_ldexp_f32 v5, v5, v23
	s_nop 0
	v_cndmask_b32_e32 v5, 0, v5, vcc
	v_cmp_ngt_f32_e32 vcc, s69, v4
	s_nop 1
	v_cndmask_b32_e32 v5, v95, v5, vcc
	v_add_f32_e32 v5, 1.0, v5
	v_div_scale_f32 v8, s[54:55], v5, v5, v4
	v_rcp_f32_e32 v23, v8
	v_div_scale_f32 v61, vcc, v4, v5, v4
	v_fma_f32 v65, -v8, v23, 1.0
	v_fmac_f32_e32 v23, v65, v23
	v_mul_f32_e32 v65, v61, v23
	v_fma_f32 v66, -v8, v65, v61
	v_fmac_f32_e32 v65, v66, v23
	v_fma_f32 v8, -v8, v65, v61
	v_div_fmas_f32 v8, v8, v23, v65
	v_div_fixup_f32 v4, v8, v5, v4
	ds_write_b32 v2, v4 offset:28672
	s_waitcnt vmcnt(6)
	v_mov_b32_e32 v4, v179
	v_mul_f32_e32 v5, 0xbfb8aa3b, v4
	v_fma_f32 v8, v4, s67, -v5
	v_rndne_f32_e32 v23, v5
	v_fmac_f32_e32 v8, 0xb2a5705f, v4
	v_sub_f32_e32 v5, v5, v23
	v_add_f32_e32 v5, v5, v8
	v_cvt_i32_f32_e32 v23, v23
	v_exp_f32_e32 v5, v5
	v_cmp_nlt_f32_e32 vcc, s68, v4
	v_ldexp_f32 v5, v5, v23
	s_nop 0
	v_cndmask_b32_e32 v5, 0, v5, vcc
	v_cmp_ngt_f32_e32 vcc, s69, v4
	s_nop 1
	v_cndmask_b32_e32 v5, v95, v5, vcc
	v_add_f32_e32 v5, 1.0, v5
	v_div_scale_f32 v8, s[54:55], v5, v5, v4
	v_rcp_f32_e32 v23, v8
	v_div_scale_f32 v61, vcc, v4, v5, v4
	v_fma_f32 v65, -v8, v23, 1.0
	v_fmac_f32_e32 v23, v65, v23
	v_mul_f32_e32 v65, v61, v23
	v_fma_f32 v66, -v8, v65, v61
	v_fmac_f32_e32 v65, v66, v23
	v_fma_f32 v8, -v8, v65, v61
	v_div_fmas_f32 v8, v8, v23, v65
	v_div_fixup_f32 v4, v8, v5, v4
	ds_write_b32 v2, v4 offset:29696
	s_waitcnt vmcnt(5)
	v_mov_b32_e32 v4, v180
	v_mul_f32_e32 v5, 0xbfb8aa3b, v4
	v_fma_f32 v8, v4, s67, -v5
	v_rndne_f32_e32 v23, v5
	v_fmac_f32_e32 v8, 0xb2a5705f, v4
	v_sub_f32_e32 v5, v5, v23
	v_add_f32_e32 v5, v5, v8
	v_cvt_i32_f32_e32 v23, v23
	v_exp_f32_e32 v5, v5
	v_cmp_nlt_f32_e32 vcc, s68, v4
	v_ldexp_f32 v5, v5, v23
	s_nop 0
	v_cndmask_b32_e32 v5, 0, v5, vcc
	v_cmp_ngt_f32_e32 vcc, s69, v4
	s_nop 1
	v_cndmask_b32_e32 v5, v95, v5, vcc
	v_add_f32_e32 v5, 1.0, v5
	v_div_scale_f32 v8, s[54:55], v5, v5, v4
	v_rcp_f32_e32 v23, v8
	v_div_scale_f32 v61, vcc, v4, v5, v4
	v_fma_f32 v65, -v8, v23, 1.0
	v_fmac_f32_e32 v23, v65, v23
	v_mul_f32_e32 v65, v61, v23
	v_fma_f32 v66, -v8, v65, v61
	v_fmac_f32_e32 v65, v66, v23
	v_fma_f32 v8, -v8, v65, v61
	v_div_fmas_f32 v8, v8, v23, v65
	v_div_fixup_f32 v4, v8, v5, v4
	ds_write_b32 v2, v4 offset:30720
	s_waitcnt vmcnt(4)
	v_mov_b32_e32 v4, v181
	v_mul_f32_e32 v5, 0xbfb8aa3b, v4
	v_fma_f32 v8, v4, s67, -v5
	v_rndne_f32_e32 v23, v5
	v_fmac_f32_e32 v8, 0xb2a5705f, v4
	v_sub_f32_e32 v5, v5, v23
	v_add_f32_e32 v5, v5, v8
	v_cvt_i32_f32_e32 v23, v23
	v_exp_f32_e32 v5, v5
	v_cmp_nlt_f32_e32 vcc, s68, v4
	v_ldexp_f32 v5, v5, v23
	s_nop 0
	v_cndmask_b32_e32 v5, 0, v5, vcc
	v_cmp_ngt_f32_e32 vcc, s69, v4
	s_nop 1
	v_cndmask_b32_e32 v5, v95, v5, vcc
	v_add_f32_e32 v5, 1.0, v5
	v_div_scale_f32 v8, s[54:55], v5, v5, v4
	v_rcp_f32_e32 v23, v8
	v_div_scale_f32 v61, vcc, v4, v5, v4
	v_fma_f32 v65, -v8, v23, 1.0
	v_fmac_f32_e32 v23, v65, v23
	v_mul_f32_e32 v65, v61, v23
	v_fma_f32 v66, -v8, v65, v61
	v_fmac_f32_e32 v65, v66, v23
	v_fma_f32 v8, -v8, v65, v61
	v_div_fmas_f32 v8, v8, v23, v65
	v_div_fixup_f32 v4, v8, v5, v4
	ds_write_b32 v2, v4 offset:31744
	s_waitcnt vmcnt(3)
	v_mov_b32_e32 v4, v182
	v_mul_f32_e32 v5, 0xbfb8aa3b, v4
	v_fma_f32 v8, v4, s67, -v5
	v_rndne_f32_e32 v23, v5
	v_fmac_f32_e32 v8, 0xb2a5705f, v4
	v_sub_f32_e32 v5, v5, v23
	v_add_f32_e32 v5, v5, v8
	v_cvt_i32_f32_e32 v23, v23
	v_exp_f32_e32 v5, v5
	v_cmp_nlt_f32_e32 vcc, s68, v4
	v_ldexp_f32 v5, v5, v23
	s_nop 0
	v_cndmask_b32_e32 v5, 0, v5, vcc
	v_cmp_ngt_f32_e32 vcc, s69, v4
	s_nop 1
	v_cndmask_b32_e32 v5, v95, v5, vcc
	v_add_f32_e32 v5, 1.0, v5
	v_div_scale_f32 v8, s[54:55], v5, v5, v4
	v_rcp_f32_e32 v23, v8
	v_div_scale_f32 v61, vcc, v4, v5, v4
	v_fma_f32 v65, -v8, v23, 1.0
	v_fmac_f32_e32 v23, v65, v23
	v_mul_f32_e32 v65, v61, v23
	v_fma_f32 v66, -v8, v65, v61
	v_fmac_f32_e32 v65, v66, v23
	v_fma_f32 v8, -v8, v65, v61
	v_div_fmas_f32 v8, v8, v23, v65
	v_div_fixup_f32 v4, v8, v5, v4
	ds_write_b32 v2, v4 offset:32768
	s_waitcnt vmcnt(2)
	v_mov_b32_e32 v4, v183
	v_mul_f32_e32 v5, 0xbfb8aa3b, v4
	v_fma_f32 v8, v4, s67, -v5
	v_rndne_f32_e32 v23, v5
	v_fmac_f32_e32 v8, 0xb2a5705f, v4
	v_sub_f32_e32 v5, v5, v23
	v_add_f32_e32 v5, v5, v8
	v_cvt_i32_f32_e32 v23, v23
	v_exp_f32_e32 v5, v5
	v_cmp_nlt_f32_e32 vcc, s68, v4
	v_ldexp_f32 v5, v5, v23
	s_nop 0
	v_cndmask_b32_e32 v5, 0, v5, vcc
	v_cmp_ngt_f32_e32 vcc, s69, v4
	s_nop 1
	v_cndmask_b32_e32 v5, v95, v5, vcc
	v_add_f32_e32 v5, 1.0, v5
	v_div_scale_f32 v8, s[54:55], v5, v5, v4
	v_rcp_f32_e32 v23, v8
	v_div_scale_f32 v61, vcc, v4, v5, v4
	v_fma_f32 v65, -v8, v23, 1.0
	v_fmac_f32_e32 v23, v65, v23
	v_mul_f32_e32 v65, v61, v23
	v_fma_f32 v66, -v8, v65, v61
	v_fmac_f32_e32 v65, v66, v23
	v_fma_f32 v8, -v8, v65, v61
	v_div_fmas_f32 v8, v8, v23, v65
	v_div_fixup_f32 v4, v8, v5, v4
	ds_write_b32 v2, v4 offset:33792
	s_waitcnt vmcnt(1)
	v_mov_b32_e32 v4, v184
	v_mul_f32_e32 v5, 0xbfb8aa3b, v4
	v_fma_f32 v8, v4, s67, -v5
	v_rndne_f32_e32 v23, v5
	v_fmac_f32_e32 v8, 0xb2a5705f, v4
	v_sub_f32_e32 v5, v5, v23
	v_add_f32_e32 v5, v5, v8
	v_cvt_i32_f32_e32 v23, v23
	v_exp_f32_e32 v5, v5
	v_cmp_nlt_f32_e32 vcc, s68, v4
	v_ldexp_f32 v5, v5, v23
	s_nop 0
	v_cndmask_b32_e32 v5, 0, v5, vcc
	v_cmp_ngt_f32_e32 vcc, s69, v4
	s_nop 1
	v_cndmask_b32_e32 v5, v95, v5, vcc
	v_add_f32_e32 v5, 1.0, v5
	v_div_scale_f32 v8, s[54:55], v5, v5, v4
	v_rcp_f32_e32 v23, v8
	v_div_scale_f32 v61, vcc, v4, v5, v4
	v_fma_f32 v65, -v8, v23, 1.0
	v_fmac_f32_e32 v23, v65, v23
	v_mul_f32_e32 v65, v61, v23
	v_fma_f32 v66, -v8, v65, v61
	v_fmac_f32_e32 v65, v66, v23
	v_fma_f32 v8, -v8, v65, v61
	v_div_fmas_f32 v8, v8, v23, v65
	v_div_fixup_f32 v4, v8, v5, v4
	ds_write_b32 v2, v4 offset:34816
	s_waitcnt vmcnt(0)
	v_mov_b32_e32 v4, v185
	v_mul_f32_e32 v5, 0xbfb8aa3b, v4
	v_fma_f32 v8, v4, s67, -v5
	v_rndne_f32_e32 v23, v5
	v_fmac_f32_e32 v8, 0xb2a5705f, v4
	v_sub_f32_e32 v5, v5, v23
	v_add_f32_e32 v5, v5, v8
	v_cvt_i32_f32_e32 v23, v23
	v_exp_f32_e32 v5, v5
	v_cmp_nlt_f32_e32 vcc, s68, v4
	v_ldexp_f32 v5, v5, v23
	s_nop 0
	v_cndmask_b32_e32 v5, 0, v5, vcc
	v_cmp_ngt_f32_e32 vcc, s69, v4
	s_nop 1
	v_cndmask_b32_e32 v5, v95, v5, vcc
	v_add_f32_e32 v5, 1.0, v5
	v_div_scale_f32 v8, s[54:55], v5, v5, v4
	v_rcp_f32_e32 v23, v8
	v_div_scale_f32 v61, vcc, v4, v5, v4
	v_fma_f32 v65, -v8, v23, 1.0
	v_fmac_f32_e32 v23, v65, v23
	v_mul_f32_e32 v65, v61, v23
	v_fma_f32 v66, -v8, v65, v61
	v_fmac_f32_e32 v65, v66, v23
	v_fma_f32 v8, -v8, v65, v61
	v_div_fmas_f32 v8, v8, v23, v65
	v_div_fixup_f32 v4, v8, v5, v4
	ds_write_b32 v2, v4 offset:35840
	s_or_b64 exec, exec, s[52:53]
	v_mov_b32_e32 v2, s72
	s_waitcnt lgkmcnt(0)
	s_barrier
	ds_read_b64 v[2:3], v2
	v_mov_b32_e32 v61, v9
	v_mov_b32_e32 v4, 0
	s_mov_b64 s[52:53], 0
	v_mov_b32_e32 v8, v81
	s_waitcnt lgkmcnt(0)
	v_add_co_u32_e32 v2, vcc, v2, v10
	v_addc_co_u32_e32 v3, vcc, v3, v11, vcc
	v_lshl_add_u64 v[2:3], v[60:61], 2, v[2:3]
	v_mov_b32_e32 v5, v4
	v_mov_b32_e32 v68, v4
	v_mov_b32_e32 v69, v4
	v_mov_b32_e32 v70, v4
	v_mov_b32_e32 v71, v4
	v_mov_b32_e32 v72, v4
	v_mov_b32_e32 v73, v4
	v_mov_b32_e32 v23, v4
	v_mov_b32_e32 v210, v2
	v_mov_b32_e32 v211, v3
	global_load_dword v150, v[210:211], off
	v_add_co_u32_e32 v210, vcc, 0x6000, v210
	v_addc_co_u32_e32 v211, vcc, 0, v211, vcc
	global_load_dword v151, v[210:211], off
	v_add_co_u32_e32 v210, vcc, 0x6000, v210
	v_addc_co_u32_e32 v211, vcc, 0, v211, vcc
	global_load_dword v152, v[210:211], off
	v_add_co_u32_e32 v210, vcc, 0x6000, v210
	v_addc_co_u32_e32 v211, vcc, 0, v211, vcc
	global_load_dword v153, v[210:211], off
	v_add_co_u32_e32 v210, vcc, 0x6000, v210
	v_addc_co_u32_e32 v211, vcc, 0, v211, vcc
	global_load_dword v154, v[210:211], off
	v_add_co_u32_e32 v210, vcc, 0x6000, v210
	v_addc_co_u32_e32 v211, vcc, 0, v211, vcc
	global_load_dword v155, v[210:211], off
	v_add_co_u32_e32 v210, vcc, 0x6000, v210
	v_addc_co_u32_e32 v211, vcc, 0, v211, vcc
	global_load_dword v156, v[210:211], off
	v_add_co_u32_e32 v210, vcc, 0x6000, v210
	v_addc_co_u32_e32 v211, vcc, 0, v211, vcc
	global_load_dword v157, v[210:211], off
	v_add_co_u32_e32 v210, vcc, 0x6000, v210
	v_addc_co_u32_e32 v211, vcc, 0, v211, vcc
	global_load_dword v158, v[210:211], off
	v_add_co_u32_e32 v210, vcc, 0x6000, v210
	v_addc_co_u32_e32 v211, vcc, 0, v211, vcc
	global_load_dword v159, v[210:211], off
	v_add_co_u32_e32 v210, vcc, 0x6000, v210
	v_addc_co_u32_e32 v211, vcc, 0, v211, vcc
	global_load_dword v160, v[210:211], off
	v_add_co_u32_e32 v210, vcc, 0x6000, v210
	v_addc_co_u32_e32 v211, vcc, 0, v211, vcc
	global_load_dword v161, v[210:211], off
	v_add_co_u32_e32 v210, vcc, 0x6000, v210
	v_addc_co_u32_e32 v211, vcc, 0, v211, vcc
	global_load_dword v162, v[210:211], off
	v_add_co_u32_e32 v210, vcc, 0x6000, v210
	v_addc_co_u32_e32 v211, vcc, 0, v211, vcc
	global_load_dword v163, v[210:211], off
	v_add_co_u32_e32 v210, vcc, 0x6000, v210
	v_addc_co_u32_e32 v211, vcc, 0, v211, vcc
	global_load_dword v164, v[210:211], off
	v_add_co_u32_e32 v210, vcc, 0x6000, v210
	v_addc_co_u32_e32 v211, vcc, 0, v211, vcc
	global_load_dword v165, v[210:211], off
	v_add_co_u32_e32 v210, vcc, 0x6000, v210
	v_addc_co_u32_e32 v211, vcc, 0, v211, vcc
	global_load_dword v166, v[210:211], off
	v_add_co_u32_e32 v210, vcc, 0x6000, v210
	v_addc_co_u32_e32 v211, vcc, 0, v211, vcc
	global_load_dword v167, v[210:211], off
	v_add_co_u32_e32 v210, vcc, 0x6000, v210
	v_addc_co_u32_e32 v211, vcc, 0, v211, vcc
	global_load_dword v168, v[210:211], off
	v_add_co_u32_e32 v210, vcc, 0x6000, v210
	v_addc_co_u32_e32 v211, vcc, 0, v211, vcc
	global_load_dword v169, v[210:211], off
	v_add_co_u32_e32 v210, vcc, 0x6000, v210
	v_addc_co_u32_e32 v211, vcc, 0, v211, vcc
	global_load_dword v170, v[210:211], off
	v_add_co_u32_e32 v210, vcc, 0x6000, v210
	v_addc_co_u32_e32 v211, vcc, 0, v211, vcc
	global_load_dword v171, v[210:211], off
	v_add_co_u32_e32 v210, vcc, 0x6000, v210
	v_addc_co_u32_e32 v211, vcc, 0, v211, vcc
	global_load_dword v172, v[210:211], off
	v_add_co_u32_e32 v210, vcc, 0x6000, v210
	v_addc_co_u32_e32 v211, vcc, 0, v211, vcc
	global_load_dword v173, v[210:211], off
	v_add_co_u32_e32 v210, vcc, 0x6000, v210
	v_addc_co_u32_e32 v211, vcc, 0, v211, vcc
	global_load_dword v174, v[210:211], off
	v_add_co_u32_e32 v210, vcc, 0x6000, v210
	v_addc_co_u32_e32 v211, vcc, 0, v211, vcc
	global_load_dword v175, v[210:211], off
	v_add_co_u32_e32 v210, vcc, 0x6000, v210
	v_addc_co_u32_e32 v211, vcc, 0, v211, vcc
	global_load_dword v176, v[210:211], off
	v_add_co_u32_e32 v210, vcc, 0x6000, v210
	v_addc_co_u32_e32 v211, vcc, 0, v211, vcc
	global_load_dword v177, v[210:211], off
	v_add_co_u32_e32 v210, vcc, 0x6000, v210
	v_addc_co_u32_e32 v211, vcc, 0, v211, vcc
	global_load_dword v178, v[210:211], off
	v_add_co_u32_e32 v210, vcc, 0x6000, v210
	v_addc_co_u32_e32 v211, vcc, 0, v211, vcc
	global_load_dword v179, v[210:211], off
	v_add_co_u32_e32 v210, vcc, 0x6000, v210
	v_addc_co_u32_e32 v211, vcc, 0, v211, vcc
	global_load_dword v180, v[210:211], off
	v_add_co_u32_e32 v210, vcc, 0x6000, v210
	v_addc_co_u32_e32 v211, vcc, 0, v211, vcc
	global_load_dword v181, v[210:211], off
	v_add_co_u32_e32 v210, vcc, 0x6000, v210
	v_addc_co_u32_e32 v211, vcc, 0, v211, vcc
	global_load_dword v182, v[210:211], off
	v_add_co_u32_e32 v210, vcc, 0x6000, v210
	v_addc_co_u32_e32 v211, vcc, 0, v211, vcc
	global_load_dword v183, v[210:211], off
	v_add_co_u32_e32 v210, vcc, 0x6000, v210
	v_addc_co_u32_e32 v211, vcc, 0, v211, vcc
	global_load_dword v184, v[210:211], off
	v_add_co_u32_e32 v210, vcc, 0x6000, v210
	v_addc_co_u32_e32 v211, vcc, 0, v211, vcc
	global_load_dword v185, v[210:211], off
	v_add_co_u32_e32 v210, vcc, 0x6000, v210
	v_addc_co_u32_e32 v211, vcc, 0, v211, vcc
	global_load_dword v186, v[210:211], off
	v_add_co_u32_e32 v210, vcc, 0x6000, v210
	v_addc_co_u32_e32 v211, vcc, 0, v211, vcc
	global_load_dword v187, v[210:211], off
	v_add_co_u32_e32 v210, vcc, 0x6000, v210
	v_addc_co_u32_e32 v211, vcc, 0, v211, vcc
	global_load_dword v188, v[210:211], off
	v_add_co_u32_e32 v210, vcc, 0x6000, v210
	v_addc_co_u32_e32 v211, vcc, 0, v211, vcc
	global_load_dword v189, v[210:211], off
	v_add_co_u32_e32 v210, vcc, 0x6000, v210
	v_addc_co_u32_e32 v211, vcc, 0, v211, vcc
	global_load_dword v190, v[210:211], off
	v_add_co_u32_e32 v210, vcc, 0x6000, v210
	v_addc_co_u32_e32 v211, vcc, 0, v211, vcc
	global_load_dword v191, v[210:211], off
	v_add_co_u32_e32 v210, vcc, 0x6000, v210
	v_addc_co_u32_e32 v211, vcc, 0, v211, vcc
	global_load_dword v192, v[210:211], off
	v_add_co_u32_e32 v210, vcc, 0x6000, v210
	v_addc_co_u32_e32 v211, vcc, 0, v211, vcc
	global_load_dword v193, v[210:211], off
	v_add_co_u32_e32 v210, vcc, 0x6000, v210
	v_addc_co_u32_e32 v211, vcc, 0, v211, vcc
	global_load_dword v194, v[210:211], off
	v_add_co_u32_e32 v210, vcc, 0x6000, v210
	v_addc_co_u32_e32 v211, vcc, 0, v211, vcc
	global_load_dword v195, v[210:211], off
	v_add_co_u32_e32 v210, vcc, 0x6000, v210
	v_addc_co_u32_e32 v211, vcc, 0, v211, vcc
	global_load_dword v196, v[210:211], off
	v_add_co_u32_e32 v210, vcc, 0x6000, v210
	v_addc_co_u32_e32 v211, vcc, 0, v211, vcc
	global_load_dword v197, v[210:211], off
	v_add_co_u32_e32 v210, vcc, 0x6000, v210
	v_addc_co_u32_e32 v211, vcc, 0, v211, vcc
	global_load_dword v198, v[210:211], off
	v_add_co_u32_e32 v210, vcc, 0x6000, v210
	v_addc_co_u32_e32 v211, vcc, 0, v211, vcc
	global_load_dword v199, v[210:211], off
	v_add_co_u32_e32 v210, vcc, 0x6000, v210
	v_addc_co_u32_e32 v211, vcc, 0, v211, vcc
	global_load_dword v200, v[210:211], off
	v_add_co_u32_e32 v210, vcc, 0x6000, v210
	v_addc_co_u32_e32 v211, vcc, 0, v211, vcc
	global_load_dword v201, v[210:211], off
	v_add_co_u32_e32 v210, vcc, 0x6000, v210
	v_addc_co_u32_e32 v211, vcc, 0, v211, vcc
	global_load_dword v202, v[210:211], off
	v_add_co_u32_e32 v210, vcc, 0x6000, v210
	v_addc_co_u32_e32 v211, vcc, 0, v211, vcc
	global_load_dword v203, v[210:211], off
	v_add_co_u32_e32 v210, vcc, 0x6000, v210
	v_addc_co_u32_e32 v211, vcc, 0, v211, vcc
	global_load_dword v204, v[210:211], off
	v_add_co_u32_e32 v210, vcc, 0x6000, v210
	v_addc_co_u32_e32 v211, vcc, 0, v211, vcc
	global_load_dword v205, v[210:211], off
	v_add_co_u32_e32 v210, vcc, 0x6000, v210
	v_addc_co_u32_e32 v211, vcc, 0, v211, vcc
	global_load_dword v206, v[210:211], off
	v_add_co_u32_e32 v210, vcc, 0x6000, v210
	v_addc_co_u32_e32 v211, vcc, 0, v211, vcc
	global_load_dword v207, v[210:211], off
	v_add_co_u32_e32 v210, vcc, 0x6000, v210
	v_addc_co_u32_e32 v211, vcc, 0, v211, vcc
	global_load_dword v208, v[210:211], off
	v_add_co_u32_e32 v210, vcc, 0x6000, v210
	v_addc_co_u32_e32 v211, vcc, 0, v211, vcc
	global_load_dword v209, v[210:211], off
	v_add_co_u32_e32 v210, vcc, 0x6000, v210
	v_addc_co_u32_e32 v211, vcc, 0, v211, vcc
	ds_read_b128 v[98:101], v8 offset:4096
	ds_read_b128 v[102:105], v8 offset:8192
	ds_read_b128 v[106:109], v8 offset:12288
	ds_read_b128 v[110:113], v8 offset:16384
	ds_read_b128 v[114:117], v8 offset:20480
	ds_read_b128 v[118:121], v8 offset:24576
	ds_read_b128 v[122:125], v8 offset:28672
	ds_read_b128 v[126:129], v8
	ds_read_b128 v[134:137], v8 offset:32768
	s_waitcnt lgkmcnt(0)
	v_mov_b32_e32 v143, v98
	v_mov_b32_e32 v144, v102
	v_mov_b32_e32 v145, v106
	v_mov_b32_e32 v142, v126
	v_mov_b32_e32 v146, v110
	v_mov_b32_e32 v147, v114
	v_mov_b32_e32 v148, v118
	v_mov_b32_e32 v149, v122
	v_mov_b32_e32 v98, v127
	v_mov_b32_e32 v106, v103
	v_mov_b32_e32 v114, v111
	v_mov_b32_e32 v122, v119
	v_mov_b32_e32 v102, v128
	v_mov_b32_e32 v103, v100
	v_mov_b32_e32 v110, v104
	v_mov_b32_e32 v111, v108
	v_mov_b32_e32 v118, v112
	v_mov_b32_e32 v119, v116
	v_mov_b32_e32 v126, v120
	v_mov_b32_e32 v127, v124
	v_mov_b32_e32 v100, v129
	v_mov_b32_e32 v108, v105
	v_mov_b32_e32 v116, v113
	v_mov_b32_e32 v124, v121
	v_add_u32_e32 v8, 16, v8
	s_waitcnt vmcnt(56)
	v_mov_b32_e32 v66, v150
	v_mov_b32_e32 v130, v151
	v_mov_b32_e32 v138, v152
	v_mov_b32_e32 v140, v153
	global_load_dword v150, v[210:211], off
	v_add_co_u32_e32 v210, vcc, 0x6000, v210
	v_addc_co_u32_e32 v211, vcc, 0, v211, vcc
	global_load_dword v151, v[210:211], off
	v_add_co_u32_e32 v210, vcc, 0x6000, v210
	v_addc_co_u32_e32 v211, vcc, 0, v211, vcc
	global_load_dword v152, v[210:211], off
	v_add_co_u32_e32 v210, vcc, 0x6000, v210
	v_addc_co_u32_e32 v211, vcc, 0, v211, vcc
	global_load_dword v153, v[210:211], off
	v_add_co_u32_e32 v210, vcc, 0x6000, v210
	v_addc_co_u32_e32 v211, vcc, 0, v211, vcc
	v_pk_fma_f32 v[4:5], v[66:67], v[142:143], v[4:5] op_sel_hi:[0,1,1]
	v_pk_fma_f32 v[68:69], v[66:67], v[144:145], v[68:69] op_sel_hi:[0,1,1]
	v_pk_fma_f32 v[70:71], v[66:67], v[146:147], v[70:71] op_sel_hi:[0,1,1]
	v_pk_fma_f32 v[72:73], v[66:67], v[148:149], v[72:73] op_sel_hi:[0,1,1]
	v_fmac_f32_e32 v23, v66, v134
	v_pk_fma_f32 v[4:5], v[130:131], v[98:99], v[4:5] op_sel_hi:[0,1,1]
	v_pk_fma_f32 v[68:69], v[130:131], v[106:107], v[68:69] op_sel_hi:[0,1,1]
	v_pk_fma_f32 v[70:71], v[130:131], v[114:115], v[70:71] op_sel_hi:[0,1,1]
	v_pk_fma_f32 v[72:73], v[130:131], v[122:123], v[72:73] op_sel_hi:[0,1,1]
	v_fmac_f32_e32 v23, v130, v135
	v_pk_fma_f32 v[4:5], v[138:139], v[102:103], v[4:5] op_sel_hi:[0,1,1]
	v_pk_fma_f32 v[68:69], v[138:139], v[110:111], v[68:69] op_sel_hi:[0,1,1]
	v_pk_fma_f32 v[70:71], v[138:139], v[118:119], v[70:71] op_sel_hi:[0,1,1]
	v_pk_fma_f32 v[72:73], v[138:139], v[126:127], v[72:73] op_sel_hi:[0,1,1]
	v_fmac_f32_e32 v23, v138, v136
	v_pk_fma_f32 v[4:5], v[140:141], v[100:101], v[4:5] op_sel_hi:[0,1,1]
	v_pk_fma_f32 v[68:69], v[140:141], v[108:109], v[68:69] op_sel_hi:[0,1,1]
	v_pk_fma_f32 v[70:71], v[140:141], v[116:117], v[70:71] op_sel_hi:[0,1,1]
	v_pk_fma_f32 v[72:73], v[140:141], v[124:125], v[72:73] op_sel_hi:[0,1,1]
	v_fmac_f32_e32 v23, v140, v137
	ds_read_b128 v[98:101], v8 offset:4096
	ds_read_b128 v[102:105], v8 offset:8192
	ds_read_b128 v[106:109], v8 offset:12288
	ds_read_b128 v[110:113], v8 offset:16384
	ds_read_b128 v[114:117], v8 offset:20480
	ds_read_b128 v[118:121], v8 offset:24576
	ds_read_b128 v[122:125], v8 offset:28672
	ds_read_b128 v[126:129], v8
	ds_read_b128 v[134:137], v8 offset:32768
	s_waitcnt lgkmcnt(0)
	v_mov_b32_e32 v143, v98
	v_mov_b32_e32 v144, v102
	v_mov_b32_e32 v145, v106
	v_mov_b32_e32 v142, v126
	v_mov_b32_e32 v146, v110
	v_mov_b32_e32 v147, v114
	v_mov_b32_e32 v148, v118
	v_mov_b32_e32 v149, v122
	v_mov_b32_e32 v98, v127
	v_mov_b32_e32 v106, v103
	v_mov_b32_e32 v114, v111
	v_mov_b32_e32 v122, v119
	v_mov_b32_e32 v102, v128
	v_mov_b32_e32 v103, v100
	v_mov_b32_e32 v110, v104
	v_mov_b32_e32 v111, v108
	v_mov_b32_e32 v118, v112
	v_mov_b32_e32 v119, v116
	v_mov_b32_e32 v126, v120
	v_mov_b32_e32 v127, v124
	v_mov_b32_e32 v100, v129
	v_mov_b32_e32 v108, v105
	v_mov_b32_e32 v116, v113
	v_mov_b32_e32 v124, v121
	v_add_u32_e32 v8, 16, v8
	s_waitcnt vmcnt(56)
	v_mov_b32_e32 v66, v154
	v_mov_b32_e32 v130, v155
	v_mov_b32_e32 v138, v156
	v_mov_b32_e32 v140, v157
	global_load_dword v154, v[210:211], off
	v_add_co_u32_e32 v210, vcc, 0x6000, v210
	v_addc_co_u32_e32 v211, vcc, 0, v211, vcc
	global_load_dword v155, v[210:211], off
	v_add_co_u32_e32 v210, vcc, 0x6000, v210
	v_addc_co_u32_e32 v211, vcc, 0, v211, vcc
	global_load_dword v156, v[210:211], off
	v_add_co_u32_e32 v210, vcc, 0x6000, v210
	v_addc_co_u32_e32 v211, vcc, 0, v211, vcc
	global_load_dword v157, v[210:211], off
	v_add_co_u32_e32 v210, vcc, 0x6000, v210
	v_addc_co_u32_e32 v211, vcc, 0, v211, vcc
	v_pk_fma_f32 v[4:5], v[66:67], v[142:143], v[4:5] op_sel_hi:[0,1,1]
	v_pk_fma_f32 v[68:69], v[66:67], v[144:145], v[68:69] op_sel_hi:[0,1,1]
	v_pk_fma_f32 v[70:71], v[66:67], v[146:147], v[70:71] op_sel_hi:[0,1,1]
	v_pk_fma_f32 v[72:73], v[66:67], v[148:149], v[72:73] op_sel_hi:[0,1,1]
	v_fmac_f32_e32 v23, v66, v134
	v_pk_fma_f32 v[4:5], v[130:131], v[98:99], v[4:5] op_sel_hi:[0,1,1]
	v_pk_fma_f32 v[68:69], v[130:131], v[106:107], v[68:69] op_sel_hi:[0,1,1]
	v_pk_fma_f32 v[70:71], v[130:131], v[114:115], v[70:71] op_sel_hi:[0,1,1]
	v_pk_fma_f32 v[72:73], v[130:131], v[122:123], v[72:73] op_sel_hi:[0,1,1]
	v_fmac_f32_e32 v23, v130, v135
	v_pk_fma_f32 v[4:5], v[138:139], v[102:103], v[4:5] op_sel_hi:[0,1,1]
	v_pk_fma_f32 v[68:69], v[138:139], v[110:111], v[68:69] op_sel_hi:[0,1,1]
	v_pk_fma_f32 v[70:71], v[138:139], v[118:119], v[70:71] op_sel_hi:[0,1,1]
	v_pk_fma_f32 v[72:73], v[138:139], v[126:127], v[72:73] op_sel_hi:[0,1,1]
	v_fmac_f32_e32 v23, v138, v136
	v_pk_fma_f32 v[4:5], v[140:141], v[100:101], v[4:5] op_sel_hi:[0,1,1]
	v_pk_fma_f32 v[68:69], v[140:141], v[108:109], v[68:69] op_sel_hi:[0,1,1]
	v_pk_fma_f32 v[70:71], v[140:141], v[116:117], v[70:71] op_sel_hi:[0,1,1]
	v_pk_fma_f32 v[72:73], v[140:141], v[124:125], v[72:73] op_sel_hi:[0,1,1]
	v_fmac_f32_e32 v23, v140, v137
	ds_read_b128 v[98:101], v8 offset:4096
	ds_read_b128 v[102:105], v8 offset:8192
	ds_read_b128 v[106:109], v8 offset:12288
	ds_read_b128 v[110:113], v8 offset:16384
	ds_read_b128 v[114:117], v8 offset:20480
	ds_read_b128 v[118:121], v8 offset:24576
	ds_read_b128 v[122:125], v8 offset:28672
	ds_read_b128 v[126:129], v8
	ds_read_b128 v[134:137], v8 offset:32768
	s_waitcnt lgkmcnt(0)
	v_mov_b32_e32 v143, v98
	v_mov_b32_e32 v144, v102
	v_mov_b32_e32 v145, v106
	v_mov_b32_e32 v142, v126
	v_mov_b32_e32 v146, v110
	v_mov_b32_e32 v147, v114
	v_mov_b32_e32 v148, v118
	v_mov_b32_e32 v149, v122
	v_mov_b32_e32 v98, v127
	v_mov_b32_e32 v106, v103
	v_mov_b32_e32 v114, v111
	v_mov_b32_e32 v122, v119
	v_mov_b32_e32 v102, v128
	v_mov_b32_e32 v103, v100
	v_mov_b32_e32 v110, v104
	v_mov_b32_e32 v111, v108
	v_mov_b32_e32 v118, v112
	v_mov_b32_e32 v119, v116
	v_mov_b32_e32 v126, v120
	v_mov_b32_e32 v127, v124
	v_mov_b32_e32 v100, v129
	v_mov_b32_e32 v108, v105
	v_mov_b32_e32 v116, v113
	v_mov_b32_e32 v124, v121
	v_add_u32_e32 v8, 16, v8
	s_waitcnt vmcnt(56)
	v_mov_b32_e32 v66, v158
	v_mov_b32_e32 v130, v159
	v_mov_b32_e32 v138, v160
	v_mov_b32_e32 v140, v161
	global_load_dword v158, v[210:211], off
	v_add_co_u32_e32 v210, vcc, 0x6000, v210
	v_addc_co_u32_e32 v211, vcc, 0, v211, vcc
	global_load_dword v159, v[210:211], off
	v_add_co_u32_e32 v210, vcc, 0x6000, v210
	v_addc_co_u32_e32 v211, vcc, 0, v211, vcc
	global_load_dword v160, v[210:211], off
	v_add_co_u32_e32 v210, vcc, 0x6000, v210
	v_addc_co_u32_e32 v211, vcc, 0, v211, vcc
	global_load_dword v161, v[210:211], off
	v_add_co_u32_e32 v210, vcc, 0x6000, v210
	v_addc_co_u32_e32 v211, vcc, 0, v211, vcc
	v_pk_fma_f32 v[4:5], v[66:67], v[142:143], v[4:5] op_sel_hi:[0,1,1]
	v_pk_fma_f32 v[68:69], v[66:67], v[144:145], v[68:69] op_sel_hi:[0,1,1]
	v_pk_fma_f32 v[70:71], v[66:67], v[146:147], v[70:71] op_sel_hi:[0,1,1]
	v_pk_fma_f32 v[72:73], v[66:67], v[148:149], v[72:73] op_sel_hi:[0,1,1]
	v_fmac_f32_e32 v23, v66, v134
	v_pk_fma_f32 v[4:5], v[130:131], v[98:99], v[4:5] op_sel_hi:[0,1,1]
	v_pk_fma_f32 v[68:69], v[130:131], v[106:107], v[68:69] op_sel_hi:[0,1,1]
	v_pk_fma_f32 v[70:71], v[130:131], v[114:115], v[70:71] op_sel_hi:[0,1,1]
	v_pk_fma_f32 v[72:73], v[130:131], v[122:123], v[72:73] op_sel_hi:[0,1,1]
	v_fmac_f32_e32 v23, v130, v135
	v_pk_fma_f32 v[4:5], v[138:139], v[102:103], v[4:5] op_sel_hi:[0,1,1]
	v_pk_fma_f32 v[68:69], v[138:139], v[110:111], v[68:69] op_sel_hi:[0,1,1]
	v_pk_fma_f32 v[70:71], v[138:139], v[118:119], v[70:71] op_sel_hi:[0,1,1]
	v_pk_fma_f32 v[72:73], v[138:139], v[126:127], v[72:73] op_sel_hi:[0,1,1]
	v_fmac_f32_e32 v23, v138, v136
	v_pk_fma_f32 v[4:5], v[140:141], v[100:101], v[4:5] op_sel_hi:[0,1,1]
	v_pk_fma_f32 v[68:69], v[140:141], v[108:109], v[68:69] op_sel_hi:[0,1,1]
	v_pk_fma_f32 v[70:71], v[140:141], v[116:117], v[70:71] op_sel_hi:[0,1,1]
	v_pk_fma_f32 v[72:73], v[140:141], v[124:125], v[72:73] op_sel_hi:[0,1,1]
	v_fmac_f32_e32 v23, v140, v137
	ds_read_b128 v[98:101], v8 offset:4096
	ds_read_b128 v[102:105], v8 offset:8192
	ds_read_b128 v[106:109], v8 offset:12288
	ds_read_b128 v[110:113], v8 offset:16384
	ds_read_b128 v[114:117], v8 offset:20480
	ds_read_b128 v[118:121], v8 offset:24576
	ds_read_b128 v[122:125], v8 offset:28672
	ds_read_b128 v[126:129], v8
	ds_read_b128 v[134:137], v8 offset:32768
	s_waitcnt lgkmcnt(0)
	v_mov_b32_e32 v143, v98
	v_mov_b32_e32 v144, v102
	v_mov_b32_e32 v145, v106
	v_mov_b32_e32 v142, v126
	v_mov_b32_e32 v146, v110
	v_mov_b32_e32 v147, v114
	v_mov_b32_e32 v148, v118
	v_mov_b32_e32 v149, v122
	v_mov_b32_e32 v98, v127
	v_mov_b32_e32 v106, v103
	v_mov_b32_e32 v114, v111
	v_mov_b32_e32 v122, v119
	v_mov_b32_e32 v102, v128
	v_mov_b32_e32 v103, v100
	v_mov_b32_e32 v110, v104
	v_mov_b32_e32 v111, v108
	v_mov_b32_e32 v118, v112
	v_mov_b32_e32 v119, v116
	v_mov_b32_e32 v126, v120
	v_mov_b32_e32 v127, v124
	v_mov_b32_e32 v100, v129
	v_mov_b32_e32 v108, v105
	v_mov_b32_e32 v116, v113
	v_mov_b32_e32 v124, v121
	v_add_u32_e32 v8, 16, v8
	s_waitcnt vmcnt(56)
	v_mov_b32_e32 v66, v162
	v_mov_b32_e32 v130, v163
	v_mov_b32_e32 v138, v164
	v_mov_b32_e32 v140, v165
	global_load_dword v162, v[210:211], off
	v_add_co_u32_e32 v210, vcc, 0x6000, v210
	v_addc_co_u32_e32 v211, vcc, 0, v211, vcc
	global_load_dword v163, v[210:211], off
	v_add_co_u32_e32 v210, vcc, 0x6000, v210
	v_addc_co_u32_e32 v211, vcc, 0, v211, vcc
	global_load_dword v164, v[210:211], off
	v_add_co_u32_e32 v210, vcc, 0x6000, v210
	v_addc_co_u32_e32 v211, vcc, 0, v211, vcc
	global_load_dword v165, v[210:211], off
	v_add_co_u32_e32 v210, vcc, 0x6000, v210
	v_addc_co_u32_e32 v211, vcc, 0, v211, vcc
	v_pk_fma_f32 v[4:5], v[66:67], v[142:143], v[4:5] op_sel_hi:[0,1,1]
	v_pk_fma_f32 v[68:69], v[66:67], v[144:145], v[68:69] op_sel_hi:[0,1,1]
	v_pk_fma_f32 v[70:71], v[66:67], v[146:147], v[70:71] op_sel_hi:[0,1,1]
	v_pk_fma_f32 v[72:73], v[66:67], v[148:149], v[72:73] op_sel_hi:[0,1,1]
	v_fmac_f32_e32 v23, v66, v134
	v_pk_fma_f32 v[4:5], v[130:131], v[98:99], v[4:5] op_sel_hi:[0,1,1]
	v_pk_fma_f32 v[68:69], v[130:131], v[106:107], v[68:69] op_sel_hi:[0,1,1]
	v_pk_fma_f32 v[70:71], v[130:131], v[114:115], v[70:71] op_sel_hi:[0,1,1]
	v_pk_fma_f32 v[72:73], v[130:131], v[122:123], v[72:73] op_sel_hi:[0,1,1]
	v_fmac_f32_e32 v23, v130, v135
	v_pk_fma_f32 v[4:5], v[138:139], v[102:103], v[4:5] op_sel_hi:[0,1,1]
	v_pk_fma_f32 v[68:69], v[138:139], v[110:111], v[68:69] op_sel_hi:[0,1,1]
	v_pk_fma_f32 v[70:71], v[138:139], v[118:119], v[70:71] op_sel_hi:[0,1,1]
	v_pk_fma_f32 v[72:73], v[138:139], v[126:127], v[72:73] op_sel_hi:[0,1,1]
	v_fmac_f32_e32 v23, v138, v136
	v_pk_fma_f32 v[4:5], v[140:141], v[100:101], v[4:5] op_sel_hi:[0,1,1]
	v_pk_fma_f32 v[68:69], v[140:141], v[108:109], v[68:69] op_sel_hi:[0,1,1]
	v_pk_fma_f32 v[70:71], v[140:141], v[116:117], v[70:71] op_sel_hi:[0,1,1]
	v_pk_fma_f32 v[72:73], v[140:141], v[124:125], v[72:73] op_sel_hi:[0,1,1]
	v_fmac_f32_e32 v23, v140, v137
	ds_read_b128 v[98:101], v8 offset:4096
	ds_read_b128 v[102:105], v8 offset:8192
	ds_read_b128 v[106:109], v8 offset:12288
	ds_read_b128 v[110:113], v8 offset:16384
	ds_read_b128 v[114:117], v8 offset:20480
	ds_read_b128 v[118:121], v8 offset:24576
	ds_read_b128 v[122:125], v8 offset:28672
	ds_read_b128 v[126:129], v8
	ds_read_b128 v[134:137], v8 offset:32768
	s_waitcnt lgkmcnt(0)
	v_mov_b32_e32 v143, v98
	v_mov_b32_e32 v144, v102
	v_mov_b32_e32 v145, v106
	v_mov_b32_e32 v142, v126
	v_mov_b32_e32 v146, v110
	v_mov_b32_e32 v147, v114
	v_mov_b32_e32 v148, v118
	v_mov_b32_e32 v149, v122
	v_mov_b32_e32 v98, v127
	v_mov_b32_e32 v106, v103
	v_mov_b32_e32 v114, v111
	v_mov_b32_e32 v122, v119
	v_mov_b32_e32 v102, v128
	v_mov_b32_e32 v103, v100
	v_mov_b32_e32 v110, v104
	v_mov_b32_e32 v111, v108
	v_mov_b32_e32 v118, v112
	v_mov_b32_e32 v119, v116
	v_mov_b32_e32 v126, v120
	v_mov_b32_e32 v127, v124
	v_mov_b32_e32 v100, v129
	v_mov_b32_e32 v108, v105
	v_mov_b32_e32 v116, v113
	v_mov_b32_e32 v124, v121
	v_add_u32_e32 v8, 16, v8
	s_waitcnt vmcnt(56)
	v_mov_b32_e32 v66, v166
	v_mov_b32_e32 v130, v167
	v_mov_b32_e32 v138, v168
	v_mov_b32_e32 v140, v169
	global_load_dword v166, v[210:211], off
	v_add_co_u32_e32 v210, vcc, 0x6000, v210
	v_addc_co_u32_e32 v211, vcc, 0, v211, vcc
	global_load_dword v167, v[210:211], off
	v_add_co_u32_e32 v210, vcc, 0x6000, v210
	v_addc_co_u32_e32 v211, vcc, 0, v211, vcc
	global_load_dword v168, v[210:211], off
	v_add_co_u32_e32 v210, vcc, 0x6000, v210
	v_addc_co_u32_e32 v211, vcc, 0, v211, vcc
	global_load_dword v169, v[210:211], off
	v_add_co_u32_e32 v210, vcc, 0x6000, v210
	v_addc_co_u32_e32 v211, vcc, 0, v211, vcc
	v_pk_fma_f32 v[4:5], v[66:67], v[142:143], v[4:5] op_sel_hi:[0,1,1]
	v_pk_fma_f32 v[68:69], v[66:67], v[144:145], v[68:69] op_sel_hi:[0,1,1]
	v_pk_fma_f32 v[70:71], v[66:67], v[146:147], v[70:71] op_sel_hi:[0,1,1]
	v_pk_fma_f32 v[72:73], v[66:67], v[148:149], v[72:73] op_sel_hi:[0,1,1]
	v_fmac_f32_e32 v23, v66, v134
	v_pk_fma_f32 v[4:5], v[130:131], v[98:99], v[4:5] op_sel_hi:[0,1,1]
	v_pk_fma_f32 v[68:69], v[130:131], v[106:107], v[68:69] op_sel_hi:[0,1,1]
	v_pk_fma_f32 v[70:71], v[130:131], v[114:115], v[70:71] op_sel_hi:[0,1,1]
	v_pk_fma_f32 v[72:73], v[130:131], v[122:123], v[72:73] op_sel_hi:[0,1,1]
	v_fmac_f32_e32 v23, v130, v135
	v_pk_fma_f32 v[4:5], v[138:139], v[102:103], v[4:5] op_sel_hi:[0,1,1]
	v_pk_fma_f32 v[68:69], v[138:139], v[110:111], v[68:69] op_sel_hi:[0,1,1]
	v_pk_fma_f32 v[70:71], v[138:139], v[118:119], v[70:71] op_sel_hi:[0,1,1]
	v_pk_fma_f32 v[72:73], v[138:139], v[126:127], v[72:73] op_sel_hi:[0,1,1]
	v_fmac_f32_e32 v23, v138, v136
	v_pk_fma_f32 v[4:5], v[140:141], v[100:101], v[4:5] op_sel_hi:[0,1,1]
	v_pk_fma_f32 v[68:69], v[140:141], v[108:109], v[68:69] op_sel_hi:[0,1,1]
	v_pk_fma_f32 v[70:71], v[140:141], v[116:117], v[70:71] op_sel_hi:[0,1,1]
	v_pk_fma_f32 v[72:73], v[140:141], v[124:125], v[72:73] op_sel_hi:[0,1,1]
	v_fmac_f32_e32 v23, v140, v137
	ds_read_b128 v[98:101], v8 offset:4096
	ds_read_b128 v[102:105], v8 offset:8192
	ds_read_b128 v[106:109], v8 offset:12288
	ds_read_b128 v[110:113], v8 offset:16384
	ds_read_b128 v[114:117], v8 offset:20480
	ds_read_b128 v[118:121], v8 offset:24576
	ds_read_b128 v[122:125], v8 offset:28672
	ds_read_b128 v[126:129], v8
	ds_read_b128 v[134:137], v8 offset:32768
	s_waitcnt lgkmcnt(0)
	v_mov_b32_e32 v143, v98
	v_mov_b32_e32 v144, v102
	v_mov_b32_e32 v145, v106
	v_mov_b32_e32 v142, v126
	v_mov_b32_e32 v146, v110
	v_mov_b32_e32 v147, v114
	v_mov_b32_e32 v148, v118
	v_mov_b32_e32 v149, v122
	v_mov_b32_e32 v98, v127
	v_mov_b32_e32 v106, v103
	v_mov_b32_e32 v114, v111
	v_mov_b32_e32 v122, v119
	v_mov_b32_e32 v102, v128
	v_mov_b32_e32 v103, v100
	v_mov_b32_e32 v110, v104
	v_mov_b32_e32 v111, v108
	v_mov_b32_e32 v118, v112
	v_mov_b32_e32 v119, v116
	v_mov_b32_e32 v126, v120
	v_mov_b32_e32 v127, v124
	v_mov_b32_e32 v100, v129
	v_mov_b32_e32 v108, v105
	v_mov_b32_e32 v116, v113
	v_mov_b32_e32 v124, v121
	v_add_u32_e32 v8, 16, v8
	s_waitcnt vmcnt(56)
	v_mov_b32_e32 v66, v170
	v_mov_b32_e32 v130, v171
	v_mov_b32_e32 v138, v172
	v_mov_b32_e32 v140, v173
	global_load_dword v170, v[210:211], off
	v_add_co_u32_e32 v210, vcc, 0x6000, v210
	v_addc_co_u32_e32 v211, vcc, 0, v211, vcc
	global_load_dword v171, v[210:211], off
	v_add_co_u32_e32 v210, vcc, 0x6000, v210
	v_addc_co_u32_e32 v211, vcc, 0, v211, vcc
	global_load_dword v172, v[210:211], off
	v_add_co_u32_e32 v210, vcc, 0x6000, v210
	v_addc_co_u32_e32 v211, vcc, 0, v211, vcc
	global_load_dword v173, v[210:211], off
	v_add_co_u32_e32 v210, vcc, 0x6000, v210
	v_addc_co_u32_e32 v211, vcc, 0, v211, vcc
	v_pk_fma_f32 v[4:5], v[66:67], v[142:143], v[4:5] op_sel_hi:[0,1,1]
	v_pk_fma_f32 v[68:69], v[66:67], v[144:145], v[68:69] op_sel_hi:[0,1,1]
	v_pk_fma_f32 v[70:71], v[66:67], v[146:147], v[70:71] op_sel_hi:[0,1,1]
	v_pk_fma_f32 v[72:73], v[66:67], v[148:149], v[72:73] op_sel_hi:[0,1,1]
	v_fmac_f32_e32 v23, v66, v134
	v_pk_fma_f32 v[4:5], v[130:131], v[98:99], v[4:5] op_sel_hi:[0,1,1]
	v_pk_fma_f32 v[68:69], v[130:131], v[106:107], v[68:69] op_sel_hi:[0,1,1]
	v_pk_fma_f32 v[70:71], v[130:131], v[114:115], v[70:71] op_sel_hi:[0,1,1]
	v_pk_fma_f32 v[72:73], v[130:131], v[122:123], v[72:73] op_sel_hi:[0,1,1]
	v_fmac_f32_e32 v23, v130, v135
	v_pk_fma_f32 v[4:5], v[138:139], v[102:103], v[4:5] op_sel_hi:[0,1,1]
	v_pk_fma_f32 v[68:69], v[138:139], v[110:111], v[68:69] op_sel_hi:[0,1,1]
	v_pk_fma_f32 v[70:71], v[138:139], v[118:119], v[70:71] op_sel_hi:[0,1,1]
	v_pk_fma_f32 v[72:73], v[138:139], v[126:127], v[72:73] op_sel_hi:[0,1,1]
	v_fmac_f32_e32 v23, v138, v136
	v_pk_fma_f32 v[4:5], v[140:141], v[100:101], v[4:5] op_sel_hi:[0,1,1]
	v_pk_fma_f32 v[68:69], v[140:141], v[108:109], v[68:69] op_sel_hi:[0,1,1]
	v_pk_fma_f32 v[70:71], v[140:141], v[116:117], v[70:71] op_sel_hi:[0,1,1]
	v_pk_fma_f32 v[72:73], v[140:141], v[124:125], v[72:73] op_sel_hi:[0,1,1]
	v_fmac_f32_e32 v23, v140, v137
	ds_read_b128 v[98:101], v8 offset:4096
	ds_read_b128 v[102:105], v8 offset:8192
	ds_read_b128 v[106:109], v8 offset:12288
	ds_read_b128 v[110:113], v8 offset:16384
	ds_read_b128 v[114:117], v8 offset:20480
	ds_read_b128 v[118:121], v8 offset:24576
	ds_read_b128 v[122:125], v8 offset:28672
	ds_read_b128 v[126:129], v8
	ds_read_b128 v[134:137], v8 offset:32768
	s_waitcnt lgkmcnt(0)
	v_mov_b32_e32 v143, v98
	v_mov_b32_e32 v144, v102
	v_mov_b32_e32 v145, v106
	v_mov_b32_e32 v142, v126
	v_mov_b32_e32 v146, v110
	v_mov_b32_e32 v147, v114
	v_mov_b32_e32 v148, v118
	v_mov_b32_e32 v149, v122
	v_mov_b32_e32 v98, v127
	v_mov_b32_e32 v106, v103
	v_mov_b32_e32 v114, v111
	v_mov_b32_e32 v122, v119
	v_mov_b32_e32 v102, v128
	v_mov_b32_e32 v103, v100
	v_mov_b32_e32 v110, v104
	v_mov_b32_e32 v111, v108
	v_mov_b32_e32 v118, v112
	v_mov_b32_e32 v119, v116
	v_mov_b32_e32 v126, v120
	v_mov_b32_e32 v127, v124
	v_mov_b32_e32 v100, v129
	v_mov_b32_e32 v108, v105
	v_mov_b32_e32 v116, v113
	v_mov_b32_e32 v124, v121
	v_add_u32_e32 v8, 16, v8
	s_waitcnt vmcnt(56)
	v_mov_b32_e32 v66, v174
	v_mov_b32_e32 v130, v175
	v_mov_b32_e32 v138, v176
	v_mov_b32_e32 v140, v177
	global_load_dword v174, v[210:211], off
	v_add_co_u32_e32 v210, vcc, 0x6000, v210
	v_addc_co_u32_e32 v211, vcc, 0, v211, vcc
	global_load_dword v175, v[210:211], off
	v_add_co_u32_e32 v210, vcc, 0x6000, v210
	v_addc_co_u32_e32 v211, vcc, 0, v211, vcc
	global_load_dword v176, v[210:211], off
	v_add_co_u32_e32 v210, vcc, 0x6000, v210
	v_addc_co_u32_e32 v211, vcc, 0, v211, vcc
	global_load_dword v177, v[210:211], off
	v_add_co_u32_e32 v210, vcc, 0x6000, v210
	v_addc_co_u32_e32 v211, vcc, 0, v211, vcc
	v_pk_fma_f32 v[4:5], v[66:67], v[142:143], v[4:5] op_sel_hi:[0,1,1]
	v_pk_fma_f32 v[68:69], v[66:67], v[144:145], v[68:69] op_sel_hi:[0,1,1]
	v_pk_fma_f32 v[70:71], v[66:67], v[146:147], v[70:71] op_sel_hi:[0,1,1]
	v_pk_fma_f32 v[72:73], v[66:67], v[148:149], v[72:73] op_sel_hi:[0,1,1]
	v_fmac_f32_e32 v23, v66, v134
	v_pk_fma_f32 v[4:5], v[130:131], v[98:99], v[4:5] op_sel_hi:[0,1,1]
	v_pk_fma_f32 v[68:69], v[130:131], v[106:107], v[68:69] op_sel_hi:[0,1,1]
	v_pk_fma_f32 v[70:71], v[130:131], v[114:115], v[70:71] op_sel_hi:[0,1,1]
	v_pk_fma_f32 v[72:73], v[130:131], v[122:123], v[72:73] op_sel_hi:[0,1,1]
	v_fmac_f32_e32 v23, v130, v135
	v_pk_fma_f32 v[4:5], v[138:139], v[102:103], v[4:5] op_sel_hi:[0,1,1]
	v_pk_fma_f32 v[68:69], v[138:139], v[110:111], v[68:69] op_sel_hi:[0,1,1]
	v_pk_fma_f32 v[70:71], v[138:139], v[118:119], v[70:71] op_sel_hi:[0,1,1]
	v_pk_fma_f32 v[72:73], v[138:139], v[126:127], v[72:73] op_sel_hi:[0,1,1]
	v_fmac_f32_e32 v23, v138, v136
	v_pk_fma_f32 v[4:5], v[140:141], v[100:101], v[4:5] op_sel_hi:[0,1,1]
	v_pk_fma_f32 v[68:69], v[140:141], v[108:109], v[68:69] op_sel_hi:[0,1,1]
	v_pk_fma_f32 v[70:71], v[140:141], v[116:117], v[70:71] op_sel_hi:[0,1,1]
	v_pk_fma_f32 v[72:73], v[140:141], v[124:125], v[72:73] op_sel_hi:[0,1,1]
	v_fmac_f32_e32 v23, v140, v137
	ds_read_b128 v[98:101], v8 offset:4096
	ds_read_b128 v[102:105], v8 offset:8192
	ds_read_b128 v[106:109], v8 offset:12288
	ds_read_b128 v[110:113], v8 offset:16384
	ds_read_b128 v[114:117], v8 offset:20480
	ds_read_b128 v[118:121], v8 offset:24576
	ds_read_b128 v[122:125], v8 offset:28672
	ds_read_b128 v[126:129], v8
	ds_read_b128 v[134:137], v8 offset:32768
	s_waitcnt lgkmcnt(0)
	v_mov_b32_e32 v143, v98
	v_mov_b32_e32 v144, v102
	v_mov_b32_e32 v145, v106
	v_mov_b32_e32 v142, v126
	v_mov_b32_e32 v146, v110
	v_mov_b32_e32 v147, v114
	v_mov_b32_e32 v148, v118
	v_mov_b32_e32 v149, v122
	v_mov_b32_e32 v98, v127
	v_mov_b32_e32 v106, v103
	v_mov_b32_e32 v114, v111
	v_mov_b32_e32 v122, v119
	v_mov_b32_e32 v102, v128
	v_mov_b32_e32 v103, v100
	v_mov_b32_e32 v110, v104
	v_mov_b32_e32 v111, v108
	v_mov_b32_e32 v118, v112
	v_mov_b32_e32 v119, v116
	v_mov_b32_e32 v126, v120
	v_mov_b32_e32 v127, v124
	v_mov_b32_e32 v100, v129
	v_mov_b32_e32 v108, v105
	v_mov_b32_e32 v116, v113
	v_mov_b32_e32 v124, v121
	v_add_u32_e32 v8, 16, v8
	s_waitcnt vmcnt(56)
	v_mov_b32_e32 v66, v178
	v_mov_b32_e32 v130, v179
	v_mov_b32_e32 v138, v180
	v_mov_b32_e32 v140, v181
	global_load_dword v178, v[210:211], off
	v_add_co_u32_e32 v210, vcc, 0x6000, v210
	v_addc_co_u32_e32 v211, vcc, 0, v211, vcc
	global_load_dword v179, v[210:211], off
	v_add_co_u32_e32 v210, vcc, 0x6000, v210
	v_addc_co_u32_e32 v211, vcc, 0, v211, vcc
	global_load_dword v180, v[210:211], off
	v_add_co_u32_e32 v210, vcc, 0x6000, v210
	v_addc_co_u32_e32 v211, vcc, 0, v211, vcc
	global_load_dword v181, v[210:211], off
	v_add_co_u32_e32 v210, vcc, 0x6000, v210
	v_addc_co_u32_e32 v211, vcc, 0, v211, vcc
	v_pk_fma_f32 v[4:5], v[66:67], v[142:143], v[4:5] op_sel_hi:[0,1,1]
	v_pk_fma_f32 v[68:69], v[66:67], v[144:145], v[68:69] op_sel_hi:[0,1,1]
	v_pk_fma_f32 v[70:71], v[66:67], v[146:147], v[70:71] op_sel_hi:[0,1,1]
	v_pk_fma_f32 v[72:73], v[66:67], v[148:149], v[72:73] op_sel_hi:[0,1,1]
	v_fmac_f32_e32 v23, v66, v134
	v_pk_fma_f32 v[4:5], v[130:131], v[98:99], v[4:5] op_sel_hi:[0,1,1]
	v_pk_fma_f32 v[68:69], v[130:131], v[106:107], v[68:69] op_sel_hi:[0,1,1]
	v_pk_fma_f32 v[70:71], v[130:131], v[114:115], v[70:71] op_sel_hi:[0,1,1]
	v_pk_fma_f32 v[72:73], v[130:131], v[122:123], v[72:73] op_sel_hi:[0,1,1]
	v_fmac_f32_e32 v23, v130, v135
	v_pk_fma_f32 v[4:5], v[138:139], v[102:103], v[4:5] op_sel_hi:[0,1,1]
	v_pk_fma_f32 v[68:69], v[138:139], v[110:111], v[68:69] op_sel_hi:[0,1,1]
	v_pk_fma_f32 v[70:71], v[138:139], v[118:119], v[70:71] op_sel_hi:[0,1,1]
	v_pk_fma_f32 v[72:73], v[138:139], v[126:127], v[72:73] op_sel_hi:[0,1,1]
	v_fmac_f32_e32 v23, v138, v136
	v_pk_fma_f32 v[4:5], v[140:141], v[100:101], v[4:5] op_sel_hi:[0,1,1]
	v_pk_fma_f32 v[68:69], v[140:141], v[108:109], v[68:69] op_sel_hi:[0,1,1]
	v_pk_fma_f32 v[70:71], v[140:141], v[116:117], v[70:71] op_sel_hi:[0,1,1]
	v_pk_fma_f32 v[72:73], v[140:141], v[124:125], v[72:73] op_sel_hi:[0,1,1]
	v_fmac_f32_e32 v23, v140, v137
	ds_read_b128 v[98:101], v8 offset:4096
	ds_read_b128 v[102:105], v8 offset:8192
	ds_read_b128 v[106:109], v8 offset:12288
	ds_read_b128 v[110:113], v8 offset:16384
	ds_read_b128 v[114:117], v8 offset:20480
	ds_read_b128 v[118:121], v8 offset:24576
	ds_read_b128 v[122:125], v8 offset:28672
	ds_read_b128 v[126:129], v8
	ds_read_b128 v[134:137], v8 offset:32768
	s_waitcnt lgkmcnt(0)
	v_mov_b32_e32 v143, v98
	v_mov_b32_e32 v144, v102
	v_mov_b32_e32 v145, v106
	v_mov_b32_e32 v142, v126
	v_mov_b32_e32 v146, v110
	v_mov_b32_e32 v147, v114
	v_mov_b32_e32 v148, v118
	v_mov_b32_e32 v149, v122
	v_mov_b32_e32 v98, v127
	v_mov_b32_e32 v106, v103
	v_mov_b32_e32 v114, v111
	v_mov_b32_e32 v122, v119
	v_mov_b32_e32 v102, v128
	v_mov_b32_e32 v103, v100
	v_mov_b32_e32 v110, v104
	v_mov_b32_e32 v111, v108
	v_mov_b32_e32 v118, v112
	v_mov_b32_e32 v119, v116
	v_mov_b32_e32 v126, v120
	v_mov_b32_e32 v127, v124
	v_mov_b32_e32 v100, v129
	v_mov_b32_e32 v108, v105
	v_mov_b32_e32 v116, v113
	v_mov_b32_e32 v124, v121
	v_add_u32_e32 v8, 16, v8
	s_waitcnt vmcnt(56)
	v_mov_b32_e32 v66, v182
	v_mov_b32_e32 v130, v183
	v_mov_b32_e32 v138, v184
	v_mov_b32_e32 v140, v185
	global_load_dword v182, v[210:211], off
	v_add_co_u32_e32 v210, vcc, 0x6000, v210
	v_addc_co_u32_e32 v211, vcc, 0, v211, vcc
	global_load_dword v183, v[210:211], off
	v_add_co_u32_e32 v210, vcc, 0x6000, v210
	v_addc_co_u32_e32 v211, vcc, 0, v211, vcc
	global_load_dword v184, v[210:211], off
	v_add_co_u32_e32 v210, vcc, 0x6000, v210
	v_addc_co_u32_e32 v211, vcc, 0, v211, vcc
	global_load_dword v185, v[210:211], off
	v_add_co_u32_e32 v210, vcc, 0x6000, v210
	v_addc_co_u32_e32 v211, vcc, 0, v211, vcc
	v_pk_fma_f32 v[4:5], v[66:67], v[142:143], v[4:5] op_sel_hi:[0,1,1]
	v_pk_fma_f32 v[68:69], v[66:67], v[144:145], v[68:69] op_sel_hi:[0,1,1]
	v_pk_fma_f32 v[70:71], v[66:67], v[146:147], v[70:71] op_sel_hi:[0,1,1]
	v_pk_fma_f32 v[72:73], v[66:67], v[148:149], v[72:73] op_sel_hi:[0,1,1]
	v_fmac_f32_e32 v23, v66, v134
	v_pk_fma_f32 v[4:5], v[130:131], v[98:99], v[4:5] op_sel_hi:[0,1,1]
	v_pk_fma_f32 v[68:69], v[130:131], v[106:107], v[68:69] op_sel_hi:[0,1,1]
	v_pk_fma_f32 v[70:71], v[130:131], v[114:115], v[70:71] op_sel_hi:[0,1,1]
	v_pk_fma_f32 v[72:73], v[130:131], v[122:123], v[72:73] op_sel_hi:[0,1,1]
	v_fmac_f32_e32 v23, v130, v135
	v_pk_fma_f32 v[4:5], v[138:139], v[102:103], v[4:5] op_sel_hi:[0,1,1]
	v_pk_fma_f32 v[68:69], v[138:139], v[110:111], v[68:69] op_sel_hi:[0,1,1]
	v_pk_fma_f32 v[70:71], v[138:139], v[118:119], v[70:71] op_sel_hi:[0,1,1]
	v_pk_fma_f32 v[72:73], v[138:139], v[126:127], v[72:73] op_sel_hi:[0,1,1]
	v_fmac_f32_e32 v23, v138, v136
	v_pk_fma_f32 v[4:5], v[140:141], v[100:101], v[4:5] op_sel_hi:[0,1,1]
	v_pk_fma_f32 v[68:69], v[140:141], v[108:109], v[68:69] op_sel_hi:[0,1,1]
	v_pk_fma_f32 v[70:71], v[140:141], v[116:117], v[70:71] op_sel_hi:[0,1,1]
	v_pk_fma_f32 v[72:73], v[140:141], v[124:125], v[72:73] op_sel_hi:[0,1,1]
	v_fmac_f32_e32 v23, v140, v137
	ds_read_b128 v[98:101], v8 offset:4096
	ds_read_b128 v[102:105], v8 offset:8192
	ds_read_b128 v[106:109], v8 offset:12288
	ds_read_b128 v[110:113], v8 offset:16384
	ds_read_b128 v[114:117], v8 offset:20480
	ds_read_b128 v[118:121], v8 offset:24576
	ds_read_b128 v[122:125], v8 offset:28672
	ds_read_b128 v[126:129], v8
	ds_read_b128 v[134:137], v8 offset:32768
	s_waitcnt lgkmcnt(0)
	v_mov_b32_e32 v143, v98
	v_mov_b32_e32 v144, v102
	v_mov_b32_e32 v145, v106
	v_mov_b32_e32 v142, v126
	v_mov_b32_e32 v146, v110
	v_mov_b32_e32 v147, v114
	v_mov_b32_e32 v148, v118
	v_mov_b32_e32 v149, v122
	v_mov_b32_e32 v98, v127
	v_mov_b32_e32 v106, v103
	v_mov_b32_e32 v114, v111
	v_mov_b32_e32 v122, v119
	v_mov_b32_e32 v102, v128
	v_mov_b32_e32 v103, v100
	v_mov_b32_e32 v110, v104
	v_mov_b32_e32 v111, v108
	v_mov_b32_e32 v118, v112
	v_mov_b32_e32 v119, v116
	v_mov_b32_e32 v126, v120
	v_mov_b32_e32 v127, v124
	v_mov_b32_e32 v100, v129
	v_mov_b32_e32 v108, v105
	v_mov_b32_e32 v116, v113
	v_mov_b32_e32 v124, v121
	v_add_u32_e32 v8, 16, v8
	s_waitcnt vmcnt(56)
	v_mov_b32_e32 v66, v186
	v_mov_b32_e32 v130, v187
	v_mov_b32_e32 v138, v188
	v_mov_b32_e32 v140, v189
	global_load_dword v186, v[210:211], off
	v_add_co_u32_e32 v210, vcc, 0x6000, v210
	v_addc_co_u32_e32 v211, vcc, 0, v211, vcc
	global_load_dword v187, v[210:211], off
	v_add_co_u32_e32 v210, vcc, 0x6000, v210
	v_addc_co_u32_e32 v211, vcc, 0, v211, vcc
	global_load_dword v188, v[210:211], off
	v_add_co_u32_e32 v210, vcc, 0x6000, v210
	v_addc_co_u32_e32 v211, vcc, 0, v211, vcc
	global_load_dword v189, v[210:211], off
	v_add_co_u32_e32 v210, vcc, 0x6000, v210
	v_addc_co_u32_e32 v211, vcc, 0, v211, vcc
	v_pk_fma_f32 v[4:5], v[66:67], v[142:143], v[4:5] op_sel_hi:[0,1,1]
	v_pk_fma_f32 v[68:69], v[66:67], v[144:145], v[68:69] op_sel_hi:[0,1,1]
	v_pk_fma_f32 v[70:71], v[66:67], v[146:147], v[70:71] op_sel_hi:[0,1,1]
	v_pk_fma_f32 v[72:73], v[66:67], v[148:149], v[72:73] op_sel_hi:[0,1,1]
	v_fmac_f32_e32 v23, v66, v134
	v_pk_fma_f32 v[4:5], v[130:131], v[98:99], v[4:5] op_sel_hi:[0,1,1]
	v_pk_fma_f32 v[68:69], v[130:131], v[106:107], v[68:69] op_sel_hi:[0,1,1]
	v_pk_fma_f32 v[70:71], v[130:131], v[114:115], v[70:71] op_sel_hi:[0,1,1]
	v_pk_fma_f32 v[72:73], v[130:131], v[122:123], v[72:73] op_sel_hi:[0,1,1]
	v_fmac_f32_e32 v23, v130, v135
	v_pk_fma_f32 v[4:5], v[138:139], v[102:103], v[4:5] op_sel_hi:[0,1,1]
	v_pk_fma_f32 v[68:69], v[138:139], v[110:111], v[68:69] op_sel_hi:[0,1,1]
	v_pk_fma_f32 v[70:71], v[138:139], v[118:119], v[70:71] op_sel_hi:[0,1,1]
	v_pk_fma_f32 v[72:73], v[138:139], v[126:127], v[72:73] op_sel_hi:[0,1,1]
	v_fmac_f32_e32 v23, v138, v136
	v_pk_fma_f32 v[4:5], v[140:141], v[100:101], v[4:5] op_sel_hi:[0,1,1]
	v_pk_fma_f32 v[68:69], v[140:141], v[108:109], v[68:69] op_sel_hi:[0,1,1]
	v_pk_fma_f32 v[70:71], v[140:141], v[116:117], v[70:71] op_sel_hi:[0,1,1]
	v_pk_fma_f32 v[72:73], v[140:141], v[124:125], v[72:73] op_sel_hi:[0,1,1]
	v_fmac_f32_e32 v23, v140, v137
	ds_read_b128 v[98:101], v8 offset:4096
	ds_read_b128 v[102:105], v8 offset:8192
	ds_read_b128 v[106:109], v8 offset:12288
	ds_read_b128 v[110:113], v8 offset:16384
	ds_read_b128 v[114:117], v8 offset:20480
	ds_read_b128 v[118:121], v8 offset:24576
	ds_read_b128 v[122:125], v8 offset:28672
	ds_read_b128 v[126:129], v8
	ds_read_b128 v[134:137], v8 offset:32768
	s_waitcnt lgkmcnt(0)
	v_mov_b32_e32 v143, v98
	v_mov_b32_e32 v144, v102
	v_mov_b32_e32 v145, v106
	v_mov_b32_e32 v142, v126
	v_mov_b32_e32 v146, v110
	v_mov_b32_e32 v147, v114
	v_mov_b32_e32 v148, v118
	v_mov_b32_e32 v149, v122
	v_mov_b32_e32 v98, v127
	v_mov_b32_e32 v106, v103
	v_mov_b32_e32 v114, v111
	v_mov_b32_e32 v122, v119
	v_mov_b32_e32 v102, v128
	v_mov_b32_e32 v103, v100
	v_mov_b32_e32 v110, v104
	v_mov_b32_e32 v111, v108
	v_mov_b32_e32 v118, v112
	v_mov_b32_e32 v119, v116
	v_mov_b32_e32 v126, v120
	v_mov_b32_e32 v127, v124
	v_mov_b32_e32 v100, v129
	v_mov_b32_e32 v108, v105
	v_mov_b32_e32 v116, v113
	v_mov_b32_e32 v124, v121
	v_add_u32_e32 v8, 16, v8
	s_waitcnt vmcnt(56)
	v_mov_b32_e32 v66, v190
	v_mov_b32_e32 v130, v191
	v_mov_b32_e32 v138, v192
	v_mov_b32_e32 v140, v193
	global_load_dword v190, v[210:211], off
	v_add_co_u32_e32 v210, vcc, 0x6000, v210
	v_addc_co_u32_e32 v211, vcc, 0, v211, vcc
	global_load_dword v191, v[210:211], off
	v_add_co_u32_e32 v210, vcc, 0x6000, v210
	v_addc_co_u32_e32 v211, vcc, 0, v211, vcc
	global_load_dword v192, v[210:211], off
	v_add_co_u32_e32 v210, vcc, 0x6000, v210
	v_addc_co_u32_e32 v211, vcc, 0, v211, vcc
	global_load_dword v193, v[210:211], off
	v_add_co_u32_e32 v210, vcc, 0x6000, v210
	v_addc_co_u32_e32 v211, vcc, 0, v211, vcc
	v_pk_fma_f32 v[4:5], v[66:67], v[142:143], v[4:5] op_sel_hi:[0,1,1]
	v_pk_fma_f32 v[68:69], v[66:67], v[144:145], v[68:69] op_sel_hi:[0,1,1]
	v_pk_fma_f32 v[70:71], v[66:67], v[146:147], v[70:71] op_sel_hi:[0,1,1]
	v_pk_fma_f32 v[72:73], v[66:67], v[148:149], v[72:73] op_sel_hi:[0,1,1]
	v_fmac_f32_e32 v23, v66, v134
	v_pk_fma_f32 v[4:5], v[130:131], v[98:99], v[4:5] op_sel_hi:[0,1,1]
	v_pk_fma_f32 v[68:69], v[130:131], v[106:107], v[68:69] op_sel_hi:[0,1,1]
	v_pk_fma_f32 v[70:71], v[130:131], v[114:115], v[70:71] op_sel_hi:[0,1,1]
	v_pk_fma_f32 v[72:73], v[130:131], v[122:123], v[72:73] op_sel_hi:[0,1,1]
	v_fmac_f32_e32 v23, v130, v135
	v_pk_fma_f32 v[4:5], v[138:139], v[102:103], v[4:5] op_sel_hi:[0,1,1]
	v_pk_fma_f32 v[68:69], v[138:139], v[110:111], v[68:69] op_sel_hi:[0,1,1]
	v_pk_fma_f32 v[70:71], v[138:139], v[118:119], v[70:71] op_sel_hi:[0,1,1]
	v_pk_fma_f32 v[72:73], v[138:139], v[126:127], v[72:73] op_sel_hi:[0,1,1]
	v_fmac_f32_e32 v23, v138, v136
	v_pk_fma_f32 v[4:5], v[140:141], v[100:101], v[4:5] op_sel_hi:[0,1,1]
	v_pk_fma_f32 v[68:69], v[140:141], v[108:109], v[68:69] op_sel_hi:[0,1,1]
	v_pk_fma_f32 v[70:71], v[140:141], v[116:117], v[70:71] op_sel_hi:[0,1,1]
	v_pk_fma_f32 v[72:73], v[140:141], v[124:125], v[72:73] op_sel_hi:[0,1,1]
	v_fmac_f32_e32 v23, v140, v137
	ds_read_b128 v[98:101], v8 offset:4096
	ds_read_b128 v[102:105], v8 offset:8192
	ds_read_b128 v[106:109], v8 offset:12288
	ds_read_b128 v[110:113], v8 offset:16384
	ds_read_b128 v[114:117], v8 offset:20480
	ds_read_b128 v[118:121], v8 offset:24576
	ds_read_b128 v[122:125], v8 offset:28672
	ds_read_b128 v[126:129], v8
	ds_read_b128 v[134:137], v8 offset:32768
	s_waitcnt lgkmcnt(0)
	v_mov_b32_e32 v143, v98
	v_mov_b32_e32 v144, v102
	v_mov_b32_e32 v145, v106
	v_mov_b32_e32 v142, v126
	v_mov_b32_e32 v146, v110
	v_mov_b32_e32 v147, v114
	v_mov_b32_e32 v148, v118
	v_mov_b32_e32 v149, v122
	v_mov_b32_e32 v98, v127
	v_mov_b32_e32 v106, v103
	v_mov_b32_e32 v114, v111
	v_mov_b32_e32 v122, v119
	v_mov_b32_e32 v102, v128
	v_mov_b32_e32 v103, v100
	v_mov_b32_e32 v110, v104
	v_mov_b32_e32 v111, v108
	v_mov_b32_e32 v118, v112
	v_mov_b32_e32 v119, v116
	v_mov_b32_e32 v126, v120
	v_mov_b32_e32 v127, v124
	v_mov_b32_e32 v100, v129
	v_mov_b32_e32 v108, v105
	v_mov_b32_e32 v116, v113
	v_mov_b32_e32 v124, v121
	v_add_u32_e32 v8, 16, v8
	s_waitcnt vmcnt(56)
	v_mov_b32_e32 v66, v194
	v_mov_b32_e32 v130, v195
	v_mov_b32_e32 v138, v196
	v_mov_b32_e32 v140, v197
	global_load_dword v194, v[210:211], off
	v_add_co_u32_e32 v210, vcc, 0x6000, v210
	v_addc_co_u32_e32 v211, vcc, 0, v211, vcc
	global_load_dword v195, v[210:211], off
	v_add_co_u32_e32 v210, vcc, 0x6000, v210
	v_addc_co_u32_e32 v211, vcc, 0, v211, vcc
	global_load_dword v196, v[210:211], off
	v_add_co_u32_e32 v210, vcc, 0x6000, v210
	v_addc_co_u32_e32 v211, vcc, 0, v211, vcc
	global_load_dword v197, v[210:211], off
	v_add_co_u32_e32 v210, vcc, 0x6000, v210
	v_addc_co_u32_e32 v211, vcc, 0, v211, vcc
	v_pk_fma_f32 v[4:5], v[66:67], v[142:143], v[4:5] op_sel_hi:[0,1,1]
	v_pk_fma_f32 v[68:69], v[66:67], v[144:145], v[68:69] op_sel_hi:[0,1,1]
	v_pk_fma_f32 v[70:71], v[66:67], v[146:147], v[70:71] op_sel_hi:[0,1,1]
	v_pk_fma_f32 v[72:73], v[66:67], v[148:149], v[72:73] op_sel_hi:[0,1,1]
	v_fmac_f32_e32 v23, v66, v134
	v_pk_fma_f32 v[4:5], v[130:131], v[98:99], v[4:5] op_sel_hi:[0,1,1]
	v_pk_fma_f32 v[68:69], v[130:131], v[106:107], v[68:69] op_sel_hi:[0,1,1]
	v_pk_fma_f32 v[70:71], v[130:131], v[114:115], v[70:71] op_sel_hi:[0,1,1]
	v_pk_fma_f32 v[72:73], v[130:131], v[122:123], v[72:73] op_sel_hi:[0,1,1]
	v_fmac_f32_e32 v23, v130, v135
	v_pk_fma_f32 v[4:5], v[138:139], v[102:103], v[4:5] op_sel_hi:[0,1,1]
	v_pk_fma_f32 v[68:69], v[138:139], v[110:111], v[68:69] op_sel_hi:[0,1,1]
	v_pk_fma_f32 v[70:71], v[138:139], v[118:119], v[70:71] op_sel_hi:[0,1,1]
	v_pk_fma_f32 v[72:73], v[138:139], v[126:127], v[72:73] op_sel_hi:[0,1,1]
	v_fmac_f32_e32 v23, v138, v136
	v_pk_fma_f32 v[4:5], v[140:141], v[100:101], v[4:5] op_sel_hi:[0,1,1]
	v_pk_fma_f32 v[68:69], v[140:141], v[108:109], v[68:69] op_sel_hi:[0,1,1]
	v_pk_fma_f32 v[70:71], v[140:141], v[116:117], v[70:71] op_sel_hi:[0,1,1]
	v_pk_fma_f32 v[72:73], v[140:141], v[124:125], v[72:73] op_sel_hi:[0,1,1]
	v_fmac_f32_e32 v23, v140, v137
	ds_read_b128 v[98:101], v8 offset:4096
	ds_read_b128 v[102:105], v8 offset:8192
	ds_read_b128 v[106:109], v8 offset:12288
	ds_read_b128 v[110:113], v8 offset:16384
	ds_read_b128 v[114:117], v8 offset:20480
	ds_read_b128 v[118:121], v8 offset:24576
	ds_read_b128 v[122:125], v8 offset:28672
	ds_read_b128 v[126:129], v8
	ds_read_b128 v[134:137], v8 offset:32768
	s_waitcnt lgkmcnt(0)
	v_mov_b32_e32 v143, v98
	v_mov_b32_e32 v144, v102
	v_mov_b32_e32 v145, v106
	v_mov_b32_e32 v142, v126
	v_mov_b32_e32 v146, v110
	v_mov_b32_e32 v147, v114
	v_mov_b32_e32 v148, v118
	v_mov_b32_e32 v149, v122
	v_mov_b32_e32 v98, v127
	v_mov_b32_e32 v106, v103
	v_mov_b32_e32 v114, v111
	v_mov_b32_e32 v122, v119
	v_mov_b32_e32 v102, v128
	v_mov_b32_e32 v103, v100
	v_mov_b32_e32 v110, v104
	v_mov_b32_e32 v111, v108
	v_mov_b32_e32 v118, v112
	v_mov_b32_e32 v119, v116
	v_mov_b32_e32 v126, v120
	v_mov_b32_e32 v127, v124
	v_mov_b32_e32 v100, v129
	v_mov_b32_e32 v108, v105
	v_mov_b32_e32 v116, v113
	v_mov_b32_e32 v124, v121
	v_add_u32_e32 v8, 16, v8
	s_waitcnt vmcnt(56)
	v_mov_b32_e32 v66, v198
	v_mov_b32_e32 v130, v199
	v_mov_b32_e32 v138, v200
	v_mov_b32_e32 v140, v201
	global_load_dword v198, v[210:211], off
	v_add_co_u32_e32 v210, vcc, 0x6000, v210
	v_addc_co_u32_e32 v211, vcc, 0, v211, vcc
	global_load_dword v199, v[210:211], off
	v_add_co_u32_e32 v210, vcc, 0x6000, v210
	v_addc_co_u32_e32 v211, vcc, 0, v211, vcc
	global_load_dword v200, v[210:211], off
	v_add_co_u32_e32 v210, vcc, 0x6000, v210
	v_addc_co_u32_e32 v211, vcc, 0, v211, vcc
	global_load_dword v201, v[210:211], off
	v_add_co_u32_e32 v210, vcc, 0x6000, v210
	v_addc_co_u32_e32 v211, vcc, 0, v211, vcc
	v_pk_fma_f32 v[4:5], v[66:67], v[142:143], v[4:5] op_sel_hi:[0,1,1]
	v_pk_fma_f32 v[68:69], v[66:67], v[144:145], v[68:69] op_sel_hi:[0,1,1]
	v_pk_fma_f32 v[70:71], v[66:67], v[146:147], v[70:71] op_sel_hi:[0,1,1]
	v_pk_fma_f32 v[72:73], v[66:67], v[148:149], v[72:73] op_sel_hi:[0,1,1]
	v_fmac_f32_e32 v23, v66, v134
	v_pk_fma_f32 v[4:5], v[130:131], v[98:99], v[4:5] op_sel_hi:[0,1,1]
	v_pk_fma_f32 v[68:69], v[130:131], v[106:107], v[68:69] op_sel_hi:[0,1,1]
	v_pk_fma_f32 v[70:71], v[130:131], v[114:115], v[70:71] op_sel_hi:[0,1,1]
	v_pk_fma_f32 v[72:73], v[130:131], v[122:123], v[72:73] op_sel_hi:[0,1,1]
	v_fmac_f32_e32 v23, v130, v135
	v_pk_fma_f32 v[4:5], v[138:139], v[102:103], v[4:5] op_sel_hi:[0,1,1]
	v_pk_fma_f32 v[68:69], v[138:139], v[110:111], v[68:69] op_sel_hi:[0,1,1]
	v_pk_fma_f32 v[70:71], v[138:139], v[118:119], v[70:71] op_sel_hi:[0,1,1]
	v_pk_fma_f32 v[72:73], v[138:139], v[126:127], v[72:73] op_sel_hi:[0,1,1]
	v_fmac_f32_e32 v23, v138, v136
	v_pk_fma_f32 v[4:5], v[140:141], v[100:101], v[4:5] op_sel_hi:[0,1,1]
	v_pk_fma_f32 v[68:69], v[140:141], v[108:109], v[68:69] op_sel_hi:[0,1,1]
	v_pk_fma_f32 v[70:71], v[140:141], v[116:117], v[70:71] op_sel_hi:[0,1,1]
	v_pk_fma_f32 v[72:73], v[140:141], v[124:125], v[72:73] op_sel_hi:[0,1,1]
	v_fmac_f32_e32 v23, v140, v137
	ds_read_b128 v[98:101], v8 offset:4096
	ds_read_b128 v[102:105], v8 offset:8192
	ds_read_b128 v[106:109], v8 offset:12288
	ds_read_b128 v[110:113], v8 offset:16384
	ds_read_b128 v[114:117], v8 offset:20480
	ds_read_b128 v[118:121], v8 offset:24576
	ds_read_b128 v[122:125], v8 offset:28672
	ds_read_b128 v[126:129], v8
	ds_read_b128 v[134:137], v8 offset:32768
	s_waitcnt lgkmcnt(0)
	v_mov_b32_e32 v143, v98
	v_mov_b32_e32 v144, v102
	v_mov_b32_e32 v145, v106
	v_mov_b32_e32 v142, v126
	v_mov_b32_e32 v146, v110
	v_mov_b32_e32 v147, v114
	v_mov_b32_e32 v148, v118
	v_mov_b32_e32 v149, v122
	v_mov_b32_e32 v98, v127
	v_mov_b32_e32 v106, v103
	v_mov_b32_e32 v114, v111
	v_mov_b32_e32 v122, v119
	v_mov_b32_e32 v102, v128
	v_mov_b32_e32 v103, v100
	v_mov_b32_e32 v110, v104
	v_mov_b32_e32 v111, v108
	v_mov_b32_e32 v118, v112
	v_mov_b32_e32 v119, v116
	v_mov_b32_e32 v126, v120
	v_mov_b32_e32 v127, v124
	v_mov_b32_e32 v100, v129
	v_mov_b32_e32 v108, v105
	v_mov_b32_e32 v116, v113
	v_mov_b32_e32 v124, v121
	v_add_u32_e32 v8, 16, v8
	s_waitcnt vmcnt(56)
	v_mov_b32_e32 v66, v202
	v_mov_b32_e32 v130, v203
	v_mov_b32_e32 v138, v204
	v_mov_b32_e32 v140, v205
	global_load_dword v202, v[210:211], off
	v_add_co_u32_e32 v210, vcc, 0x6000, v210
	v_addc_co_u32_e32 v211, vcc, 0, v211, vcc
	global_load_dword v203, v[210:211], off
	v_add_co_u32_e32 v210, vcc, 0x6000, v210
	v_addc_co_u32_e32 v211, vcc, 0, v211, vcc
	global_load_dword v204, v[210:211], off
	v_add_co_u32_e32 v210, vcc, 0x6000, v210
	v_addc_co_u32_e32 v211, vcc, 0, v211, vcc
	global_load_dword v205, v[210:211], off
	v_add_co_u32_e32 v210, vcc, 0x6000, v210
	v_addc_co_u32_e32 v211, vcc, 0, v211, vcc
	v_pk_fma_f32 v[4:5], v[66:67], v[142:143], v[4:5] op_sel_hi:[0,1,1]
	v_pk_fma_f32 v[68:69], v[66:67], v[144:145], v[68:69] op_sel_hi:[0,1,1]
	v_pk_fma_f32 v[70:71], v[66:67], v[146:147], v[70:71] op_sel_hi:[0,1,1]
	v_pk_fma_f32 v[72:73], v[66:67], v[148:149], v[72:73] op_sel_hi:[0,1,1]
	v_fmac_f32_e32 v23, v66, v134
	v_pk_fma_f32 v[4:5], v[130:131], v[98:99], v[4:5] op_sel_hi:[0,1,1]
	v_pk_fma_f32 v[68:69], v[130:131], v[106:107], v[68:69] op_sel_hi:[0,1,1]
	v_pk_fma_f32 v[70:71], v[130:131], v[114:115], v[70:71] op_sel_hi:[0,1,1]
	v_pk_fma_f32 v[72:73], v[130:131], v[122:123], v[72:73] op_sel_hi:[0,1,1]
	v_fmac_f32_e32 v23, v130, v135
	v_pk_fma_f32 v[4:5], v[138:139], v[102:103], v[4:5] op_sel_hi:[0,1,1]
	v_pk_fma_f32 v[68:69], v[138:139], v[110:111], v[68:69] op_sel_hi:[0,1,1]
	v_pk_fma_f32 v[70:71], v[138:139], v[118:119], v[70:71] op_sel_hi:[0,1,1]
	v_pk_fma_f32 v[72:73], v[138:139], v[126:127], v[72:73] op_sel_hi:[0,1,1]
	v_fmac_f32_e32 v23, v138, v136
	v_pk_fma_f32 v[4:5], v[140:141], v[100:101], v[4:5] op_sel_hi:[0,1,1]
	v_pk_fma_f32 v[68:69], v[140:141], v[108:109], v[68:69] op_sel_hi:[0,1,1]
	v_pk_fma_f32 v[70:71], v[140:141], v[116:117], v[70:71] op_sel_hi:[0,1,1]
	v_pk_fma_f32 v[72:73], v[140:141], v[124:125], v[72:73] op_sel_hi:[0,1,1]
	v_fmac_f32_e32 v23, v140, v137
	ds_read_b128 v[98:101], v8 offset:4096
	ds_read_b128 v[102:105], v8 offset:8192
	ds_read_b128 v[106:109], v8 offset:12288
	ds_read_b128 v[110:113], v8 offset:16384
	ds_read_b128 v[114:117], v8 offset:20480
	ds_read_b128 v[118:121], v8 offset:24576
	ds_read_b128 v[122:125], v8 offset:28672
	ds_read_b128 v[126:129], v8
	ds_read_b128 v[134:137], v8 offset:32768
	s_waitcnt lgkmcnt(0)
	v_mov_b32_e32 v143, v98
	v_mov_b32_e32 v144, v102
	v_mov_b32_e32 v145, v106
	v_mov_b32_e32 v142, v126
	v_mov_b32_e32 v146, v110
	v_mov_b32_e32 v147, v114
	v_mov_b32_e32 v148, v118
	v_mov_b32_e32 v149, v122
	v_mov_b32_e32 v98, v127
	v_mov_b32_e32 v106, v103
	v_mov_b32_e32 v114, v111
	v_mov_b32_e32 v122, v119
	v_mov_b32_e32 v102, v128
	v_mov_b32_e32 v103, v100
	v_mov_b32_e32 v110, v104
	v_mov_b32_e32 v111, v108
	v_mov_b32_e32 v118, v112
	v_mov_b32_e32 v119, v116
	v_mov_b32_e32 v126, v120
	v_mov_b32_e32 v127, v124
	v_mov_b32_e32 v100, v129
	v_mov_b32_e32 v108, v105
	v_mov_b32_e32 v116, v113
	v_mov_b32_e32 v124, v121
	v_add_u32_e32 v8, 16, v8
	s_waitcnt vmcnt(56)
	v_mov_b32_e32 v66, v206
	v_mov_b32_e32 v130, v207
	v_mov_b32_e32 v138, v208
	v_mov_b32_e32 v140, v209
	global_load_dword v206, v[210:211], off
	v_add_co_u32_e32 v210, vcc, 0x6000, v210
	v_addc_co_u32_e32 v211, vcc, 0, v211, vcc
	global_load_dword v207, v[210:211], off
	v_add_co_u32_e32 v210, vcc, 0x6000, v210
	v_addc_co_u32_e32 v211, vcc, 0, v211, vcc
	global_load_dword v208, v[210:211], off
	v_add_co_u32_e32 v210, vcc, 0x6000, v210
	v_addc_co_u32_e32 v211, vcc, 0, v211, vcc
	global_load_dword v209, v[210:211], off
	v_add_co_u32_e32 v210, vcc, 0x6000, v210
	v_addc_co_u32_e32 v211, vcc, 0, v211, vcc
	v_pk_fma_f32 v[4:5], v[66:67], v[142:143], v[4:5] op_sel_hi:[0,1,1]
	v_pk_fma_f32 v[68:69], v[66:67], v[144:145], v[68:69] op_sel_hi:[0,1,1]
	v_pk_fma_f32 v[70:71], v[66:67], v[146:147], v[70:71] op_sel_hi:[0,1,1]
	v_pk_fma_f32 v[72:73], v[66:67], v[148:149], v[72:73] op_sel_hi:[0,1,1]
	v_fmac_f32_e32 v23, v66, v134
	v_pk_fma_f32 v[4:5], v[130:131], v[98:99], v[4:5] op_sel_hi:[0,1,1]
	v_pk_fma_f32 v[68:69], v[130:131], v[106:107], v[68:69] op_sel_hi:[0,1,1]
	v_pk_fma_f32 v[70:71], v[130:131], v[114:115], v[70:71] op_sel_hi:[0,1,1]
	v_pk_fma_f32 v[72:73], v[130:131], v[122:123], v[72:73] op_sel_hi:[0,1,1]
	v_fmac_f32_e32 v23, v130, v135
	v_pk_fma_f32 v[4:5], v[138:139], v[102:103], v[4:5] op_sel_hi:[0,1,1]
	v_pk_fma_f32 v[68:69], v[138:139], v[110:111], v[68:69] op_sel_hi:[0,1,1]
	v_pk_fma_f32 v[70:71], v[138:139], v[118:119], v[70:71] op_sel_hi:[0,1,1]
	v_pk_fma_f32 v[72:73], v[138:139], v[126:127], v[72:73] op_sel_hi:[0,1,1]
	v_fmac_f32_e32 v23, v138, v136
	v_pk_fma_f32 v[4:5], v[140:141], v[100:101], v[4:5] op_sel_hi:[0,1,1]
	v_pk_fma_f32 v[68:69], v[140:141], v[108:109], v[68:69] op_sel_hi:[0,1,1]
	v_pk_fma_f32 v[70:71], v[140:141], v[116:117], v[70:71] op_sel_hi:[0,1,1]
	v_pk_fma_f32 v[72:73], v[140:141], v[124:125], v[72:73] op_sel_hi:[0,1,1]
	v_fmac_f32_e32 v23, v140, v137
	ds_read_b128 v[98:101], v8 offset:4096
	ds_read_b128 v[102:105], v8 offset:8192
	ds_read_b128 v[106:109], v8 offset:12288
	ds_read_b128 v[110:113], v8 offset:16384
	ds_read_b128 v[114:117], v8 offset:20480
	ds_read_b128 v[118:121], v8 offset:24576
	ds_read_b128 v[122:125], v8 offset:28672
	ds_read_b128 v[126:129], v8
	ds_read_b128 v[134:137], v8 offset:32768
	s_waitcnt lgkmcnt(0)
	v_mov_b32_e32 v143, v98
	v_mov_b32_e32 v144, v102
	v_mov_b32_e32 v145, v106
	v_mov_b32_e32 v142, v126
	v_mov_b32_e32 v146, v110
	v_mov_b32_e32 v147, v114
	v_mov_b32_e32 v148, v118
	v_mov_b32_e32 v149, v122
	v_mov_b32_e32 v98, v127
	v_mov_b32_e32 v106, v103
	v_mov_b32_e32 v114, v111
	v_mov_b32_e32 v122, v119
	v_mov_b32_e32 v102, v128
	v_mov_b32_e32 v103, v100
	v_mov_b32_e32 v110, v104
	v_mov_b32_e32 v111, v108
	v_mov_b32_e32 v118, v112
	v_mov_b32_e32 v119, v116
	v_mov_b32_e32 v126, v120
	v_mov_b32_e32 v127, v124
	v_mov_b32_e32 v100, v129
	v_mov_b32_e32 v108, v105
	v_mov_b32_e32 v116, v113
	v_mov_b32_e32 v124, v121
	v_add_u32_e32 v8, 16, v8
	s_waitcnt vmcnt(56)
	v_mov_b32_e32 v66, v150
	v_mov_b32_e32 v130, v151
	v_mov_b32_e32 v138, v152
	v_mov_b32_e32 v140, v153
	global_load_dword v150, v[210:211], off
	v_add_co_u32_e32 v210, vcc, 0x6000, v210
	v_addc_co_u32_e32 v211, vcc, 0, v211, vcc
	global_load_dword v151, v[210:211], off
	v_add_co_u32_e32 v210, vcc, 0x6000, v210
	v_addc_co_u32_e32 v211, vcc, 0, v211, vcc
	global_load_dword v152, v[210:211], off
	v_add_co_u32_e32 v210, vcc, 0x6000, v210
	v_addc_co_u32_e32 v211, vcc, 0, v211, vcc
	global_load_dword v153, v[210:211], off
	v_add_co_u32_e32 v210, vcc, 0x6000, v210
	v_addc_co_u32_e32 v211, vcc, 0, v211, vcc
	v_pk_fma_f32 v[4:5], v[66:67], v[142:143], v[4:5] op_sel_hi:[0,1,1]
	v_pk_fma_f32 v[68:69], v[66:67], v[144:145], v[68:69] op_sel_hi:[0,1,1]
	v_pk_fma_f32 v[70:71], v[66:67], v[146:147], v[70:71] op_sel_hi:[0,1,1]
	v_pk_fma_f32 v[72:73], v[66:67], v[148:149], v[72:73] op_sel_hi:[0,1,1]
	v_fmac_f32_e32 v23, v66, v134
	v_pk_fma_f32 v[4:5], v[130:131], v[98:99], v[4:5] op_sel_hi:[0,1,1]
	v_pk_fma_f32 v[68:69], v[130:131], v[106:107], v[68:69] op_sel_hi:[0,1,1]
	v_pk_fma_f32 v[70:71], v[130:131], v[114:115], v[70:71] op_sel_hi:[0,1,1]
	v_pk_fma_f32 v[72:73], v[130:131], v[122:123], v[72:73] op_sel_hi:[0,1,1]
	v_fmac_f32_e32 v23, v130, v135
	v_pk_fma_f32 v[4:5], v[138:139], v[102:103], v[4:5] op_sel_hi:[0,1,1]
	v_pk_fma_f32 v[68:69], v[138:139], v[110:111], v[68:69] op_sel_hi:[0,1,1]
	v_pk_fma_f32 v[70:71], v[138:139], v[118:119], v[70:71] op_sel_hi:[0,1,1]
	v_pk_fma_f32 v[72:73], v[138:139], v[126:127], v[72:73] op_sel_hi:[0,1,1]
	v_fmac_f32_e32 v23, v138, v136
	v_pk_fma_f32 v[4:5], v[140:141], v[100:101], v[4:5] op_sel_hi:[0,1,1]
	v_pk_fma_f32 v[68:69], v[140:141], v[108:109], v[68:69] op_sel_hi:[0,1,1]
	v_pk_fma_f32 v[70:71], v[140:141], v[116:117], v[70:71] op_sel_hi:[0,1,1]
	v_pk_fma_f32 v[72:73], v[140:141], v[124:125], v[72:73] op_sel_hi:[0,1,1]
	v_fmac_f32_e32 v23, v140, v137
	ds_read_b128 v[98:101], v8 offset:4096
	ds_read_b128 v[102:105], v8 offset:8192
	ds_read_b128 v[106:109], v8 offset:12288
	ds_read_b128 v[110:113], v8 offset:16384
	ds_read_b128 v[114:117], v8 offset:20480
	ds_read_b128 v[118:121], v8 offset:24576
	ds_read_b128 v[122:125], v8 offset:28672
	ds_read_b128 v[126:129], v8
	ds_read_b128 v[134:137], v8 offset:32768
	s_waitcnt lgkmcnt(0)
	v_mov_b32_e32 v143, v98
	v_mov_b32_e32 v144, v102
	v_mov_b32_e32 v145, v106
	v_mov_b32_e32 v142, v126
	v_mov_b32_e32 v146, v110
	v_mov_b32_e32 v147, v114
	v_mov_b32_e32 v148, v118
	v_mov_b32_e32 v149, v122
	v_mov_b32_e32 v98, v127
	v_mov_b32_e32 v106, v103
	v_mov_b32_e32 v114, v111
	v_mov_b32_e32 v122, v119
	v_mov_b32_e32 v102, v128
	v_mov_b32_e32 v103, v100
	v_mov_b32_e32 v110, v104
	v_mov_b32_e32 v111, v108
	v_mov_b32_e32 v118, v112
	v_mov_b32_e32 v119, v116
	v_mov_b32_e32 v126, v120
	v_mov_b32_e32 v127, v124
	v_mov_b32_e32 v100, v129
	v_mov_b32_e32 v108, v105
	v_mov_b32_e32 v116, v113
	v_mov_b32_e32 v124, v121
	v_add_u32_e32 v8, 16, v8
	s_waitcnt vmcnt(56)
	v_mov_b32_e32 v66, v154
	v_mov_b32_e32 v130, v155
	v_mov_b32_e32 v138, v156
	v_mov_b32_e32 v140, v157
	global_load_dword v154, v[210:211], off
	v_add_co_u32_e32 v210, vcc, 0x6000, v210
	v_addc_co_u32_e32 v211, vcc, 0, v211, vcc
	global_load_dword v155, v[210:211], off
	v_add_co_u32_e32 v210, vcc, 0x6000, v210
	v_addc_co_u32_e32 v211, vcc, 0, v211, vcc
	global_load_dword v156, v[210:211], off
	v_add_co_u32_e32 v210, vcc, 0x6000, v210
	v_addc_co_u32_e32 v211, vcc, 0, v211, vcc
	global_load_dword v157, v[210:211], off
	v_pk_fma_f32 v[4:5], v[66:67], v[142:143], v[4:5] op_sel_hi:[0,1,1]
	v_pk_fma_f32 v[68:69], v[66:67], v[144:145], v[68:69] op_sel_hi:[0,1,1]
	v_pk_fma_f32 v[70:71], v[66:67], v[146:147], v[70:71] op_sel_hi:[0,1,1]
	v_pk_fma_f32 v[72:73], v[66:67], v[148:149], v[72:73] op_sel_hi:[0,1,1]
	v_fmac_f32_e32 v23, v66, v134
	v_pk_fma_f32 v[4:5], v[130:131], v[98:99], v[4:5] op_sel_hi:[0,1,1]
	v_pk_fma_f32 v[68:69], v[130:131], v[106:107], v[68:69] op_sel_hi:[0,1,1]
	v_pk_fma_f32 v[70:71], v[130:131], v[114:115], v[70:71] op_sel_hi:[0,1,1]
	v_pk_fma_f32 v[72:73], v[130:131], v[122:123], v[72:73] op_sel_hi:[0,1,1]
	v_fmac_f32_e32 v23, v130, v135
	v_pk_fma_f32 v[4:5], v[138:139], v[102:103], v[4:5] op_sel_hi:[0,1,1]
	v_pk_fma_f32 v[68:69], v[138:139], v[110:111], v[68:69] op_sel_hi:[0,1,1]
	v_pk_fma_f32 v[70:71], v[138:139], v[118:119], v[70:71] op_sel_hi:[0,1,1]
	v_pk_fma_f32 v[72:73], v[138:139], v[126:127], v[72:73] op_sel_hi:[0,1,1]
	v_fmac_f32_e32 v23, v138, v136
	v_pk_fma_f32 v[4:5], v[140:141], v[100:101], v[4:5] op_sel_hi:[0,1,1]
	v_pk_fma_f32 v[68:69], v[140:141], v[108:109], v[68:69] op_sel_hi:[0,1,1]
	v_pk_fma_f32 v[70:71], v[140:141], v[116:117], v[70:71] op_sel_hi:[0,1,1]
	v_pk_fma_f32 v[72:73], v[140:141], v[124:125], v[72:73] op_sel_hi:[0,1,1]
	v_fmac_f32_e32 v23, v140, v137
	ds_read_b128 v[98:101], v8 offset:4096
	ds_read_b128 v[102:105], v8 offset:8192
	ds_read_b128 v[106:109], v8 offset:12288
	ds_read_b128 v[110:113], v8 offset:16384
	ds_read_b128 v[114:117], v8 offset:20480
	ds_read_b128 v[118:121], v8 offset:24576
	ds_read_b128 v[122:125], v8 offset:28672
	ds_read_b128 v[126:129], v8
	ds_read_b128 v[134:137], v8 offset:32768
	s_waitcnt lgkmcnt(0)
	v_mov_b32_e32 v143, v98
	v_mov_b32_e32 v144, v102
	v_mov_b32_e32 v145, v106
	v_mov_b32_e32 v142, v126
	v_mov_b32_e32 v146, v110
	v_mov_b32_e32 v147, v114
	v_mov_b32_e32 v148, v118
	v_mov_b32_e32 v149, v122
	v_mov_b32_e32 v98, v127
	v_mov_b32_e32 v106, v103
	v_mov_b32_e32 v114, v111
	v_mov_b32_e32 v122, v119
	v_mov_b32_e32 v102, v128
	v_mov_b32_e32 v103, v100
	v_mov_b32_e32 v110, v104
	v_mov_b32_e32 v111, v108
	v_mov_b32_e32 v118, v112
	v_mov_b32_e32 v119, v116
	v_mov_b32_e32 v126, v120
	v_mov_b32_e32 v127, v124
	v_mov_b32_e32 v100, v129
	v_mov_b32_e32 v108, v105
	v_mov_b32_e32 v116, v113
	v_mov_b32_e32 v124, v121
	v_add_u32_e32 v8, 16, v8
	s_waitcnt vmcnt(56)
	v_mov_b32_e32 v66, v158
	v_mov_b32_e32 v130, v159
	v_mov_b32_e32 v138, v160
	v_mov_b32_e32 v140, v161
	v_pk_fma_f32 v[4:5], v[66:67], v[142:143], v[4:5] op_sel_hi:[0,1,1]
	v_pk_fma_f32 v[68:69], v[66:67], v[144:145], v[68:69] op_sel_hi:[0,1,1]
	v_pk_fma_f32 v[70:71], v[66:67], v[146:147], v[70:71] op_sel_hi:[0,1,1]
	v_pk_fma_f32 v[72:73], v[66:67], v[148:149], v[72:73] op_sel_hi:[0,1,1]
	v_fmac_f32_e32 v23, v66, v134
	v_pk_fma_f32 v[4:5], v[130:131], v[98:99], v[4:5] op_sel_hi:[0,1,1]
	v_pk_fma_f32 v[68:69], v[130:131], v[106:107], v[68:69] op_sel_hi:[0,1,1]
	v_pk_fma_f32 v[70:71], v[130:131], v[114:115], v[70:71] op_sel_hi:[0,1,1]
	v_pk_fma_f32 v[72:73], v[130:131], v[122:123], v[72:73] op_sel_hi:[0,1,1]
	v_fmac_f32_e32 v23, v130, v135
	v_pk_fma_f32 v[4:5], v[138:139], v[102:103], v[4:5] op_sel_hi:[0,1,1]
	v_pk_fma_f32 v[68:69], v[138:139], v[110:111], v[68:69] op_sel_hi:[0,1,1]
	v_pk_fma_f32 v[70:71], v[138:139], v[118:119], v[70:71] op_sel_hi:[0,1,1]
	v_pk_fma_f32 v[72:73], v[138:139], v[126:127], v[72:73] op_sel_hi:[0,1,1]
	v_fmac_f32_e32 v23, v138, v136
	v_pk_fma_f32 v[4:5], v[140:141], v[100:101], v[4:5] op_sel_hi:[0,1,1]
	v_pk_fma_f32 v[68:69], v[140:141], v[108:109], v[68:69] op_sel_hi:[0,1,1]
	v_pk_fma_f32 v[70:71], v[140:141], v[116:117], v[70:71] op_sel_hi:[0,1,1]
	v_pk_fma_f32 v[72:73], v[140:141], v[124:125], v[72:73] op_sel_hi:[0,1,1]
	v_fmac_f32_e32 v23, v140, v137
	ds_read_b128 v[98:101], v8 offset:4096
	ds_read_b128 v[102:105], v8 offset:8192
	ds_read_b128 v[106:109], v8 offset:12288
	ds_read_b128 v[110:113], v8 offset:16384
	ds_read_b128 v[114:117], v8 offset:20480
	ds_read_b128 v[118:121], v8 offset:24576
	ds_read_b128 v[122:125], v8 offset:28672
	ds_read_b128 v[126:129], v8
	ds_read_b128 v[134:137], v8 offset:32768
	s_waitcnt lgkmcnt(0)
	v_mov_b32_e32 v143, v98
	v_mov_b32_e32 v144, v102
	v_mov_b32_e32 v145, v106
	v_mov_b32_e32 v142, v126
	v_mov_b32_e32 v146, v110
	v_mov_b32_e32 v147, v114
	v_mov_b32_e32 v148, v118
	v_mov_b32_e32 v149, v122
	v_mov_b32_e32 v98, v127
	v_mov_b32_e32 v106, v103
	v_mov_b32_e32 v114, v111
	v_mov_b32_e32 v122, v119
	v_mov_b32_e32 v102, v128
	v_mov_b32_e32 v103, v100
	v_mov_b32_e32 v110, v104
	v_mov_b32_e32 v111, v108
	v_mov_b32_e32 v118, v112
	v_mov_b32_e32 v119, v116
	v_mov_b32_e32 v126, v120
	v_mov_b32_e32 v127, v124
	v_mov_b32_e32 v100, v129
	v_mov_b32_e32 v108, v105
	v_mov_b32_e32 v116, v113
	v_mov_b32_e32 v124, v121
	v_add_u32_e32 v8, 16, v8
	s_waitcnt vmcnt(52)
	v_mov_b32_e32 v66, v162
	v_mov_b32_e32 v130, v163
	v_mov_b32_e32 v138, v164
	v_mov_b32_e32 v140, v165
	v_pk_fma_f32 v[4:5], v[66:67], v[142:143], v[4:5] op_sel_hi:[0,1,1]
	v_pk_fma_f32 v[68:69], v[66:67], v[144:145], v[68:69] op_sel_hi:[0,1,1]
	v_pk_fma_f32 v[70:71], v[66:67], v[146:147], v[70:71] op_sel_hi:[0,1,1]
	v_pk_fma_f32 v[72:73], v[66:67], v[148:149], v[72:73] op_sel_hi:[0,1,1]
	v_fmac_f32_e32 v23, v66, v134
	v_pk_fma_f32 v[4:5], v[130:131], v[98:99], v[4:5] op_sel_hi:[0,1,1]
	v_pk_fma_f32 v[68:69], v[130:131], v[106:107], v[68:69] op_sel_hi:[0,1,1]
	v_pk_fma_f32 v[70:71], v[130:131], v[114:115], v[70:71] op_sel_hi:[0,1,1]
	v_pk_fma_f32 v[72:73], v[130:131], v[122:123], v[72:73] op_sel_hi:[0,1,1]
	v_fmac_f32_e32 v23, v130, v135
	v_pk_fma_f32 v[4:5], v[138:139], v[102:103], v[4:5] op_sel_hi:[0,1,1]
	v_pk_fma_f32 v[68:69], v[138:139], v[110:111], v[68:69] op_sel_hi:[0,1,1]
	v_pk_fma_f32 v[70:71], v[138:139], v[118:119], v[70:71] op_sel_hi:[0,1,1]
	v_pk_fma_f32 v[72:73], v[138:139], v[126:127], v[72:73] op_sel_hi:[0,1,1]
	v_fmac_f32_e32 v23, v138, v136
	v_pk_fma_f32 v[4:5], v[140:141], v[100:101], v[4:5] op_sel_hi:[0,1,1]
	v_pk_fma_f32 v[68:69], v[140:141], v[108:109], v[68:69] op_sel_hi:[0,1,1]
	v_pk_fma_f32 v[70:71], v[140:141], v[116:117], v[70:71] op_sel_hi:[0,1,1]
	v_pk_fma_f32 v[72:73], v[140:141], v[124:125], v[72:73] op_sel_hi:[0,1,1]
	v_fmac_f32_e32 v23, v140, v137
	ds_read_b128 v[98:101], v8 offset:4096
	ds_read_b128 v[102:105], v8 offset:8192
	ds_read_b128 v[106:109], v8 offset:12288
	ds_read_b128 v[110:113], v8 offset:16384
	ds_read_b128 v[114:117], v8 offset:20480
	ds_read_b128 v[118:121], v8 offset:24576
	ds_read_b128 v[122:125], v8 offset:28672
	ds_read_b128 v[126:129], v8
	ds_read_b128 v[134:137], v8 offset:32768
	s_waitcnt lgkmcnt(0)
	v_mov_b32_e32 v143, v98
	v_mov_b32_e32 v144, v102
	v_mov_b32_e32 v145, v106
	v_mov_b32_e32 v142, v126
	v_mov_b32_e32 v146, v110
	v_mov_b32_e32 v147, v114
	v_mov_b32_e32 v148, v118
	v_mov_b32_e32 v149, v122
	v_mov_b32_e32 v98, v127
	v_mov_b32_e32 v106, v103
	v_mov_b32_e32 v114, v111
	v_mov_b32_e32 v122, v119
	v_mov_b32_e32 v102, v128
	v_mov_b32_e32 v103, v100
	v_mov_b32_e32 v110, v104
	v_mov_b32_e32 v111, v108
	v_mov_b32_e32 v118, v112
	v_mov_b32_e32 v119, v116
	v_mov_b32_e32 v126, v120
	v_mov_b32_e32 v127, v124
	v_mov_b32_e32 v100, v129
	v_mov_b32_e32 v108, v105
	v_mov_b32_e32 v116, v113
	v_mov_b32_e32 v124, v121
	v_add_u32_e32 v8, 16, v8
	s_waitcnt vmcnt(48)
	v_mov_b32_e32 v66, v166
	v_mov_b32_e32 v130, v167
	v_mov_b32_e32 v138, v168
	v_mov_b32_e32 v140, v169
	v_pk_fma_f32 v[4:5], v[66:67], v[142:143], v[4:5] op_sel_hi:[0,1,1]
	v_pk_fma_f32 v[68:69], v[66:67], v[144:145], v[68:69] op_sel_hi:[0,1,1]
	v_pk_fma_f32 v[70:71], v[66:67], v[146:147], v[70:71] op_sel_hi:[0,1,1]
	v_pk_fma_f32 v[72:73], v[66:67], v[148:149], v[72:73] op_sel_hi:[0,1,1]
	v_fmac_f32_e32 v23, v66, v134
	v_pk_fma_f32 v[4:5], v[130:131], v[98:99], v[4:5] op_sel_hi:[0,1,1]
	v_pk_fma_f32 v[68:69], v[130:131], v[106:107], v[68:69] op_sel_hi:[0,1,1]
	v_pk_fma_f32 v[70:71], v[130:131], v[114:115], v[70:71] op_sel_hi:[0,1,1]
	v_pk_fma_f32 v[72:73], v[130:131], v[122:123], v[72:73] op_sel_hi:[0,1,1]
	v_fmac_f32_e32 v23, v130, v135
	v_pk_fma_f32 v[4:5], v[138:139], v[102:103], v[4:5] op_sel_hi:[0,1,1]
	v_pk_fma_f32 v[68:69], v[138:139], v[110:111], v[68:69] op_sel_hi:[0,1,1]
	v_pk_fma_f32 v[70:71], v[138:139], v[118:119], v[70:71] op_sel_hi:[0,1,1]
	v_pk_fma_f32 v[72:73], v[138:139], v[126:127], v[72:73] op_sel_hi:[0,1,1]
	v_fmac_f32_e32 v23, v138, v136
	v_pk_fma_f32 v[4:5], v[140:141], v[100:101], v[4:5] op_sel_hi:[0,1,1]
	v_pk_fma_f32 v[68:69], v[140:141], v[108:109], v[68:69] op_sel_hi:[0,1,1]
	v_pk_fma_f32 v[70:71], v[140:141], v[116:117], v[70:71] op_sel_hi:[0,1,1]
	v_pk_fma_f32 v[72:73], v[140:141], v[124:125], v[72:73] op_sel_hi:[0,1,1]
	v_fmac_f32_e32 v23, v140, v137
	ds_read_b128 v[98:101], v8 offset:4096
	ds_read_b128 v[102:105], v8 offset:8192
	ds_read_b128 v[106:109], v8 offset:12288
	ds_read_b128 v[110:113], v8 offset:16384
	ds_read_b128 v[114:117], v8 offset:20480
	ds_read_b128 v[118:121], v8 offset:24576
	ds_read_b128 v[122:125], v8 offset:28672
	ds_read_b128 v[126:129], v8
	ds_read_b128 v[134:137], v8 offset:32768
	s_waitcnt lgkmcnt(0)
	v_mov_b32_e32 v143, v98
	v_mov_b32_e32 v144, v102
	v_mov_b32_e32 v145, v106
	v_mov_b32_e32 v142, v126
	v_mov_b32_e32 v146, v110
	v_mov_b32_e32 v147, v114
	v_mov_b32_e32 v148, v118
	v_mov_b32_e32 v149, v122
	v_mov_b32_e32 v98, v127
	v_mov_b32_e32 v106, v103
	v_mov_b32_e32 v114, v111
	v_mov_b32_e32 v122, v119
	v_mov_b32_e32 v102, v128
	v_mov_b32_e32 v103, v100
	v_mov_b32_e32 v110, v104
	v_mov_b32_e32 v111, v108
	v_mov_b32_e32 v118, v112
	v_mov_b32_e32 v119, v116
	v_mov_b32_e32 v126, v120
	v_mov_b32_e32 v127, v124
	v_mov_b32_e32 v100, v129
	v_mov_b32_e32 v108, v105
	v_mov_b32_e32 v116, v113
	v_mov_b32_e32 v124, v121
	v_add_u32_e32 v8, 16, v8
	s_waitcnt vmcnt(44)
	v_mov_b32_e32 v66, v170
	v_mov_b32_e32 v130, v171
	v_mov_b32_e32 v138, v172
	v_mov_b32_e32 v140, v173
	v_pk_fma_f32 v[4:5], v[66:67], v[142:143], v[4:5] op_sel_hi:[0,1,1]
	v_pk_fma_f32 v[68:69], v[66:67], v[144:145], v[68:69] op_sel_hi:[0,1,1]
	v_pk_fma_f32 v[70:71], v[66:67], v[146:147], v[70:71] op_sel_hi:[0,1,1]
	v_pk_fma_f32 v[72:73], v[66:67], v[148:149], v[72:73] op_sel_hi:[0,1,1]
	v_fmac_f32_e32 v23, v66, v134
	v_pk_fma_f32 v[4:5], v[130:131], v[98:99], v[4:5] op_sel_hi:[0,1,1]
	v_pk_fma_f32 v[68:69], v[130:131], v[106:107], v[68:69] op_sel_hi:[0,1,1]
	v_pk_fma_f32 v[70:71], v[130:131], v[114:115], v[70:71] op_sel_hi:[0,1,1]
	v_pk_fma_f32 v[72:73], v[130:131], v[122:123], v[72:73] op_sel_hi:[0,1,1]
	v_fmac_f32_e32 v23, v130, v135
	v_pk_fma_f32 v[4:5], v[138:139], v[102:103], v[4:5] op_sel_hi:[0,1,1]
	v_pk_fma_f32 v[68:69], v[138:139], v[110:111], v[68:69] op_sel_hi:[0,1,1]
	v_pk_fma_f32 v[70:71], v[138:139], v[118:119], v[70:71] op_sel_hi:[0,1,1]
	v_pk_fma_f32 v[72:73], v[138:139], v[126:127], v[72:73] op_sel_hi:[0,1,1]
	v_fmac_f32_e32 v23, v138, v136
	v_pk_fma_f32 v[4:5], v[140:141], v[100:101], v[4:5] op_sel_hi:[0,1,1]
	v_pk_fma_f32 v[68:69], v[140:141], v[108:109], v[68:69] op_sel_hi:[0,1,1]
	v_pk_fma_f32 v[70:71], v[140:141], v[116:117], v[70:71] op_sel_hi:[0,1,1]
	v_pk_fma_f32 v[72:73], v[140:141], v[124:125], v[72:73] op_sel_hi:[0,1,1]
	v_fmac_f32_e32 v23, v140, v137
	ds_read_b128 v[98:101], v8 offset:4096
	ds_read_b128 v[102:105], v8 offset:8192
	ds_read_b128 v[106:109], v8 offset:12288
	ds_read_b128 v[110:113], v8 offset:16384
	ds_read_b128 v[114:117], v8 offset:20480
	ds_read_b128 v[118:121], v8 offset:24576
	ds_read_b128 v[122:125], v8 offset:28672
	ds_read_b128 v[126:129], v8
	ds_read_b128 v[134:137], v8 offset:32768
	s_waitcnt lgkmcnt(0)
	v_mov_b32_e32 v143, v98
	v_mov_b32_e32 v144, v102
	v_mov_b32_e32 v145, v106
	v_mov_b32_e32 v142, v126
	v_mov_b32_e32 v146, v110
	v_mov_b32_e32 v147, v114
	v_mov_b32_e32 v148, v118
	v_mov_b32_e32 v149, v122
	v_mov_b32_e32 v98, v127
	v_mov_b32_e32 v106, v103
	v_mov_b32_e32 v114, v111
	v_mov_b32_e32 v122, v119
	v_mov_b32_e32 v102, v128
	v_mov_b32_e32 v103, v100
	v_mov_b32_e32 v110, v104
	v_mov_b32_e32 v111, v108
	v_mov_b32_e32 v118, v112
	v_mov_b32_e32 v119, v116
	v_mov_b32_e32 v126, v120
	v_mov_b32_e32 v127, v124
	v_mov_b32_e32 v100, v129
	v_mov_b32_e32 v108, v105
	v_mov_b32_e32 v116, v113
	v_mov_b32_e32 v124, v121
	v_add_u32_e32 v8, 16, v8
	s_waitcnt vmcnt(40)
	v_mov_b32_e32 v66, v174
	v_mov_b32_e32 v130, v175
	v_mov_b32_e32 v138, v176
	v_mov_b32_e32 v140, v177
	v_pk_fma_f32 v[4:5], v[66:67], v[142:143], v[4:5] op_sel_hi:[0,1,1]
	v_pk_fma_f32 v[68:69], v[66:67], v[144:145], v[68:69] op_sel_hi:[0,1,1]
	v_pk_fma_f32 v[70:71], v[66:67], v[146:147], v[70:71] op_sel_hi:[0,1,1]
	v_pk_fma_f32 v[72:73], v[66:67], v[148:149], v[72:73] op_sel_hi:[0,1,1]
	v_fmac_f32_e32 v23, v66, v134
	v_pk_fma_f32 v[4:5], v[130:131], v[98:99], v[4:5] op_sel_hi:[0,1,1]
	v_pk_fma_f32 v[68:69], v[130:131], v[106:107], v[68:69] op_sel_hi:[0,1,1]
	v_pk_fma_f32 v[70:71], v[130:131], v[114:115], v[70:71] op_sel_hi:[0,1,1]
	v_pk_fma_f32 v[72:73], v[130:131], v[122:123], v[72:73] op_sel_hi:[0,1,1]
	v_fmac_f32_e32 v23, v130, v135
	v_pk_fma_f32 v[4:5], v[138:139], v[102:103], v[4:5] op_sel_hi:[0,1,1]
	v_pk_fma_f32 v[68:69], v[138:139], v[110:111], v[68:69] op_sel_hi:[0,1,1]
	v_pk_fma_f32 v[70:71], v[138:139], v[118:119], v[70:71] op_sel_hi:[0,1,1]
	v_pk_fma_f32 v[72:73], v[138:139], v[126:127], v[72:73] op_sel_hi:[0,1,1]
	v_fmac_f32_e32 v23, v138, v136
	v_pk_fma_f32 v[4:5], v[140:141], v[100:101], v[4:5] op_sel_hi:[0,1,1]
	v_pk_fma_f32 v[68:69], v[140:141], v[108:109], v[68:69] op_sel_hi:[0,1,1]
	v_pk_fma_f32 v[70:71], v[140:141], v[116:117], v[70:71] op_sel_hi:[0,1,1]
	v_pk_fma_f32 v[72:73], v[140:141], v[124:125], v[72:73] op_sel_hi:[0,1,1]
	v_fmac_f32_e32 v23, v140, v137
	ds_read_b128 v[98:101], v8 offset:4096
	ds_read_b128 v[102:105], v8 offset:8192
	ds_read_b128 v[106:109], v8 offset:12288
	ds_read_b128 v[110:113], v8 offset:16384
	ds_read_b128 v[114:117], v8 offset:20480
	ds_read_b128 v[118:121], v8 offset:24576
	ds_read_b128 v[122:125], v8 offset:28672
	ds_read_b128 v[126:129], v8
	ds_read_b128 v[134:137], v8 offset:32768
	s_waitcnt lgkmcnt(0)
	v_mov_b32_e32 v143, v98
	v_mov_b32_e32 v144, v102
	v_mov_b32_e32 v145, v106
	v_mov_b32_e32 v142, v126
	v_mov_b32_e32 v146, v110
	v_mov_b32_e32 v147, v114
	v_mov_b32_e32 v148, v118
	v_mov_b32_e32 v149, v122
	v_mov_b32_e32 v98, v127
	v_mov_b32_e32 v106, v103
	v_mov_b32_e32 v114, v111
	v_mov_b32_e32 v122, v119
	v_mov_b32_e32 v102, v128
	v_mov_b32_e32 v103, v100
	v_mov_b32_e32 v110, v104
	v_mov_b32_e32 v111, v108
	v_mov_b32_e32 v118, v112
	v_mov_b32_e32 v119, v116
	v_mov_b32_e32 v126, v120
	v_mov_b32_e32 v127, v124
	v_mov_b32_e32 v100, v129
	v_mov_b32_e32 v108, v105
	v_mov_b32_e32 v116, v113
	v_mov_b32_e32 v124, v121
	v_add_u32_e32 v8, 16, v8
	s_waitcnt vmcnt(36)
	v_mov_b32_e32 v66, v178
	v_mov_b32_e32 v130, v179
	v_mov_b32_e32 v138, v180
	v_mov_b32_e32 v140, v181
	v_pk_fma_f32 v[4:5], v[66:67], v[142:143], v[4:5] op_sel_hi:[0,1,1]
	v_pk_fma_f32 v[68:69], v[66:67], v[144:145], v[68:69] op_sel_hi:[0,1,1]
	v_pk_fma_f32 v[70:71], v[66:67], v[146:147], v[70:71] op_sel_hi:[0,1,1]
	v_pk_fma_f32 v[72:73], v[66:67], v[148:149], v[72:73] op_sel_hi:[0,1,1]
	v_fmac_f32_e32 v23, v66, v134
	v_pk_fma_f32 v[4:5], v[130:131], v[98:99], v[4:5] op_sel_hi:[0,1,1]
	v_pk_fma_f32 v[68:69], v[130:131], v[106:107], v[68:69] op_sel_hi:[0,1,1]
	v_pk_fma_f32 v[70:71], v[130:131], v[114:115], v[70:71] op_sel_hi:[0,1,1]
	v_pk_fma_f32 v[72:73], v[130:131], v[122:123], v[72:73] op_sel_hi:[0,1,1]
	v_fmac_f32_e32 v23, v130, v135
	v_pk_fma_f32 v[4:5], v[138:139], v[102:103], v[4:5] op_sel_hi:[0,1,1]
	v_pk_fma_f32 v[68:69], v[138:139], v[110:111], v[68:69] op_sel_hi:[0,1,1]
	v_pk_fma_f32 v[70:71], v[138:139], v[118:119], v[70:71] op_sel_hi:[0,1,1]
	v_pk_fma_f32 v[72:73], v[138:139], v[126:127], v[72:73] op_sel_hi:[0,1,1]
	v_fmac_f32_e32 v23, v138, v136
	v_pk_fma_f32 v[4:5], v[140:141], v[100:101], v[4:5] op_sel_hi:[0,1,1]
	v_pk_fma_f32 v[68:69], v[140:141], v[108:109], v[68:69] op_sel_hi:[0,1,1]
	v_pk_fma_f32 v[70:71], v[140:141], v[116:117], v[70:71] op_sel_hi:[0,1,1]
	v_pk_fma_f32 v[72:73], v[140:141], v[124:125], v[72:73] op_sel_hi:[0,1,1]
	v_fmac_f32_e32 v23, v140, v137
	ds_read_b128 v[98:101], v8 offset:4096
	ds_read_b128 v[102:105], v8 offset:8192
	ds_read_b128 v[106:109], v8 offset:12288
	ds_read_b128 v[110:113], v8 offset:16384
	ds_read_b128 v[114:117], v8 offset:20480
	ds_read_b128 v[118:121], v8 offset:24576
	ds_read_b128 v[122:125], v8 offset:28672
	ds_read_b128 v[126:129], v8
	ds_read_b128 v[134:137], v8 offset:32768
	s_waitcnt lgkmcnt(0)
	v_mov_b32_e32 v143, v98
	v_mov_b32_e32 v144, v102
	v_mov_b32_e32 v145, v106
	v_mov_b32_e32 v142, v126
	v_mov_b32_e32 v146, v110
	v_mov_b32_e32 v147, v114
	v_mov_b32_e32 v148, v118
	v_mov_b32_e32 v149, v122
	v_mov_b32_e32 v98, v127
	v_mov_b32_e32 v106, v103
	v_mov_b32_e32 v114, v111
	v_mov_b32_e32 v122, v119
	v_mov_b32_e32 v102, v128
	v_mov_b32_e32 v103, v100
	v_mov_b32_e32 v110, v104
	v_mov_b32_e32 v111, v108
	v_mov_b32_e32 v118, v112
	v_mov_b32_e32 v119, v116
	v_mov_b32_e32 v126, v120
	v_mov_b32_e32 v127, v124
	v_mov_b32_e32 v100, v129
	v_mov_b32_e32 v108, v105
	v_mov_b32_e32 v116, v113
	v_mov_b32_e32 v124, v121
	v_add_u32_e32 v8, 16, v8
	s_waitcnt vmcnt(32)
	v_mov_b32_e32 v66, v182
	v_mov_b32_e32 v130, v183
	v_mov_b32_e32 v138, v184
	v_mov_b32_e32 v140, v185
	v_pk_fma_f32 v[4:5], v[66:67], v[142:143], v[4:5] op_sel_hi:[0,1,1]
	v_pk_fma_f32 v[68:69], v[66:67], v[144:145], v[68:69] op_sel_hi:[0,1,1]
	v_pk_fma_f32 v[70:71], v[66:67], v[146:147], v[70:71] op_sel_hi:[0,1,1]
	v_pk_fma_f32 v[72:73], v[66:67], v[148:149], v[72:73] op_sel_hi:[0,1,1]
	v_fmac_f32_e32 v23, v66, v134
	v_pk_fma_f32 v[4:5], v[130:131], v[98:99], v[4:5] op_sel_hi:[0,1,1]
	v_pk_fma_f32 v[68:69], v[130:131], v[106:107], v[68:69] op_sel_hi:[0,1,1]
	v_pk_fma_f32 v[70:71], v[130:131], v[114:115], v[70:71] op_sel_hi:[0,1,1]
	v_pk_fma_f32 v[72:73], v[130:131], v[122:123], v[72:73] op_sel_hi:[0,1,1]
	v_fmac_f32_e32 v23, v130, v135
	v_pk_fma_f32 v[4:5], v[138:139], v[102:103], v[4:5] op_sel_hi:[0,1,1]
	v_pk_fma_f32 v[68:69], v[138:139], v[110:111], v[68:69] op_sel_hi:[0,1,1]
	v_pk_fma_f32 v[70:71], v[138:139], v[118:119], v[70:71] op_sel_hi:[0,1,1]
	v_pk_fma_f32 v[72:73], v[138:139], v[126:127], v[72:73] op_sel_hi:[0,1,1]
	v_fmac_f32_e32 v23, v138, v136
	v_pk_fma_f32 v[4:5], v[140:141], v[100:101], v[4:5] op_sel_hi:[0,1,1]
	v_pk_fma_f32 v[68:69], v[140:141], v[108:109], v[68:69] op_sel_hi:[0,1,1]
	v_pk_fma_f32 v[70:71], v[140:141], v[116:117], v[70:71] op_sel_hi:[0,1,1]
	v_pk_fma_f32 v[72:73], v[140:141], v[124:125], v[72:73] op_sel_hi:[0,1,1]
	v_fmac_f32_e32 v23, v140, v137
	ds_read_b128 v[98:101], v8 offset:4096
	ds_read_b128 v[102:105], v8 offset:8192
	ds_read_b128 v[106:109], v8 offset:12288
	ds_read_b128 v[110:113], v8 offset:16384
	ds_read_b128 v[114:117], v8 offset:20480
	ds_read_b128 v[118:121], v8 offset:24576
	ds_read_b128 v[122:125], v8 offset:28672
	ds_read_b128 v[126:129], v8
	ds_read_b128 v[134:137], v8 offset:32768
	s_waitcnt lgkmcnt(0)
	v_mov_b32_e32 v143, v98
	v_mov_b32_e32 v144, v102
	v_mov_b32_e32 v145, v106
	v_mov_b32_e32 v142, v126
	v_mov_b32_e32 v146, v110
	v_mov_b32_e32 v147, v114
	v_mov_b32_e32 v148, v118
	v_mov_b32_e32 v149, v122
	v_mov_b32_e32 v98, v127
	v_mov_b32_e32 v106, v103
	v_mov_b32_e32 v114, v111
	v_mov_b32_e32 v122, v119
	v_mov_b32_e32 v102, v128
	v_mov_b32_e32 v103, v100
	v_mov_b32_e32 v110, v104
	v_mov_b32_e32 v111, v108
	v_mov_b32_e32 v118, v112
	v_mov_b32_e32 v119, v116
	v_mov_b32_e32 v126, v120
	v_mov_b32_e32 v127, v124
	v_mov_b32_e32 v100, v129
	v_mov_b32_e32 v108, v105
	v_mov_b32_e32 v116, v113
	v_mov_b32_e32 v124, v121
	v_add_u32_e32 v8, 16, v8
	s_waitcnt vmcnt(28)
	v_mov_b32_e32 v66, v186
	v_mov_b32_e32 v130, v187
	v_mov_b32_e32 v138, v188
	v_mov_b32_e32 v140, v189
	v_pk_fma_f32 v[4:5], v[66:67], v[142:143], v[4:5] op_sel_hi:[0,1,1]
	v_pk_fma_f32 v[68:69], v[66:67], v[144:145], v[68:69] op_sel_hi:[0,1,1]
	v_pk_fma_f32 v[70:71], v[66:67], v[146:147], v[70:71] op_sel_hi:[0,1,1]
	v_pk_fma_f32 v[72:73], v[66:67], v[148:149], v[72:73] op_sel_hi:[0,1,1]
	v_fmac_f32_e32 v23, v66, v134
	v_pk_fma_f32 v[4:5], v[130:131], v[98:99], v[4:5] op_sel_hi:[0,1,1]
	v_pk_fma_f32 v[68:69], v[130:131], v[106:107], v[68:69] op_sel_hi:[0,1,1]
	v_pk_fma_f32 v[70:71], v[130:131], v[114:115], v[70:71] op_sel_hi:[0,1,1]
	v_pk_fma_f32 v[72:73], v[130:131], v[122:123], v[72:73] op_sel_hi:[0,1,1]
	v_fmac_f32_e32 v23, v130, v135
	v_pk_fma_f32 v[4:5], v[138:139], v[102:103], v[4:5] op_sel_hi:[0,1,1]
	v_pk_fma_f32 v[68:69], v[138:139], v[110:111], v[68:69] op_sel_hi:[0,1,1]
	v_pk_fma_f32 v[70:71], v[138:139], v[118:119], v[70:71] op_sel_hi:[0,1,1]
	v_pk_fma_f32 v[72:73], v[138:139], v[126:127], v[72:73] op_sel_hi:[0,1,1]
	v_fmac_f32_e32 v23, v138, v136
	v_pk_fma_f32 v[4:5], v[140:141], v[100:101], v[4:5] op_sel_hi:[0,1,1]
	v_pk_fma_f32 v[68:69], v[140:141], v[108:109], v[68:69] op_sel_hi:[0,1,1]
	v_pk_fma_f32 v[70:71], v[140:141], v[116:117], v[70:71] op_sel_hi:[0,1,1]
	v_pk_fma_f32 v[72:73], v[140:141], v[124:125], v[72:73] op_sel_hi:[0,1,1]
	v_fmac_f32_e32 v23, v140, v137
	ds_read_b128 v[98:101], v8 offset:4096
	ds_read_b128 v[102:105], v8 offset:8192
	ds_read_b128 v[106:109], v8 offset:12288
	ds_read_b128 v[110:113], v8 offset:16384
	ds_read_b128 v[114:117], v8 offset:20480
	ds_read_b128 v[118:121], v8 offset:24576
	ds_read_b128 v[122:125], v8 offset:28672
	ds_read_b128 v[126:129], v8
	ds_read_b128 v[134:137], v8 offset:32768
	s_waitcnt lgkmcnt(0)
	v_mov_b32_e32 v143, v98
	v_mov_b32_e32 v144, v102
	v_mov_b32_e32 v145, v106
	v_mov_b32_e32 v142, v126
	v_mov_b32_e32 v146, v110
	v_mov_b32_e32 v147, v114
	v_mov_b32_e32 v148, v118
	v_mov_b32_e32 v149, v122
	v_mov_b32_e32 v98, v127
	v_mov_b32_e32 v106, v103
	v_mov_b32_e32 v114, v111
	v_mov_b32_e32 v122, v119
	v_mov_b32_e32 v102, v128
	v_mov_b32_e32 v103, v100
	v_mov_b32_e32 v110, v104
	v_mov_b32_e32 v111, v108
	v_mov_b32_e32 v118, v112
	v_mov_b32_e32 v119, v116
	v_mov_b32_e32 v126, v120
	v_mov_b32_e32 v127, v124
	v_mov_b32_e32 v100, v129
	v_mov_b32_e32 v108, v105
	v_mov_b32_e32 v116, v113
	v_mov_b32_e32 v124, v121
	v_add_u32_e32 v8, 16, v8
	s_waitcnt vmcnt(24)
	v_mov_b32_e32 v66, v190
	v_mov_b32_e32 v130, v191
	v_mov_b32_e32 v138, v192
	v_mov_b32_e32 v140, v193
	v_pk_fma_f32 v[4:5], v[66:67], v[142:143], v[4:5] op_sel_hi:[0,1,1]
	v_pk_fma_f32 v[68:69], v[66:67], v[144:145], v[68:69] op_sel_hi:[0,1,1]
	v_pk_fma_f32 v[70:71], v[66:67], v[146:147], v[70:71] op_sel_hi:[0,1,1]
	v_pk_fma_f32 v[72:73], v[66:67], v[148:149], v[72:73] op_sel_hi:[0,1,1]
	v_fmac_f32_e32 v23, v66, v134
	v_pk_fma_f32 v[4:5], v[130:131], v[98:99], v[4:5] op_sel_hi:[0,1,1]
	v_pk_fma_f32 v[68:69], v[130:131], v[106:107], v[68:69] op_sel_hi:[0,1,1]
	v_pk_fma_f32 v[70:71], v[130:131], v[114:115], v[70:71] op_sel_hi:[0,1,1]
	v_pk_fma_f32 v[72:73], v[130:131], v[122:123], v[72:73] op_sel_hi:[0,1,1]
	v_fmac_f32_e32 v23, v130, v135
	v_pk_fma_f32 v[4:5], v[138:139], v[102:103], v[4:5] op_sel_hi:[0,1,1]
	v_pk_fma_f32 v[68:69], v[138:139], v[110:111], v[68:69] op_sel_hi:[0,1,1]
	v_pk_fma_f32 v[70:71], v[138:139], v[118:119], v[70:71] op_sel_hi:[0,1,1]
	v_pk_fma_f32 v[72:73], v[138:139], v[126:127], v[72:73] op_sel_hi:[0,1,1]
	v_fmac_f32_e32 v23, v138, v136
	v_pk_fma_f32 v[4:5], v[140:141], v[100:101], v[4:5] op_sel_hi:[0,1,1]
	v_pk_fma_f32 v[68:69], v[140:141], v[108:109], v[68:69] op_sel_hi:[0,1,1]
	v_pk_fma_f32 v[70:71], v[140:141], v[116:117], v[70:71] op_sel_hi:[0,1,1]
	v_pk_fma_f32 v[72:73], v[140:141], v[124:125], v[72:73] op_sel_hi:[0,1,1]
	v_fmac_f32_e32 v23, v140, v137
	ds_read_b128 v[98:101], v8 offset:4096
	ds_read_b128 v[102:105], v8 offset:8192
	ds_read_b128 v[106:109], v8 offset:12288
	ds_read_b128 v[110:113], v8 offset:16384
	ds_read_b128 v[114:117], v8 offset:20480
	ds_read_b128 v[118:121], v8 offset:24576
	ds_read_b128 v[122:125], v8 offset:28672
	ds_read_b128 v[126:129], v8
	ds_read_b128 v[134:137], v8 offset:32768
	s_waitcnt lgkmcnt(0)
	v_mov_b32_e32 v143, v98
	v_mov_b32_e32 v144, v102
	v_mov_b32_e32 v145, v106
	v_mov_b32_e32 v142, v126
	v_mov_b32_e32 v146, v110
	v_mov_b32_e32 v147, v114
	v_mov_b32_e32 v148, v118
	v_mov_b32_e32 v149, v122
	v_mov_b32_e32 v98, v127
	v_mov_b32_e32 v106, v103
	v_mov_b32_e32 v114, v111
	v_mov_b32_e32 v122, v119
	v_mov_b32_e32 v102, v128
	v_mov_b32_e32 v103, v100
	v_mov_b32_e32 v110, v104
	v_mov_b32_e32 v111, v108
	v_mov_b32_e32 v118, v112
	v_mov_b32_e32 v119, v116
	v_mov_b32_e32 v126, v120
	v_mov_b32_e32 v127, v124
	v_mov_b32_e32 v100, v129
	v_mov_b32_e32 v108, v105
	v_mov_b32_e32 v116, v113
	v_mov_b32_e32 v124, v121
	v_add_u32_e32 v8, 16, v8
	s_waitcnt vmcnt(20)
	v_mov_b32_e32 v66, v194
	v_mov_b32_e32 v130, v195
	v_mov_b32_e32 v138, v196
	v_mov_b32_e32 v140, v197
	v_pk_fma_f32 v[4:5], v[66:67], v[142:143], v[4:5] op_sel_hi:[0,1,1]
	v_pk_fma_f32 v[68:69], v[66:67], v[144:145], v[68:69] op_sel_hi:[0,1,1]
	v_pk_fma_f32 v[70:71], v[66:67], v[146:147], v[70:71] op_sel_hi:[0,1,1]
	v_pk_fma_f32 v[72:73], v[66:67], v[148:149], v[72:73] op_sel_hi:[0,1,1]
	v_fmac_f32_e32 v23, v66, v134
	v_pk_fma_f32 v[4:5], v[130:131], v[98:99], v[4:5] op_sel_hi:[0,1,1]
	v_pk_fma_f32 v[68:69], v[130:131], v[106:107], v[68:69] op_sel_hi:[0,1,1]
	v_pk_fma_f32 v[70:71], v[130:131], v[114:115], v[70:71] op_sel_hi:[0,1,1]
	v_pk_fma_f32 v[72:73], v[130:131], v[122:123], v[72:73] op_sel_hi:[0,1,1]
	v_fmac_f32_e32 v23, v130, v135
	v_pk_fma_f32 v[4:5], v[138:139], v[102:103], v[4:5] op_sel_hi:[0,1,1]
	v_pk_fma_f32 v[68:69], v[138:139], v[110:111], v[68:69] op_sel_hi:[0,1,1]
	v_pk_fma_f32 v[70:71], v[138:139], v[118:119], v[70:71] op_sel_hi:[0,1,1]
	v_pk_fma_f32 v[72:73], v[138:139], v[126:127], v[72:73] op_sel_hi:[0,1,1]
	v_fmac_f32_e32 v23, v138, v136
	v_pk_fma_f32 v[4:5], v[140:141], v[100:101], v[4:5] op_sel_hi:[0,1,1]
	v_pk_fma_f32 v[68:69], v[140:141], v[108:109], v[68:69] op_sel_hi:[0,1,1]
	v_pk_fma_f32 v[70:71], v[140:141], v[116:117], v[70:71] op_sel_hi:[0,1,1]
	v_pk_fma_f32 v[72:73], v[140:141], v[124:125], v[72:73] op_sel_hi:[0,1,1]
	v_fmac_f32_e32 v23, v140, v137
	ds_read_b128 v[98:101], v8 offset:4096
	ds_read_b128 v[102:105], v8 offset:8192
	ds_read_b128 v[106:109], v8 offset:12288
	ds_read_b128 v[110:113], v8 offset:16384
	ds_read_b128 v[114:117], v8 offset:20480
	ds_read_b128 v[118:121], v8 offset:24576
	ds_read_b128 v[122:125], v8 offset:28672
	ds_read_b128 v[126:129], v8
	ds_read_b128 v[134:137], v8 offset:32768
	s_waitcnt lgkmcnt(0)
	v_mov_b32_e32 v143, v98
	v_mov_b32_e32 v144, v102
	v_mov_b32_e32 v145, v106
	v_mov_b32_e32 v142, v126
	v_mov_b32_e32 v146, v110
	v_mov_b32_e32 v147, v114
	v_mov_b32_e32 v148, v118
	v_mov_b32_e32 v149, v122
	v_mov_b32_e32 v98, v127
	v_mov_b32_e32 v106, v103
	v_mov_b32_e32 v114, v111
	v_mov_b32_e32 v122, v119
	v_mov_b32_e32 v102, v128
	v_mov_b32_e32 v103, v100
	v_mov_b32_e32 v110, v104
	v_mov_b32_e32 v111, v108
	v_mov_b32_e32 v118, v112
	v_mov_b32_e32 v119, v116
	v_mov_b32_e32 v126, v120
	v_mov_b32_e32 v127, v124
	v_mov_b32_e32 v100, v129
	v_mov_b32_e32 v108, v105
	v_mov_b32_e32 v116, v113
	v_mov_b32_e32 v124, v121
	v_add_u32_e32 v8, 16, v8
	s_waitcnt vmcnt(16)
	v_mov_b32_e32 v66, v198
	v_mov_b32_e32 v130, v199
	v_mov_b32_e32 v138, v200
	v_mov_b32_e32 v140, v201
	v_pk_fma_f32 v[4:5], v[66:67], v[142:143], v[4:5] op_sel_hi:[0,1,1]
	v_pk_fma_f32 v[68:69], v[66:67], v[144:145], v[68:69] op_sel_hi:[0,1,1]
	v_pk_fma_f32 v[70:71], v[66:67], v[146:147], v[70:71] op_sel_hi:[0,1,1]
	v_pk_fma_f32 v[72:73], v[66:67], v[148:149], v[72:73] op_sel_hi:[0,1,1]
	v_fmac_f32_e32 v23, v66, v134
	v_pk_fma_f32 v[4:5], v[130:131], v[98:99], v[4:5] op_sel_hi:[0,1,1]
	v_pk_fma_f32 v[68:69], v[130:131], v[106:107], v[68:69] op_sel_hi:[0,1,1]
	v_pk_fma_f32 v[70:71], v[130:131], v[114:115], v[70:71] op_sel_hi:[0,1,1]
	v_pk_fma_f32 v[72:73], v[130:131], v[122:123], v[72:73] op_sel_hi:[0,1,1]
	v_fmac_f32_e32 v23, v130, v135
	v_pk_fma_f32 v[4:5], v[138:139], v[102:103], v[4:5] op_sel_hi:[0,1,1]
	v_pk_fma_f32 v[68:69], v[138:139], v[110:111], v[68:69] op_sel_hi:[0,1,1]
	v_pk_fma_f32 v[70:71], v[138:139], v[118:119], v[70:71] op_sel_hi:[0,1,1]
	v_pk_fma_f32 v[72:73], v[138:139], v[126:127], v[72:73] op_sel_hi:[0,1,1]
	v_fmac_f32_e32 v23, v138, v136
	v_pk_fma_f32 v[4:5], v[140:141], v[100:101], v[4:5] op_sel_hi:[0,1,1]
	v_pk_fma_f32 v[68:69], v[140:141], v[108:109], v[68:69] op_sel_hi:[0,1,1]
	v_pk_fma_f32 v[70:71], v[140:141], v[116:117], v[70:71] op_sel_hi:[0,1,1]
	v_pk_fma_f32 v[72:73], v[140:141], v[124:125], v[72:73] op_sel_hi:[0,1,1]
	v_fmac_f32_e32 v23, v140, v137
	ds_read_b128 v[98:101], v8 offset:4096
	ds_read_b128 v[102:105], v8 offset:8192
	ds_read_b128 v[106:109], v8 offset:12288
	ds_read_b128 v[110:113], v8 offset:16384
	ds_read_b128 v[114:117], v8 offset:20480
	ds_read_b128 v[118:121], v8 offset:24576
	ds_read_b128 v[122:125], v8 offset:28672
	ds_read_b128 v[126:129], v8
	ds_read_b128 v[134:137], v8 offset:32768
	s_waitcnt lgkmcnt(0)
	v_mov_b32_e32 v143, v98
	v_mov_b32_e32 v144, v102
	v_mov_b32_e32 v145, v106
	v_mov_b32_e32 v142, v126
	v_mov_b32_e32 v146, v110
	v_mov_b32_e32 v147, v114
	v_mov_b32_e32 v148, v118
	v_mov_b32_e32 v149, v122
	v_mov_b32_e32 v98, v127
	v_mov_b32_e32 v106, v103
	v_mov_b32_e32 v114, v111
	v_mov_b32_e32 v122, v119
	v_mov_b32_e32 v102, v128
	v_mov_b32_e32 v103, v100
	v_mov_b32_e32 v110, v104
	v_mov_b32_e32 v111, v108
	v_mov_b32_e32 v118, v112
	v_mov_b32_e32 v119, v116
	v_mov_b32_e32 v126, v120
	v_mov_b32_e32 v127, v124
	v_mov_b32_e32 v100, v129
	v_mov_b32_e32 v108, v105
	v_mov_b32_e32 v116, v113
	v_mov_b32_e32 v124, v121
	v_add_u32_e32 v8, 16, v8
	s_waitcnt vmcnt(12)
	v_mov_b32_e32 v66, v202
	v_mov_b32_e32 v130, v203
	v_mov_b32_e32 v138, v204
	v_mov_b32_e32 v140, v205
	v_pk_fma_f32 v[4:5], v[66:67], v[142:143], v[4:5] op_sel_hi:[0,1,1]
	v_pk_fma_f32 v[68:69], v[66:67], v[144:145], v[68:69] op_sel_hi:[0,1,1]
	v_pk_fma_f32 v[70:71], v[66:67], v[146:147], v[70:71] op_sel_hi:[0,1,1]
	v_pk_fma_f32 v[72:73], v[66:67], v[148:149], v[72:73] op_sel_hi:[0,1,1]
	v_fmac_f32_e32 v23, v66, v134
	v_pk_fma_f32 v[4:5], v[130:131], v[98:99], v[4:5] op_sel_hi:[0,1,1]
	v_pk_fma_f32 v[68:69], v[130:131], v[106:107], v[68:69] op_sel_hi:[0,1,1]
	v_pk_fma_f32 v[70:71], v[130:131], v[114:115], v[70:71] op_sel_hi:[0,1,1]
	v_pk_fma_f32 v[72:73], v[130:131], v[122:123], v[72:73] op_sel_hi:[0,1,1]
	v_fmac_f32_e32 v23, v130, v135
	v_pk_fma_f32 v[4:5], v[138:139], v[102:103], v[4:5] op_sel_hi:[0,1,1]
	v_pk_fma_f32 v[68:69], v[138:139], v[110:111], v[68:69] op_sel_hi:[0,1,1]
	v_pk_fma_f32 v[70:71], v[138:139], v[118:119], v[70:71] op_sel_hi:[0,1,1]
	v_pk_fma_f32 v[72:73], v[138:139], v[126:127], v[72:73] op_sel_hi:[0,1,1]
	v_fmac_f32_e32 v23, v138, v136
	v_pk_fma_f32 v[4:5], v[140:141], v[100:101], v[4:5] op_sel_hi:[0,1,1]
	v_pk_fma_f32 v[68:69], v[140:141], v[108:109], v[68:69] op_sel_hi:[0,1,1]
	v_pk_fma_f32 v[70:71], v[140:141], v[116:117], v[70:71] op_sel_hi:[0,1,1]
	v_pk_fma_f32 v[72:73], v[140:141], v[124:125], v[72:73] op_sel_hi:[0,1,1]
	v_fmac_f32_e32 v23, v140, v137
	ds_read_b128 v[98:101], v8 offset:4096
	ds_read_b128 v[102:105], v8 offset:8192
	ds_read_b128 v[106:109], v8 offset:12288
	ds_read_b128 v[110:113], v8 offset:16384
	ds_read_b128 v[114:117], v8 offset:20480
	ds_read_b128 v[118:121], v8 offset:24576
	ds_read_b128 v[122:125], v8 offset:28672
	ds_read_b128 v[126:129], v8
	ds_read_b128 v[134:137], v8 offset:32768
	s_waitcnt lgkmcnt(0)
	v_mov_b32_e32 v143, v98
	v_mov_b32_e32 v144, v102
	v_mov_b32_e32 v145, v106
	v_mov_b32_e32 v142, v126
	v_mov_b32_e32 v146, v110
	v_mov_b32_e32 v147, v114
	v_mov_b32_e32 v148, v118
	v_mov_b32_e32 v149, v122
	v_mov_b32_e32 v98, v127
	v_mov_b32_e32 v106, v103
	v_mov_b32_e32 v114, v111
	v_mov_b32_e32 v122, v119
	v_mov_b32_e32 v102, v128
	v_mov_b32_e32 v103, v100
	v_mov_b32_e32 v110, v104
	v_mov_b32_e32 v111, v108
	v_mov_b32_e32 v118, v112
	v_mov_b32_e32 v119, v116
	v_mov_b32_e32 v126, v120
	v_mov_b32_e32 v127, v124
	v_mov_b32_e32 v100, v129
	v_mov_b32_e32 v108, v105
	v_mov_b32_e32 v116, v113
	v_mov_b32_e32 v124, v121
	v_add_u32_e32 v8, 16, v8
	s_waitcnt vmcnt(8)
	v_mov_b32_e32 v66, v206
	v_mov_b32_e32 v130, v207
	v_mov_b32_e32 v138, v208
	v_mov_b32_e32 v140, v209
	v_pk_fma_f32 v[4:5], v[66:67], v[142:143], v[4:5] op_sel_hi:[0,1,1]
	v_pk_fma_f32 v[68:69], v[66:67], v[144:145], v[68:69] op_sel_hi:[0,1,1]
	v_pk_fma_f32 v[70:71], v[66:67], v[146:147], v[70:71] op_sel_hi:[0,1,1]
	v_pk_fma_f32 v[72:73], v[66:67], v[148:149], v[72:73] op_sel_hi:[0,1,1]
	v_fmac_f32_e32 v23, v66, v134
	v_pk_fma_f32 v[4:5], v[130:131], v[98:99], v[4:5] op_sel_hi:[0,1,1]
	v_pk_fma_f32 v[68:69], v[130:131], v[106:107], v[68:69] op_sel_hi:[0,1,1]
	v_pk_fma_f32 v[70:71], v[130:131], v[114:115], v[70:71] op_sel_hi:[0,1,1]
	v_pk_fma_f32 v[72:73], v[130:131], v[122:123], v[72:73] op_sel_hi:[0,1,1]
	v_fmac_f32_e32 v23, v130, v135
	v_pk_fma_f32 v[4:5], v[138:139], v[102:103], v[4:5] op_sel_hi:[0,1,1]
	v_pk_fma_f32 v[68:69], v[138:139], v[110:111], v[68:69] op_sel_hi:[0,1,1]
	v_pk_fma_f32 v[70:71], v[138:139], v[118:119], v[70:71] op_sel_hi:[0,1,1]
	v_pk_fma_f32 v[72:73], v[138:139], v[126:127], v[72:73] op_sel_hi:[0,1,1]
	v_fmac_f32_e32 v23, v138, v136
	v_pk_fma_f32 v[4:5], v[140:141], v[100:101], v[4:5] op_sel_hi:[0,1,1]
	v_pk_fma_f32 v[68:69], v[140:141], v[108:109], v[68:69] op_sel_hi:[0,1,1]
	v_pk_fma_f32 v[70:71], v[140:141], v[116:117], v[70:71] op_sel_hi:[0,1,1]
	v_pk_fma_f32 v[72:73], v[140:141], v[124:125], v[72:73] op_sel_hi:[0,1,1]
	v_fmac_f32_e32 v23, v140, v137
	ds_read_b128 v[98:101], v8 offset:4096
	ds_read_b128 v[102:105], v8 offset:8192
	ds_read_b128 v[106:109], v8 offset:12288
	ds_read_b128 v[110:113], v8 offset:16384
	ds_read_b128 v[114:117], v8 offset:20480
	ds_read_b128 v[118:121], v8 offset:24576
	ds_read_b128 v[122:125], v8 offset:28672
	ds_read_b128 v[126:129], v8
	ds_read_b128 v[134:137], v8 offset:32768
	s_waitcnt lgkmcnt(0)
	v_mov_b32_e32 v143, v98
	v_mov_b32_e32 v144, v102
	v_mov_b32_e32 v145, v106
	v_mov_b32_e32 v142, v126
	v_mov_b32_e32 v146, v110
	v_mov_b32_e32 v147, v114
	v_mov_b32_e32 v148, v118
	v_mov_b32_e32 v149, v122
	v_mov_b32_e32 v98, v127
	v_mov_b32_e32 v106, v103
	v_mov_b32_e32 v114, v111
	v_mov_b32_e32 v122, v119
	v_mov_b32_e32 v102, v128
	v_mov_b32_e32 v103, v100
	v_mov_b32_e32 v110, v104
	v_mov_b32_e32 v111, v108
	v_mov_b32_e32 v118, v112
	v_mov_b32_e32 v119, v116
	v_mov_b32_e32 v126, v120
	v_mov_b32_e32 v127, v124
	v_mov_b32_e32 v100, v129
	v_mov_b32_e32 v108, v105
	v_mov_b32_e32 v116, v113
	v_mov_b32_e32 v124, v121
	v_add_u32_e32 v8, 16, v8
	s_waitcnt vmcnt(4)
	v_mov_b32_e32 v66, v150
	v_mov_b32_e32 v130, v151
	v_mov_b32_e32 v138, v152
	v_mov_b32_e32 v140, v153
	v_pk_fma_f32 v[4:5], v[66:67], v[142:143], v[4:5] op_sel_hi:[0,1,1]
	v_pk_fma_f32 v[68:69], v[66:67], v[144:145], v[68:69] op_sel_hi:[0,1,1]
	v_pk_fma_f32 v[70:71], v[66:67], v[146:147], v[70:71] op_sel_hi:[0,1,1]
	v_pk_fma_f32 v[72:73], v[66:67], v[148:149], v[72:73] op_sel_hi:[0,1,1]
	v_fmac_f32_e32 v23, v66, v134
	v_pk_fma_f32 v[4:5], v[130:131], v[98:99], v[4:5] op_sel_hi:[0,1,1]
	v_pk_fma_f32 v[68:69], v[130:131], v[106:107], v[68:69] op_sel_hi:[0,1,1]
	v_pk_fma_f32 v[70:71], v[130:131], v[114:115], v[70:71] op_sel_hi:[0,1,1]
	v_pk_fma_f32 v[72:73], v[130:131], v[122:123], v[72:73] op_sel_hi:[0,1,1]
	v_fmac_f32_e32 v23, v130, v135
	v_pk_fma_f32 v[4:5], v[138:139], v[102:103], v[4:5] op_sel_hi:[0,1,1]
	v_pk_fma_f32 v[68:69], v[138:139], v[110:111], v[68:69] op_sel_hi:[0,1,1]
	v_pk_fma_f32 v[70:71], v[138:139], v[118:119], v[70:71] op_sel_hi:[0,1,1]
	v_pk_fma_f32 v[72:73], v[138:139], v[126:127], v[72:73] op_sel_hi:[0,1,1]
	v_fmac_f32_e32 v23, v138, v136
	v_pk_fma_f32 v[4:5], v[140:141], v[100:101], v[4:5] op_sel_hi:[0,1,1]
	v_pk_fma_f32 v[68:69], v[140:141], v[108:109], v[68:69] op_sel_hi:[0,1,1]
	v_pk_fma_f32 v[70:71], v[140:141], v[116:117], v[70:71] op_sel_hi:[0,1,1]
	v_pk_fma_f32 v[72:73], v[140:141], v[124:125], v[72:73] op_sel_hi:[0,1,1]
	v_fmac_f32_e32 v23, v140, v137
	ds_read_b128 v[98:101], v8 offset:4096
	ds_read_b128 v[102:105], v8 offset:8192
	ds_read_b128 v[106:109], v8 offset:12288
	ds_read_b128 v[110:113], v8 offset:16384
	ds_read_b128 v[114:117], v8 offset:20480
	ds_read_b128 v[118:121], v8 offset:24576
	ds_read_b128 v[122:125], v8 offset:28672
	ds_read_b128 v[126:129], v8
	ds_read_b128 v[134:137], v8 offset:32768
	s_waitcnt lgkmcnt(0)
	v_mov_b32_e32 v143, v98
	v_mov_b32_e32 v144, v102
	v_mov_b32_e32 v145, v106
	v_mov_b32_e32 v142, v126
	v_mov_b32_e32 v146, v110
	v_mov_b32_e32 v147, v114
	v_mov_b32_e32 v148, v118
	v_mov_b32_e32 v149, v122
	v_mov_b32_e32 v98, v127
	v_mov_b32_e32 v106, v103
	v_mov_b32_e32 v114, v111
	v_mov_b32_e32 v122, v119
	v_mov_b32_e32 v102, v128
	v_mov_b32_e32 v103, v100
	v_mov_b32_e32 v110, v104
	v_mov_b32_e32 v111, v108
	v_mov_b32_e32 v118, v112
	v_mov_b32_e32 v119, v116
	v_mov_b32_e32 v126, v120
	v_mov_b32_e32 v127, v124
	v_mov_b32_e32 v100, v129
	v_mov_b32_e32 v108, v105
	v_mov_b32_e32 v116, v113
	v_mov_b32_e32 v124, v121
	v_add_u32_e32 v8, 16, v8
	s_waitcnt vmcnt(0)
	v_mov_b32_e32 v66, v154
	v_mov_b32_e32 v130, v155
	v_mov_b32_e32 v138, v156
	v_mov_b32_e32 v140, v157
	v_pk_fma_f32 v[4:5], v[66:67], v[142:143], v[4:5] op_sel_hi:[0,1,1]
	v_pk_fma_f32 v[68:69], v[66:67], v[144:145], v[68:69] op_sel_hi:[0,1,1]
	v_pk_fma_f32 v[70:71], v[66:67], v[146:147], v[70:71] op_sel_hi:[0,1,1]
	v_pk_fma_f32 v[72:73], v[66:67], v[148:149], v[72:73] op_sel_hi:[0,1,1]
	v_fmac_f32_e32 v23, v66, v134
	v_pk_fma_f32 v[4:5], v[130:131], v[98:99], v[4:5] op_sel_hi:[0,1,1]
	v_pk_fma_f32 v[68:69], v[130:131], v[106:107], v[68:69] op_sel_hi:[0,1,1]
	v_pk_fma_f32 v[70:71], v[130:131], v[114:115], v[70:71] op_sel_hi:[0,1,1]
	v_pk_fma_f32 v[72:73], v[130:131], v[122:123], v[72:73] op_sel_hi:[0,1,1]
	v_fmac_f32_e32 v23, v130, v135
	v_pk_fma_f32 v[4:5], v[138:139], v[102:103], v[4:5] op_sel_hi:[0,1,1]
	v_pk_fma_f32 v[68:69], v[138:139], v[110:111], v[68:69] op_sel_hi:[0,1,1]
	v_pk_fma_f32 v[70:71], v[138:139], v[118:119], v[70:71] op_sel_hi:[0,1,1]
	v_pk_fma_f32 v[72:73], v[138:139], v[126:127], v[72:73] op_sel_hi:[0,1,1]
	v_fmac_f32_e32 v23, v138, v136
	v_pk_fma_f32 v[4:5], v[140:141], v[100:101], v[4:5] op_sel_hi:[0,1,1]
	v_pk_fma_f32 v[68:69], v[140:141], v[108:109], v[68:69] op_sel_hi:[0,1,1]
	v_pk_fma_f32 v[70:71], v[140:141], v[116:117], v[70:71] op_sel_hi:[0,1,1]
	v_pk_fma_f32 v[72:73], v[140:141], v[124:125], v[72:73] op_sel_hi:[0,1,1]
	v_fmac_f32_e32 v23, v140, v137
	v_add_u32_e32 v2, 0x9000, v76
	ds_write2_b32 v2, v4, v5 offset1:32
	ds_write2_b32 v2, v68, v69 offset0:64 offset1:96
	ds_write2_b32 v2, v70, v71 offset0:128 offset1:160
	ds_write2_b32 v2, v72, v73 offset0:192 offset1:224
	ds_write_b32 v76, v23 offset:37888
	v_mov_b32_e32 v2, s63
	v_mov_b32_e32 v4, s75
	s_waitcnt lgkmcnt(0)
	s_barrier
	ds_read_b64 v[2:3], v2
	ds_read_b64 v[4:5], v4
	v_lshl_or_b32 v8, v1, 5, v74
	v_add_u32_e32 v8, 0xfffdd800, v8
	s_mov_b64 s[52:53], 0
	s_waitcnt lgkmcnt(1)
	v_lshl_add_u64 v[2:3], v[2:3], 0, s[36:37]
	s_waitcnt lgkmcnt(0)
	v_lshl_add_u64 v[4:5], v[8:9], 2, v[4:5]
	v_mov_b32_e32 v8, v84
	v_mov_b32_e32 v23, v83
	v_mov_b32_e32 v61, v82
	v_mov_b32_e32 v65, v89
